# v16: LDS-DMA rebalanced 4/4/4/4 per load segment (As[b][0] stage moved to next SP1, SP2 tails vmcnt(6)), mem-kv loop vmcnt(0) hoisted, on v15
# speedup vs baseline: 1.0073x; 1.0073x over previous
; #define PG8_STAGE(bufoff, gbase, voff) do { _Pragma("unroll") for (int _i = 0; _i < 2; ++_i) \
;         __builtin_amdgcn_global_load_lds((const unsigned*)((const char*)(gbase) + (voff)[_i]), (PG8_LAS unsigned*)(lds + (bufoff) + ldsw + _i * 8192), 16, 0, 0); } while (0)
; #define PG8_LDA(dst, b, h) do { _Pragma("unroll") for (int m = 0; m < 4; ++m) _Pragma("unroll") for (int k = 0; k < 2; ++k) dst[m][k] = *(const PG8_LAS bf16x8*)(lds + PG8_SA(b, h) + aoff + m * 2048 + k * 1024); } while (0)
; #define PG8_LDB(dst, b, h) do { _Pragma("unroll") for (int n = 0; n < 2; ++n) _Pragma("unroll") for (int k = 0; k < 2; ++k) dst[n][k] = *(const PG8_LAS bf16x8*)(lds + PG8_SB(b, h) + boff + n * 2048 + k * 1024); } while (0)
; #define PG8_MMA(ai, bj, At, Bt) do { __builtin_amdgcn_s_setprio(1); _Pragma("unroll") for (int m = 0; m < 4; ++m) _Pragma("unroll") for (int n = 0; n < 2; ++n) _Pragma("unroll") for (int k = 0; k < 2; ++k) \
;         acc[ai][bj][m][n] = __builtin_amdgcn_mfma_f32_16x16x32_bf16(Bt[n][k], At[m][k], acc[ai][bj][m][n], 0, 0, 0); __builtin_amdgcn_s_setprio(0); } while (0)
; #define PG8_WAIT_V(n) asm volatile("s_waitcnt vmcnt(" #n ")" ::: "memory")
; #define PG8_WAIT_L(n) asm volatile("s_waitcnt lgkmcnt(" #n ")" ::: "memory")
; #define PG8_BAR __builtin_amdgcn_s_barrier()
; #define PG8_SCHED __builtin_amdgcn_sched_barrier(0)
; template <class Epi, class Sched, bool ALIGN_EPI = false, bool SP2 = false>
; __device__ __forceinline__ void gemm_phase(PG8_LAS unsigned char* lds, const Gemm g, const Sched& S, const Epi& E) {
;     ...
;             if constexpr (SP2) {
;             PG8_LDB(B0, 0, 0); PG8_LDB(B1, 0, 1); PG8_SCHED; PG8_LDA(At, 0, 0); PG8_STAGE(PG8_SA(1, 1), a1 + hstep, voffA);
;             PG8_WAIT_V(8); PG8_WAIT_L(0); PG8_BAR; PG8_MMA(0, 0, At, B0); PG8_MMA(0, 1, At, B1); PG8_BAR; PG8_SCHED;
;             PG8_LDA(At, 0, 1); PG8_STAGE(PG8_SB(0, 0), b2, voffB); PG8_STAGE(PG8_SB(0, 1), b2 + hstep, voffB); PG8_STAGE(PG8_SA(0, 0), a2, voffA);
;             PG8_WAIT_V(8); PG8_WAIT_L(0); PG8_BAR; PG8_MMA(1, 0, At, B0); PG8_MMA(1, 1, At, B1); PG8_BAR; PG8_SCHED;
.LBB0_816:
	ds_read_b128 v[142:145], v198
	ds_read_b128 v[146:149], v198 offset:1024
	ds_read_b128 v[154:157], v198 offset:2048
	ds_read_b128 v[158:161], v198 offset:3072
	ds_read_b128 v[162:165], v198 offset:16384
	ds_read_b128 v[166:169], v198 offset:17408
	ds_read_b128 v[170:173], v198 offset:18432
	ds_read_b128 v[174:177], v198 offset:19456
	ds_read_b128 v[178:181], v153
	ds_read_b128 v[182:185], v153 offset:1024
	ds_read_b128 v[186:189], v153 offset:2048
	ds_read_b128 v[190:193], v153 offset:3072
	ds_read_b128 v[194:197], v153 offset:4096
	ds_read_b128 v[214:217], v153 offset:5120
	ds_read_b128 v[218:221], v153 offset:6144
	ds_read_b128 v[234:237], v153 offset:7168
	s_setprio 0
	s_add_u32 s0, s50, 0xfff00080
	s_addc_u32 s1, s51, -1
	s_add_i32 s61, 0, 0x10000
	s_cmp_eq_u32 s60, 60
	s_cselect_b32 s27, s47, s1
	s_cselect_b32 s26, s46, s0
	s_cselect_b32 s1, s49, s45
	s_cselect_b32 s0, s48, s43
	s_add_i32 s64, 0, 0x14000
	s_add_u32 s100, s50, 0xfff00000
	s_addc_u32 s101, s51, -1
	s_mov_b32 m0, s54
	s_nop 0
	global_load_lds_dwordx4 v136, s[100:101]
	s_mov_b32 m0, s55
	s_nop 0
	global_load_lds_dwordx4 v134, s[100:101]
	s_add_i32 m0, s9, 0xc000
	s_nop 0
	global_load_lds_dwordx4 v138, s[50:51]
	s_add_i32 m0, s9, 0xe000
	s_nop 0
	global_load_lds_dwordx4 v140, s[50:51]
	s_nop 0
	s_setprio 1
	s_waitcnt vmcnt(8)
	s_waitcnt lgkmcnt(0)
	s_barrier
	v_mfma_f32_16x16x32_bf16 v[128:131], v[142:145], v[178:181], v[128:131]
	v_mfma_f32_16x16x32_bf16 v[128:131], v[146:149], v[182:185], v[128:131]
	v_mfma_f32_16x16x32_bf16 v[124:127], v[154:157], v[178:181], v[124:127]
	v_mfma_f32_16x16x32_bf16 v[124:127], v[158:161], v[182:185], v[124:127]
	v_mfma_f32_16x16x32_bf16 v[108:111], v[154:157], v[186:189], v[108:111]
	v_mfma_f32_16x16x32_bf16 v[108:111], v[158:161], v[190:193], v[108:111]
	v_mfma_f32_16x16x32_bf16 v[116:119], v[142:145], v[186:189], v[116:119]
	v_mfma_f32_16x16x32_bf16 v[116:119], v[146:149], v[190:193], v[116:119]
	v_mfma_f32_16x16x32_bf16 v[100:103], v[142:145], v[194:197], v[100:103]
	v_mfma_f32_16x16x32_bf16 v[100:103], v[146:149], v[214:217], v[100:103]
	v_mfma_f32_16x16x32_bf16 v[92:95], v[154:157], v[194:197], v[92:95]
	v_mfma_f32_16x16x32_bf16 v[92:95], v[158:161], v[214:217], v[92:95]
	v_mfma_f32_16x16x32_bf16 v[76:79], v[154:157], v[218:221], v[76:79]
	v_mfma_f32_16x16x32_bf16 v[76:79], v[158:161], v[234:237], v[76:79]
	v_mfma_f32_16x16x32_bf16 v[84:87], v[142:145], v[218:221], v[84:87]
	v_mfma_f32_16x16x32_bf16 v[84:87], v[146:149], v[234:237], v[84:87]
	s_setprio 0
	s_setprio 1
	v_mfma_f32_16x16x32_bf16 v[120:123], v[162:165], v[178:181], v[120:123]
	v_mfma_f32_16x16x32_bf16 v[120:123], v[166:169], v[182:185], v[120:123]
	v_mfma_f32_16x16x32_bf16 v[112:115], v[170:173], v[178:181], v[112:115]
	v_mfma_f32_16x16x32_bf16 v[112:115], v[174:177], v[182:185], v[112:115]
	v_mfma_f32_16x16x32_bf16 v[96:99], v[170:173], v[186:189], v[96:99]
	v_mfma_f32_16x16x32_bf16 v[96:99], v[174:177], v[190:193], v[96:99]
	v_mfma_f32_16x16x32_bf16 v[104:107], v[162:165], v[186:189], v[104:107]
	v_mfma_f32_16x16x32_bf16 v[104:107], v[166:169], v[190:193], v[104:107]
	v_mfma_f32_16x16x32_bf16 v[88:91], v[162:165], v[194:197], v[88:91]
	v_mfma_f32_16x16x32_bf16 v[88:91], v[166:169], v[214:217], v[88:91]
	v_mfma_f32_16x16x32_bf16 v[80:83], v[170:173], v[194:197], v[80:83]
	v_mfma_f32_16x16x32_bf16 v[80:83], v[174:177], v[214:217], v[80:83]
	v_mfma_f32_16x16x32_bf16 v[68:71], v[170:173], v[218:221], v[68:71]
	v_mfma_f32_16x16x32_bf16 v[68:71], v[174:177], v[234:237], v[68:71]
	v_mfma_f32_16x16x32_bf16 v[72:75], v[162:165], v[218:221], v[72:75]
	v_mfma_f32_16x16x32_bf16 v[72:75], v[166:169], v[234:237], v[72:75]
	s_barrier
	ds_read_b128 v[178:181], v153 offset:16384
	ds_read_b128 v[182:185], v153 offset:17408
	ds_read_b128 v[186:189], v153 offset:18432
	ds_read_b128 v[190:193], v153 offset:19456
	ds_read_b128 v[194:197], v153 offset:20480
	ds_read_b128 v[214:217], v153 offset:21504
	ds_read_b128 v[218:221], v153 offset:22528
	ds_read_b128 v[234:237], v153 offset:23552
	s_setprio 0
	s_add_i32 s61, s61, s8
	s_mov_b32 m0, s61
	s_nop 0
	global_load_lds_dwordx4 v2, s[0:1]
	s_add_i32 m0, s61, 0x2000
	s_add_u32 s62, s0, 0x100000
	s_addc_u32 s63, s1, 0
	s_add_i32 s61, s64, s8
	global_load_lds_dwordx4 v132, s[0:1]
	s_mov_b32 m0, s61
	s_nop 0
	global_load_lds_dwordx4 v2, s[62:63]
	s_add_i32 m0, s61, 0x2000
	s_nop 0
	global_load_lds_dwordx4 v132, s[62:63]
	s_setprio 1
	s_waitcnt vmcnt(6)
	s_waitcnt lgkmcnt(0)
	s_barrier
	v_mfma_f32_16x16x32_bf16 v[64:67], v[142:145], v[178:181], v[64:67]
	v_mfma_f32_16x16x32_bf16 v[64:67], v[146:149], v[182:185], v[64:67]
	v_mfma_f32_16x16x32_bf16 v[60:63], v[154:157], v[178:181], v[60:63]
	v_mfma_f32_16x16x32_bf16 v[60:63], v[158:161], v[182:185], v[60:63]
	v_mfma_f32_16x16x32_bf16 v[44:47], v[154:157], v[186:189], v[44:47]
	v_mfma_f32_16x16x32_bf16 v[44:47], v[158:161], v[190:193], v[44:47]
	v_mfma_f32_16x16x32_bf16 v[52:55], v[142:145], v[186:189], v[52:55]
	v_mfma_f32_16x16x32_bf16 v[52:55], v[146:149], v[190:193], v[52:55]
	v_mfma_f32_16x16x32_bf16 v[36:39], v[142:145], v[194:197], v[36:39]
	v_mfma_f32_16x16x32_bf16 v[36:39], v[146:149], v[214:217], v[36:39]
	v_mfma_f32_16x16x32_bf16 v[28:31], v[154:157], v[194:197], v[28:31]
	v_mfma_f32_16x16x32_bf16 v[28:31], v[158:161], v[214:217], v[28:31]
	v_mfma_f32_16x16x32_bf16 v[12:15], v[154:157], v[218:221], v[12:15]
	v_mfma_f32_16x16x32_bf16 v[12:15], v[158:161], v[234:237], v[12:15]
	v_mfma_f32_16x16x32_bf16 v[16:19], v[142:145], v[218:221], v[16:19]
	v_mfma_f32_16x16x32_bf16 v[16:19], v[146:149], v[234:237], v[16:19]
	s_setprio 0
	s_setprio 1
	v_mfma_f32_16x16x32_bf16 v[56:59], v[162:165], v[178:181], v[56:59]
	v_mfma_f32_16x16x32_bf16 v[56:59], v[166:169], v[182:185], v[56:59]
	v_mfma_f32_16x16x32_bf16 v[48:51], v[170:173], v[178:181], v[48:51]
	v_mfma_f32_16x16x32_bf16 v[48:51], v[174:177], v[182:185], v[48:51]
	v_mfma_f32_16x16x32_bf16 v[32:35], v[170:173], v[186:189], v[32:35]
	v_mfma_f32_16x16x32_bf16 v[32:35], v[174:177], v[190:193], v[32:35]
	v_mfma_f32_16x16x32_bf16 v[40:43], v[162:165], v[186:189], v[40:43]
	v_mfma_f32_16x16x32_bf16 v[40:43], v[166:169], v[190:193], v[40:43]
	v_mfma_f32_16x16x32_bf16 v[24:27], v[162:165], v[194:197], v[24:27]
	v_mfma_f32_16x16x32_bf16 v[24:27], v[166:169], v[214:217], v[24:27]
	v_mfma_f32_16x16x32_bf16 v[20:23], v[170:173], v[194:197], v[20:23]
	v_mfma_f32_16x16x32_bf16 v[20:23], v[174:177], v[214:217], v[20:23]
	v_mfma_f32_16x16x32_bf16 v[4:7], v[170:173], v[218:221], v[4:7]
	v_mfma_f32_16x16x32_bf16 v[4:7], v[174:177], v[234:237], v[4:7]
	v_mfma_f32_16x16x32_bf16 v[8:11], v[162:165], v[218:221], v[8:11]
	v_mfma_f32_16x16x32_bf16 v[8:11], v[166:169], v[234:237], v[8:11]
	s_barrier
; #define PG8_STAGE(bufoff, gbase, voff) do { _Pragma("unroll") for (int _i = 0; _i < 2; ++_i) \
;         __builtin_amdgcn_global_load_lds((const unsigned*)((const char*)(gbase) + (voff)[_i]), (PG8_LAS unsigned*)(lds + (bufoff) + ldsw + _i * 8192), 16, 0, 0); } while (0)
; #define PG8_LDA(dst, b, h) do { _Pragma("unroll") for (int m = 0; m < 4; ++m) _Pragma("unroll") for (int k = 0; k < 2; ++k) dst[m][k] = *(const PG8_LAS bf16x8*)(lds + PG8_SA(b, h) + aoff + m * 2048 + k * 1024); } while (0)
; #define PG8_LDB(dst, b, h) do { _Pragma("unroll") for (int n = 0; n < 2; ++n) _Pragma("unroll") for (int k = 0; k < 2; ++k) dst[n][k] = *(const PG8_LAS bf16x8*)(lds + PG8_SB(b, h) + boff + n * 2048 + k * 1024); } while (0)
; #define PG8_MMA(ai, bj, At, Bt) do { __builtin_amdgcn_s_setprio(1); _Pragma("unroll") for (int m = 0; m < 4; ++m) _Pragma("unroll") for (int n = 0; n < 2; ++n) _Pragma("unroll") for (int k = 0; k < 2; ++k) \
;         acc[ai][bj][m][n] = __builtin_amdgcn_mfma_f32_16x16x32_bf16(Bt[n][k], At[m][k], acc[ai][bj][m][n], 0, 0, 0); __builtin_amdgcn_s_setprio(0); } while (0)
; #define PG8_WAIT_V(n) asm volatile("s_waitcnt vmcnt(" #n ")" ::: "memory")
; #define PG8_WAIT_L(n) asm volatile("s_waitcnt lgkmcnt(" #n ")" ::: "memory")
; #define PG8_BAR __builtin_amdgcn_s_barrier()
; #define PG8_SCHED __builtin_amdgcn_sched_barrier(0)
; template <class Epi, class Sched, bool ALIGN_EPI = false, bool SP2 = false>
; __device__ __forceinline__ void gemm_phase(PG8_LAS unsigned char* lds, const Gemm g, const Sched& S, const Epi& E) {
;     ...
;             PG8_LDB(B0, 1, 0); PG8_LDB(B1, 1, 1); PG8_SCHED; PG8_LDA(At, 1, 0); PG8_STAGE(PG8_SA(0, 1), a2 + hstep, voffA);
;             PG8_WAIT_V(8); PG8_WAIT_L(0); PG8_BAR; PG8_MMA(0, 0, At, B0); PG8_MMA(0, 1, At, B1); PG8_BAR; PG8_SCHED;
;             PG8_LDA(At, 1, 1); PG8_STAGE(PG8_SB(1, 0), b3, voffB); PG8_STAGE(PG8_SB(1, 1), b3 + hstep, voffB); PG8_STAGE(PG8_SA(1, 0), a3, voffA);
;             PG8_WAIT_V(8); PG8_WAIT_L(0); PG8_BAR; PG8_MMA(1, 0, At, B0); PG8_MMA(1, 1, At, B1); PG8_BAR; PG8_SCHED;
	ds_read_b128 v[142:145], v198 offset:32768
	ds_read_b128 v[146:149], v198 offset:33792
	ds_read_b128 v[154:157], v198 offset:34816
	ds_read_b128 v[158:161], v198 offset:35840
	ds_read_b128 v[162:165], v198 offset:49152
	ds_read_b128 v[166:169], v198 offset:50176
	ds_read_b128 v[170:173], v198 offset:51200
	ds_read_b128 v[174:177], v198 offset:52224
	ds_read_b128 v[178:181], v153 offset:32768
	ds_read_b128 v[182:185], v153 offset:33792
	ds_read_b128 v[186:189], v153 offset:34816
	ds_read_b128 v[190:193], v153 offset:35840
	ds_read_b128 v[194:197], v153 offset:36864
	ds_read_b128 v[214:217], v153 offset:37888
	ds_read_b128 v[218:221], v153 offset:38912
	ds_read_b128 v[234:237], v153 offset:39936
	s_setprio 0
	s_add_i32 s61, 0, 0x18000
	s_add_i32 s62, 0, 0x1c000
	s_mov_b32 m0, s9
	s_nop 0
	global_load_lds_dwordx4 v136, s[26:27]
	s_mov_b32 m0, s10
	s_nop 0
	global_load_lds_dwordx4 v134, s[26:27]
	s_add_u32 s26, s26, 0x100000
	s_addc_u32 s27, s27, 0
	s_mov_b32 m0, s11
	s_nop 0
	global_load_lds_dwordx4 v136, s[26:27]
	s_mov_b32 m0, s52
	s_nop 0
	global_load_lds_dwordx4 v134, s[26:27]
	s_nop 0
	s_setprio 1
	s_waitcnt vmcnt(8)
	s_waitcnt lgkmcnt(0)
	s_barrier
	v_mfma_f32_16x16x32_bf16 v[128:131], v[142:145], v[178:181], v[128:131]
	v_mfma_f32_16x16x32_bf16 v[128:131], v[146:149], v[182:185], v[128:131]
	v_mfma_f32_16x16x32_bf16 v[124:127], v[154:157], v[178:181], v[124:127]
	v_mfma_f32_16x16x32_bf16 v[124:127], v[158:161], v[182:185], v[124:127]
	v_mfma_f32_16x16x32_bf16 v[108:111], v[154:157], v[186:189], v[108:111]
	v_mfma_f32_16x16x32_bf16 v[108:111], v[158:161], v[190:193], v[108:111]
	v_mfma_f32_16x16x32_bf16 v[116:119], v[142:145], v[186:189], v[116:119]
	v_mfma_f32_16x16x32_bf16 v[116:119], v[146:149], v[190:193], v[116:119]
	v_mfma_f32_16x16x32_bf16 v[100:103], v[142:145], v[194:197], v[100:103]
	v_mfma_f32_16x16x32_bf16 v[100:103], v[146:149], v[214:217], v[100:103]
	v_mfma_f32_16x16x32_bf16 v[92:95], v[154:157], v[194:197], v[92:95]
	v_mfma_f32_16x16x32_bf16 v[92:95], v[158:161], v[214:217], v[92:95]
	v_mfma_f32_16x16x32_bf16 v[76:79], v[154:157], v[218:221], v[76:79]
	v_mfma_f32_16x16x32_bf16 v[76:79], v[158:161], v[234:237], v[76:79]
	v_mfma_f32_16x16x32_bf16 v[84:87], v[142:145], v[218:221], v[84:87]
	v_mfma_f32_16x16x32_bf16 v[84:87], v[146:149], v[234:237], v[84:87]
	s_setprio 0
	s_setprio 1
	v_mfma_f32_16x16x32_bf16 v[120:123], v[162:165], v[178:181], v[120:123]
	v_mfma_f32_16x16x32_bf16 v[120:123], v[166:169], v[182:185], v[120:123]
	v_mfma_f32_16x16x32_bf16 v[112:115], v[170:173], v[178:181], v[112:115]
	v_mfma_f32_16x16x32_bf16 v[112:115], v[174:177], v[182:185], v[112:115]
	v_mfma_f32_16x16x32_bf16 v[96:99], v[170:173], v[186:189], v[96:99]
	v_mfma_f32_16x16x32_bf16 v[96:99], v[174:177], v[190:193], v[96:99]
	v_mfma_f32_16x16x32_bf16 v[104:107], v[162:165], v[186:189], v[104:107]
	v_mfma_f32_16x16x32_bf16 v[104:107], v[166:169], v[190:193], v[104:107]
	v_mfma_f32_16x16x32_bf16 v[88:91], v[162:165], v[194:197], v[88:91]
	v_mfma_f32_16x16x32_bf16 v[88:91], v[166:169], v[214:217], v[88:91]
	v_mfma_f32_16x16x32_bf16 v[80:83], v[170:173], v[194:197], v[80:83]
	v_mfma_f32_16x16x32_bf16 v[80:83], v[174:177], v[214:217], v[80:83]
	v_mfma_f32_16x16x32_bf16 v[68:71], v[170:173], v[218:221], v[68:71]
	v_mfma_f32_16x16x32_bf16 v[68:71], v[174:177], v[234:237], v[68:71]
	v_mfma_f32_16x16x32_bf16 v[72:75], v[162:165], v[218:221], v[72:75]
	v_mfma_f32_16x16x32_bf16 v[72:75], v[166:169], v[234:237], v[72:75]
	s_barrier
	ds_read_b128 v[178:181], v153 offset:49152
	ds_read_b128 v[182:185], v153 offset:50176
	ds_read_b128 v[186:189], v153 offset:51200
	ds_read_b128 v[190:193], v153 offset:52224
	ds_read_b128 v[194:197], v153 offset:53248
	ds_read_b128 v[214:217], v153 offset:54272
	ds_read_b128 v[218:221], v153 offset:55296
	ds_read_b128 v[234:237], v153 offset:56320
	s_setprio 0
	s_add_i32 s26, s61, s8
	s_mov_b32 m0, s26
	s_add_u32 s0, s0, 0x80
	s_addc_u32 s1, s1, 0
	global_load_lds_dwordx4 v2, s[0:1]
	s_add_i32 m0, s26, 0x2000
	s_add_i32 s26, s62, s8
	global_load_lds_dwordx4 v132, s[0:1]
	s_add_u32 s0, s0, 0x100000
	s_addc_u32 s1, s1, 0
	s_mov_b32 m0, s26
	s_nop 0
	global_load_lds_dwordx4 v2, s[0:1]
	s_add_i32 m0, s26, 0x2000
	s_nop 0
	global_load_lds_dwordx4 v132, s[0:1]
	s_setprio 1
	s_waitcnt vmcnt(6)
	s_waitcnt lgkmcnt(0)
	s_barrier
	v_mfma_f32_16x16x32_bf16 v[64:67], v[142:145], v[178:181], v[64:67]
	v_mfma_f32_16x16x32_bf16 v[64:67], v[146:149], v[182:185], v[64:67]
	v_mfma_f32_16x16x32_bf16 v[60:63], v[154:157], v[178:181], v[60:63]
	v_mfma_f32_16x16x32_bf16 v[60:63], v[158:161], v[182:185], v[60:63]
	v_mfma_f32_16x16x32_bf16 v[44:47], v[154:157], v[186:189], v[44:47]
	v_mfma_f32_16x16x32_bf16 v[44:47], v[158:161], v[190:193], v[44:47]
	v_mfma_f32_16x16x32_bf16 v[52:55], v[142:145], v[186:189], v[52:55]
	v_mfma_f32_16x16x32_bf16 v[52:55], v[146:149], v[190:193], v[52:55]
	v_mfma_f32_16x16x32_bf16 v[36:39], v[142:145], v[194:197], v[36:39]
	v_mfma_f32_16x16x32_bf16 v[36:39], v[146:149], v[214:217], v[36:39]
	v_mfma_f32_16x16x32_bf16 v[28:31], v[154:157], v[194:197], v[28:31]
	v_mfma_f32_16x16x32_bf16 v[28:31], v[158:161], v[214:217], v[28:31]
	v_mfma_f32_16x16x32_bf16 v[12:15], v[154:157], v[218:221], v[12:15]
	v_mfma_f32_16x16x32_bf16 v[12:15], v[158:161], v[234:237], v[12:15]
	v_mfma_f32_16x16x32_bf16 v[16:19], v[142:145], v[218:221], v[16:19]
	v_mfma_f32_16x16x32_bf16 v[16:19], v[146:149], v[234:237], v[16:19]
	s_setprio 0
	s_setprio 1
	s_add_i32 s60, s60, 2
	s_add_u32 s50, s50, 0x100
	s_addc_u32 s51, s51, 0
	s_add_u32 s43, s43, 0x100
	s_addc_u32 s45, s45, 0
	s_nop 0
	v_mfma_f32_16x16x32_bf16 v[56:59], v[162:165], v[178:181], v[56:59]
	v_mfma_f32_16x16x32_bf16 v[56:59], v[166:169], v[182:185], v[56:59]
	v_mfma_f32_16x16x32_bf16 v[48:51], v[170:173], v[178:181], v[48:51]
	v_mfma_f32_16x16x32_bf16 v[48:51], v[174:177], v[182:185], v[48:51]
	v_mfma_f32_16x16x32_bf16 v[32:35], v[170:173], v[186:189], v[32:35]
	v_mfma_f32_16x16x32_bf16 v[32:35], v[174:177], v[190:193], v[32:35]
	v_mfma_f32_16x16x32_bf16 v[40:43], v[162:165], v[186:189], v[40:43]
	v_mfma_f32_16x16x32_bf16 v[40:43], v[166:169], v[190:193], v[40:43]
	v_mfma_f32_16x16x32_bf16 v[24:27], v[162:165], v[194:197], v[24:27]
	v_mfma_f32_16x16x32_bf16 v[24:27], v[166:169], v[214:217], v[24:27]
	v_mfma_f32_16x16x32_bf16 v[20:23], v[170:173], v[194:197], v[20:23]
	v_mfma_f32_16x16x32_bf16 v[20:23], v[174:177], v[214:217], v[20:23]
	v_mfma_f32_16x16x32_bf16 v[4:7], v[170:173], v[218:221], v[4:7]
	v_mfma_f32_16x16x32_bf16 v[4:7], v[174:177], v[234:237], v[4:7]
	v_mfma_f32_16x16x32_bf16 v[8:11], v[162:165], v[218:221], v[8:11]
	v_mfma_f32_16x16x32_bf16 v[8:11], v[166:169], v[234:237], v[8:11]
	s_barrier
	s_cmp_gt_u32 s60, 61
	s_cbranch_scc0 .LBB0_816
	s_setprio 0
	s_and_b64 vcc, exec, s[40:41]
	s_cbranch_vccz .LBB0_819
	s_barrier

; #define PG8_STAGE(bufoff, gbase, voff) do { _Pragma("unroll") for (int _i = 0; _i < 2; ++_i) \
;         __builtin_amdgcn_global_load_lds((const unsigned*)((const char*)(gbase) + (voff)[_i]), (PG8_LAS unsigned*)(lds + (bufoff) + ldsw + _i * 8192), 16, 0, 0); } while (0)
; #define PG8_LDA(dst, b, h) do { _Pragma("unroll") for (int m = 0; m < 4; ++m) _Pragma("unroll") for (int k = 0; k < 2; ++k) dst[m][k] = *(const PG8_LAS bf16x8*)(lds + PG8_SA(b, h) + aoff + m * 2048 + k * 1024); } while (0)
; #define PG8_LDB(dst, b, h) do { _Pragma("unroll") for (int n = 0; n < 2; ++n) _Pragma("unroll") for (int k = 0; k < 2; ++k) dst[n][k] = *(const PG8_LAS bf16x8*)(lds + PG8_SB(b, h) + boff + n * 2048 + k * 1024); } while (0)
; #define PG8_MMA(ai, bj, At, Bt) do { __builtin_amdgcn_s_setprio(1); _Pragma("unroll") for (int m = 0; m < 4; ++m) _Pragma("unroll") for (int n = 0; n < 2; ++n) _Pragma("unroll") for (int k = 0; k < 2; ++k) \
;         acc[ai][bj][m][n] = __builtin_amdgcn_mfma_f32_16x16x32_bf16(Bt[n][k], At[m][k], acc[ai][bj][m][n], 0, 0, 0); __builtin_amdgcn_s_setprio(0); } while (0)
; #define PG8_WAIT_V(n) asm volatile("s_waitcnt vmcnt(" #n ")" ::: "memory")
; #define PG8_WAIT_L(n) asm volatile("s_waitcnt lgkmcnt(" #n ")" ::: "memory")
; #define PG8_BAR __builtin_amdgcn_s_barrier()
; #define PG8_SCHED __builtin_amdgcn_sched_barrier(0)
; template <class Epi, class Sched, bool ALIGN_EPI = false, bool SP2 = false>
; __device__ __forceinline__ void gemm_phase(PG8_LAS unsigned char* lds, const Gemm g, const Sched& S, const Epi& E) {
;     ...
;             if constexpr (SP2) {
;             PG8_LDB(B0, 0, 0); PG8_LDB(B1, 0, 1); PG8_SCHED; PG8_LDA(At, 0, 0); PG8_STAGE(PG8_SA(1, 1), a1 + hstep, voffA);
;             PG8_WAIT_V(8); PG8_WAIT_L(0); PG8_BAR; PG8_MMA(0, 0, At, B0); PG8_MMA(0, 1, At, B1); PG8_BAR; PG8_SCHED;
;             PG8_LDA(At, 0, 1); PG8_STAGE(PG8_SB(0, 0), b2, voffB); PG8_STAGE(PG8_SB(0, 1), b2 + hstep, voffB); PG8_STAGE(PG8_SA(0, 0), a2, voffA);
;             PG8_WAIT_V(8); PG8_WAIT_L(0); PG8_BAR; PG8_MMA(1, 0, At, B0); PG8_MMA(1, 1, At, B1); PG8_BAR; PG8_SCHED;
.LBB0_1032:
	ds_read_b128 v[146:149], v198
	ds_read_b128 v[150:153], v198 offset:1024
	ds_read_b128 v[154:157], v198 offset:2048
	ds_read_b128 v[158:161], v198 offset:3072
	ds_read_b128 v[162:165], v198 offset:16384
	ds_read_b128 v[166:169], v198 offset:17408
	ds_read_b128 v[170:173], v198 offset:18432
	ds_read_b128 v[174:177], v198 offset:19456
	ds_read_b128 v[178:181], v145
	ds_read_b128 v[182:185], v145 offset:1024
	ds_read_b128 v[186:189], v145 offset:2048
	ds_read_b128 v[190:193], v145 offset:3072
	ds_read_b128 v[194:197], v145 offset:4096
	ds_read_b128 v[214:217], v145 offset:5120
	ds_read_b128 v[218:221], v145 offset:6144
	ds_read_b128 v[234:237], v145 offset:7168
	s_setprio 0
	s_add_u32 s0, s50, 0xfffc0080
	s_addc_u32 s1, s51, -1
	s_add_i32 s53, 0, 0x10000
	s_cmp_eq_u32 s52, 12
	s_cselect_b32 s27, s47, s1
	s_cselect_b32 s26, s46, s0
	s_cselect_b32 s1, s49, s45
	s_cselect_b32 s0, s48, s43
	s_add_i32 s64, 0, 0x14000
	s_add_u32 s100, s50, 0xfffc0000
	s_addc_u32 s101, s51, -1
	s_mov_b32 m0, s57
	s_nop 0
	global_load_lds_dwordx4 v136, s[100:101]
	s_mov_b32 m0, s58
	s_nop 0
	global_load_lds_dwordx4 v134, s[100:101]
	s_add_i32 m0, s37, 0xc000
	s_nop 0
	global_load_lds_dwordx4 v138, s[50:51]
	s_add_i32 m0, s37, 0xe000
	s_nop 0
	global_load_lds_dwordx4 v140, s[50:51]
	s_setprio 1
	s_waitcnt vmcnt(8)
	s_waitcnt lgkmcnt(0)
	s_barrier
	v_mfma_f32_16x16x32_bf16 v[128:131], v[146:149], v[178:181], v[128:131]
	v_mfma_f32_16x16x32_bf16 v[128:131], v[150:153], v[182:185], v[128:131]
	v_mfma_f32_16x16x32_bf16 v[124:127], v[154:157], v[178:181], v[124:127]
	v_mfma_f32_16x16x32_bf16 v[124:127], v[158:161], v[182:185], v[124:127]
	v_mfma_f32_16x16x32_bf16 v[116:119], v[154:157], v[186:189], v[116:119]
	v_mfma_f32_16x16x32_bf16 v[116:119], v[158:161], v[190:193], v[116:119]
	v_mfma_f32_16x16x32_bf16 v[120:123], v[146:149], v[186:189], v[120:123]
	v_mfma_f32_16x16x32_bf16 v[120:123], v[150:153], v[190:193], v[120:123]
	v_mfma_f32_16x16x32_bf16 v[104:107], v[146:149], v[194:197], v[104:107]
	v_mfma_f32_16x16x32_bf16 v[104:107], v[150:153], v[214:217], v[104:107]
	v_mfma_f32_16x16x32_bf16 v[100:103], v[154:157], v[194:197], v[100:103]
	v_mfma_f32_16x16x32_bf16 v[100:103], v[158:161], v[214:217], v[100:103]
	v_mfma_f32_16x16x32_bf16 v[84:87], v[154:157], v[218:221], v[84:87]
	v_mfma_f32_16x16x32_bf16 v[84:87], v[158:161], v[234:237], v[84:87]
	v_mfma_f32_16x16x32_bf16 v[88:91], v[146:149], v[218:221], v[88:91]
	v_mfma_f32_16x16x32_bf16 v[88:91], v[150:153], v[234:237], v[88:91]
	s_setprio 0
	s_setprio 1
	v_mfma_f32_16x16x32_bf16 v[112:115], v[162:165], v[178:181], v[112:115]
	v_mfma_f32_16x16x32_bf16 v[112:115], v[166:169], v[182:185], v[112:115]
	v_mfma_f32_16x16x32_bf16 v[108:111], v[170:173], v[178:181], v[108:111]
	v_mfma_f32_16x16x32_bf16 v[108:111], v[174:177], v[182:185], v[108:111]
	v_mfma_f32_16x16x32_bf16 v[92:95], v[170:173], v[186:189], v[92:95]
	v_mfma_f32_16x16x32_bf16 v[92:95], v[174:177], v[190:193], v[92:95]
	v_mfma_f32_16x16x32_bf16 v[96:99], v[162:165], v[186:189], v[96:99]
	v_mfma_f32_16x16x32_bf16 v[96:99], v[166:169], v[190:193], v[96:99]
	v_mfma_f32_16x16x32_bf16 v[80:83], v[162:165], v[194:197], v[80:83]
	v_mfma_f32_16x16x32_bf16 v[80:83], v[166:169], v[214:217], v[80:83]
	v_mfma_f32_16x16x32_bf16 v[76:79], v[170:173], v[194:197], v[76:79]
	v_mfma_f32_16x16x32_bf16 v[76:79], v[174:177], v[214:217], v[76:79]
	v_mfma_f32_16x16x32_bf16 v[68:71], v[170:173], v[218:221], v[68:71]
	v_mfma_f32_16x16x32_bf16 v[68:71], v[174:177], v[234:237], v[68:71]
	v_mfma_f32_16x16x32_bf16 v[72:75], v[162:165], v[218:221], v[72:75]
	v_mfma_f32_16x16x32_bf16 v[72:75], v[166:169], v[234:237], v[72:75]
	s_barrier
	ds_read_b128 v[178:181], v145 offset:16384
	ds_read_b128 v[182:185], v145 offset:17408
	ds_read_b128 v[186:189], v145 offset:18432
	ds_read_b128 v[190:193], v145 offset:19456
	ds_read_b128 v[194:197], v145 offset:20480
	ds_read_b128 v[214:217], v145 offset:21504
	ds_read_b128 v[218:221], v145 offset:22528
	ds_read_b128 v[234:237], v145 offset:23552
	s_setprio 0
	s_add_i32 s53, s53, s10
	s_mov_b32 m0, s53
	s_nop 0
	global_load_lds_dwordx4 v2, s[0:1]
	s_add_i32 m0, s53, 0x2000
	s_add_u32 s62, s0, 0x40000
	s_addc_u32 s63, s1, 0
	s_add_i32 s53, s64, s10
	global_load_lds_dwordx4 v132, s[0:1]
	s_mov_b32 m0, s53
	s_nop 0
	global_load_lds_dwordx4 v2, s[62:63]
	s_add_i32 m0, s53, 0x2000
	s_nop 0
	global_load_lds_dwordx4 v132, s[62:63]
	s_setprio 1
	s_waitcnt vmcnt(6)
	s_waitcnt lgkmcnt(0)
	s_barrier
	v_mfma_f32_16x16x32_bf16 v[64:67], v[146:149], v[178:181], v[64:67]
	v_mfma_f32_16x16x32_bf16 v[64:67], v[150:153], v[182:185], v[64:67]
	v_mfma_f32_16x16x32_bf16 v[60:63], v[154:157], v[178:181], v[60:63]
	v_mfma_f32_16x16x32_bf16 v[60:63], v[158:161], v[182:185], v[60:63]
	v_mfma_f32_16x16x32_bf16 v[52:55], v[154:157], v[186:189], v[52:55]
	v_mfma_f32_16x16x32_bf16 v[52:55], v[158:161], v[190:193], v[52:55]
	v_mfma_f32_16x16x32_bf16 v[56:59], v[146:149], v[186:189], v[56:59]
	v_mfma_f32_16x16x32_bf16 v[56:59], v[150:153], v[190:193], v[56:59]
	v_mfma_f32_16x16x32_bf16 v[40:43], v[146:149], v[194:197], v[40:43]
	v_mfma_f32_16x16x32_bf16 v[40:43], v[150:153], v[214:217], v[40:43]
	v_mfma_f32_16x16x32_bf16 v[36:39], v[154:157], v[194:197], v[36:39]
	v_mfma_f32_16x16x32_bf16 v[36:39], v[158:161], v[214:217], v[36:39]
	v_mfma_f32_16x16x32_bf16 v[20:23], v[154:157], v[218:221], v[20:23]
	v_mfma_f32_16x16x32_bf16 v[20:23], v[158:161], v[234:237], v[20:23]
	v_mfma_f32_16x16x32_bf16 v[24:27], v[146:149], v[218:221], v[24:27]
	v_mfma_f32_16x16x32_bf16 v[24:27], v[150:153], v[234:237], v[24:27]
	s_setprio 0
	s_setprio 1
	v_mfma_f32_16x16x32_bf16 v[48:51], v[162:165], v[178:181], v[48:51]
	v_mfma_f32_16x16x32_bf16 v[48:51], v[166:169], v[182:185], v[48:51]
	v_mfma_f32_16x16x32_bf16 v[44:47], v[170:173], v[178:181], v[44:47]
	v_mfma_f32_16x16x32_bf16 v[44:47], v[174:177], v[182:185], v[44:47]
	v_mfma_f32_16x16x32_bf16 v[28:31], v[170:173], v[186:189], v[28:31]
	v_mfma_f32_16x16x32_bf16 v[28:31], v[174:177], v[190:193], v[28:31]
	v_mfma_f32_16x16x32_bf16 v[32:35], v[162:165], v[186:189], v[32:35]
	v_mfma_f32_16x16x32_bf16 v[32:35], v[166:169], v[190:193], v[32:35]
	v_mfma_f32_16x16x32_bf16 v[16:19], v[162:165], v[194:197], v[16:19]
	v_mfma_f32_16x16x32_bf16 v[16:19], v[166:169], v[214:217], v[16:19]
	v_mfma_f32_16x16x32_bf16 v[12:15], v[170:173], v[194:197], v[12:15]
	v_mfma_f32_16x16x32_bf16 v[12:15], v[174:177], v[214:217], v[12:15]
	v_mfma_f32_16x16x32_bf16 v[4:7], v[170:173], v[218:221], v[4:7]
	v_mfma_f32_16x16x32_bf16 v[4:7], v[174:177], v[234:237], v[4:7]
	v_mfma_f32_16x16x32_bf16 v[8:11], v[162:165], v[218:221], v[8:11]
	v_mfma_f32_16x16x32_bf16 v[8:11], v[166:169], v[234:237], v[8:11]
	s_barrier
; #define PG8_STAGE(bufoff, gbase, voff) do { _Pragma("unroll") for (int _i = 0; _i < 2; ++_i) \
;         __builtin_amdgcn_global_load_lds((const unsigned*)((const char*)(gbase) + (voff)[_i]), (PG8_LAS unsigned*)(lds + (bufoff) + ldsw + _i * 8192), 16, 0, 0); } while (0)
; #define PG8_LDA(dst, b, h) do { _Pragma("unroll") for (int m = 0; m < 4; ++m) _Pragma("unroll") for (int k = 0; k < 2; ++k) dst[m][k] = *(const PG8_LAS bf16x8*)(lds + PG8_SA(b, h) + aoff + m * 2048 + k * 1024); } while (0)
; #define PG8_LDB(dst, b, h) do { _Pragma("unroll") for (int n = 0; n < 2; ++n) _Pragma("unroll") for (int k = 0; k < 2; ++k) dst[n][k] = *(const PG8_LAS bf16x8*)(lds + PG8_SB(b, h) + boff + n * 2048 + k * 1024); } while (0)
; #define PG8_MMA(ai, bj, At, Bt) do { __builtin_amdgcn_s_setprio(1); _Pragma("unroll") for (int m = 0; m < 4; ++m) _Pragma("unroll") for (int n = 0; n < 2; ++n) _Pragma("unroll") for (int k = 0; k < 2; ++k) \
;         acc[ai][bj][m][n] = __builtin_amdgcn_mfma_f32_16x16x32_bf16(Bt[n][k], At[m][k], acc[ai][bj][m][n], 0, 0, 0); __builtin_amdgcn_s_setprio(0); } while (0)
; #define PG8_WAIT_V(n) asm volatile("s_waitcnt vmcnt(" #n ")" ::: "memory")
; #define PG8_WAIT_L(n) asm volatile("s_waitcnt lgkmcnt(" #n ")" ::: "memory")
; #define PG8_BAR __builtin_amdgcn_s_barrier()
; #define PG8_SCHED __builtin_amdgcn_sched_barrier(0)
; template <class Epi, class Sched, bool ALIGN_EPI = false, bool SP2 = false>
; __device__ __forceinline__ void gemm_phase(PG8_LAS unsigned char* lds, const Gemm g, const Sched& S, const Epi& E) {
;     ...
;             PG8_LDB(B0, 1, 0); PG8_LDB(B1, 1, 1); PG8_SCHED; PG8_LDA(At, 1, 0); PG8_STAGE(PG8_SA(0, 1), a2 + hstep, voffA);
;             PG8_WAIT_V(8); PG8_WAIT_L(0); PG8_BAR; PG8_MMA(0, 0, At, B0); PG8_MMA(0, 1, At, B1); PG8_BAR; PG8_SCHED;
;             PG8_LDA(At, 1, 1); PG8_STAGE(PG8_SB(1, 0), b3, voffB); PG8_STAGE(PG8_SB(1, 1), b3 + hstep, voffB); PG8_STAGE(PG8_SA(1, 0), a3, voffA);
;             PG8_WAIT_V(8); PG8_WAIT_L(0); PG8_BAR; PG8_MMA(1, 0, At, B0); PG8_MMA(1, 1, At, B1); PG8_BAR; PG8_SCHED;
	ds_read_b128 v[146:149], v198 offset:32768
	ds_read_b128 v[150:153], v198 offset:33792
	ds_read_b128 v[154:157], v198 offset:34816
	ds_read_b128 v[158:161], v198 offset:35840
	ds_read_b128 v[162:165], v198 offset:49152
	ds_read_b128 v[166:169], v198 offset:50176
	ds_read_b128 v[170:173], v198 offset:51200
	ds_read_b128 v[174:177], v198 offset:52224
	ds_read_b128 v[178:181], v145 offset:32768
	ds_read_b128 v[182:185], v145 offset:33792
	ds_read_b128 v[186:189], v145 offset:34816
	ds_read_b128 v[190:193], v145 offset:35840
	ds_read_b128 v[194:197], v145 offset:36864
	ds_read_b128 v[214:217], v145 offset:37888
	ds_read_b128 v[218:221], v145 offset:38912
	ds_read_b128 v[234:237], v145 offset:39936
	s_setprio 0
	s_add_i32 s53, 0, 0x18000
	s_add_i32 s62, 0, 0x1c000
	s_mov_b32 m0, s37
	s_nop 0
	global_load_lds_dwordx4 v136, s[26:27]
	s_mov_b32 m0, s54
	s_nop 0
	global_load_lds_dwordx4 v134, s[26:27]
	s_add_u32 s26, s26, 0x40000
	s_addc_u32 s27, s27, 0
	s_mov_b32 m0, s55
	s_nop 0
	global_load_lds_dwordx4 v136, s[26:27]
	s_mov_b32 m0, s56
	s_nop 0
	global_load_lds_dwordx4 v134, s[26:27]
	s_nop 0
	s_setprio 1
	s_waitcnt vmcnt(8)
	s_waitcnt lgkmcnt(0)
	s_barrier
	v_mfma_f32_16x16x32_bf16 v[128:131], v[146:149], v[178:181], v[128:131]
	v_mfma_f32_16x16x32_bf16 v[128:131], v[150:153], v[182:185], v[128:131]
	v_mfma_f32_16x16x32_bf16 v[124:127], v[154:157], v[178:181], v[124:127]
	v_mfma_f32_16x16x32_bf16 v[124:127], v[158:161], v[182:185], v[124:127]
	v_mfma_f32_16x16x32_bf16 v[116:119], v[154:157], v[186:189], v[116:119]
	v_mfma_f32_16x16x32_bf16 v[116:119], v[158:161], v[190:193], v[116:119]
	v_mfma_f32_16x16x32_bf16 v[120:123], v[146:149], v[186:189], v[120:123]
	v_mfma_f32_16x16x32_bf16 v[120:123], v[150:153], v[190:193], v[120:123]
	v_mfma_f32_16x16x32_bf16 v[104:107], v[146:149], v[194:197], v[104:107]
	v_mfma_f32_16x16x32_bf16 v[104:107], v[150:153], v[214:217], v[104:107]
	v_mfma_f32_16x16x32_bf16 v[100:103], v[154:157], v[194:197], v[100:103]
	v_mfma_f32_16x16x32_bf16 v[100:103], v[158:161], v[214:217], v[100:103]
	v_mfma_f32_16x16x32_bf16 v[84:87], v[154:157], v[218:221], v[84:87]
	v_mfma_f32_16x16x32_bf16 v[84:87], v[158:161], v[234:237], v[84:87]
	v_mfma_f32_16x16x32_bf16 v[88:91], v[146:149], v[218:221], v[88:91]
	v_mfma_f32_16x16x32_bf16 v[88:91], v[150:153], v[234:237], v[88:91]
	s_setprio 0
	s_setprio 1
	v_mfma_f32_16x16x32_bf16 v[112:115], v[162:165], v[178:181], v[112:115]
	v_mfma_f32_16x16x32_bf16 v[112:115], v[166:169], v[182:185], v[112:115]
	v_mfma_f32_16x16x32_bf16 v[108:111], v[170:173], v[178:181], v[108:111]
	v_mfma_f32_16x16x32_bf16 v[108:111], v[174:177], v[182:185], v[108:111]
	v_mfma_f32_16x16x32_bf16 v[92:95], v[170:173], v[186:189], v[92:95]
	v_mfma_f32_16x16x32_bf16 v[92:95], v[174:177], v[190:193], v[92:95]
	v_mfma_f32_16x16x32_bf16 v[96:99], v[162:165], v[186:189], v[96:99]
	v_mfma_f32_16x16x32_bf16 v[96:99], v[166:169], v[190:193], v[96:99]
	v_mfma_f32_16x16x32_bf16 v[80:83], v[162:165], v[194:197], v[80:83]
	v_mfma_f32_16x16x32_bf16 v[80:83], v[166:169], v[214:217], v[80:83]
	v_mfma_f32_16x16x32_bf16 v[76:79], v[170:173], v[194:197], v[76:79]
	v_mfma_f32_16x16x32_bf16 v[76:79], v[174:177], v[214:217], v[76:79]
	v_mfma_f32_16x16x32_bf16 v[68:71], v[170:173], v[218:221], v[68:71]
	v_mfma_f32_16x16x32_bf16 v[68:71], v[174:177], v[234:237], v[68:71]
	v_mfma_f32_16x16x32_bf16 v[72:75], v[162:165], v[218:221], v[72:75]
	v_mfma_f32_16x16x32_bf16 v[72:75], v[166:169], v[234:237], v[72:75]
	s_barrier
	ds_read_b128 v[178:181], v145 offset:49152
	ds_read_b128 v[182:185], v145 offset:50176
	ds_read_b128 v[186:189], v145 offset:51200
	ds_read_b128 v[190:193], v145 offset:52224
	ds_read_b128 v[194:197], v145 offset:53248
	ds_read_b128 v[214:217], v145 offset:54272
	ds_read_b128 v[218:221], v145 offset:55296
	ds_read_b128 v[234:237], v145 offset:56320
	s_setprio 0
	s_add_i32 s26, s53, s10
	s_mov_b32 m0, s26
	s_add_u32 s0, s0, 0x80
	s_addc_u32 s1, s1, 0
	global_load_lds_dwordx4 v2, s[0:1]
	s_add_i32 m0, s26, 0x2000
	s_add_i32 s26, s62, s10
	global_load_lds_dwordx4 v132, s[0:1]
	s_add_u32 s0, s0, 0x40000
	s_addc_u32 s1, s1, 0
	s_mov_b32 m0, s26
	s_nop 0
	global_load_lds_dwordx4 v2, s[0:1]
	s_add_i32 m0, s26, 0x2000
	s_nop 0
	global_load_lds_dwordx4 v132, s[0:1]
	s_setprio 1
	s_waitcnt vmcnt(6)
	s_waitcnt lgkmcnt(0)
	s_barrier
	v_mfma_f32_16x16x32_bf16 v[64:67], v[146:149], v[178:181], v[64:67]
	v_mfma_f32_16x16x32_bf16 v[64:67], v[150:153], v[182:185], v[64:67]
	v_mfma_f32_16x16x32_bf16 v[60:63], v[154:157], v[178:181], v[60:63]
	v_mfma_f32_16x16x32_bf16 v[60:63], v[158:161], v[182:185], v[60:63]
	v_mfma_f32_16x16x32_bf16 v[52:55], v[154:157], v[186:189], v[52:55]
	v_mfma_f32_16x16x32_bf16 v[52:55], v[158:161], v[190:193], v[52:55]
	v_mfma_f32_16x16x32_bf16 v[56:59], v[146:149], v[186:189], v[56:59]
	v_mfma_f32_16x16x32_bf16 v[56:59], v[150:153], v[190:193], v[56:59]
	v_mfma_f32_16x16x32_bf16 v[40:43], v[146:149], v[194:197], v[40:43]
	v_mfma_f32_16x16x32_bf16 v[40:43], v[150:153], v[214:217], v[40:43]
	v_mfma_f32_16x16x32_bf16 v[36:39], v[154:157], v[194:197], v[36:39]
	v_mfma_f32_16x16x32_bf16 v[36:39], v[158:161], v[214:217], v[36:39]
	v_mfma_f32_16x16x32_bf16 v[20:23], v[154:157], v[218:221], v[20:23]
	v_mfma_f32_16x16x32_bf16 v[20:23], v[158:161], v[234:237], v[20:23]
	v_mfma_f32_16x16x32_bf16 v[24:27], v[146:149], v[218:221], v[24:27]
	v_mfma_f32_16x16x32_bf16 v[24:27], v[150:153], v[234:237], v[24:27]
	s_setprio 0
	s_setprio 1
	s_add_i32 s52, s52, 2
	s_add_u32 s50, s50, 0x100
	s_addc_u32 s51, s51, 0
	s_add_u32 s43, s43, 0x100
	s_addc_u32 s45, s45, 0
	s_nop 0
	v_mfma_f32_16x16x32_bf16 v[48:51], v[162:165], v[178:181], v[48:51]
	v_mfma_f32_16x16x32_bf16 v[48:51], v[166:169], v[182:185], v[48:51]
	v_mfma_f32_16x16x32_bf16 v[44:47], v[170:173], v[178:181], v[44:47]
	v_mfma_f32_16x16x32_bf16 v[44:47], v[174:177], v[182:185], v[44:47]
	v_mfma_f32_16x16x32_bf16 v[28:31], v[170:173], v[186:189], v[28:31]
	v_mfma_f32_16x16x32_bf16 v[28:31], v[174:177], v[190:193], v[28:31]
	v_mfma_f32_16x16x32_bf16 v[32:35], v[162:165], v[186:189], v[32:35]
	v_mfma_f32_16x16x32_bf16 v[32:35], v[166:169], v[190:193], v[32:35]
	v_mfma_f32_16x16x32_bf16 v[16:19], v[162:165], v[194:197], v[16:19]
	v_mfma_f32_16x16x32_bf16 v[16:19], v[166:169], v[214:217], v[16:19]
	v_mfma_f32_16x16x32_bf16 v[12:15], v[170:173], v[194:197], v[12:15]
	v_mfma_f32_16x16x32_bf16 v[12:15], v[174:177], v[214:217], v[12:15]
	v_mfma_f32_16x16x32_bf16 v[4:7], v[170:173], v[218:221], v[4:7]
	v_mfma_f32_16x16x32_bf16 v[4:7], v[174:177], v[234:237], v[4:7]
	v_mfma_f32_16x16x32_bf16 v[8:11], v[162:165], v[218:221], v[8:11]
	v_mfma_f32_16x16x32_bf16 v[8:11], v[166:169], v[234:237], v[8:11]
	s_barrier
	s_cmp_gt_u32 s52, 13
	s_cbranch_scc0 .LBB0_1032
	s_setprio 0
	s_and_b64 vcc, exec, s[40:41]
	s_cbranch_vccz .LBB0_1035
	s_barrier

; #define PG8_STAGE(bufoff, gbase, voff) do { _Pragma("unroll") for (int _i = 0; _i < 2; ++_i) \
;         __builtin_amdgcn_global_load_lds((const unsigned*)((const char*)(gbase) + (voff)[_i]), (PG8_LAS unsigned*)(lds + (bufoff) + ldsw + _i * 8192), 16, 0, 0); } while (0)
; #define PG8_LDA(dst, b, h) do { _Pragma("unroll") for (int m = 0; m < 4; ++m) _Pragma("unroll") for (int k = 0; k < 2; ++k) dst[m][k] = *(const PG8_LAS bf16x8*)(lds + PG8_SA(b, h) + aoff + m * 2048 + k * 1024); } while (0)
; #define PG8_LDB(dst, b, h) do { _Pragma("unroll") for (int n = 0; n < 2; ++n) _Pragma("unroll") for (int k = 0; k < 2; ++k) dst[n][k] = *(const PG8_LAS bf16x8*)(lds + PG8_SB(b, h) + boff + n * 2048 + k * 1024); } while (0)
; #define PG8_MMA(ai, bj, At, Bt) do { __builtin_amdgcn_s_setprio(1); _Pragma("unroll") for (int m = 0; m < 4; ++m) _Pragma("unroll") for (int n = 0; n < 2; ++n) _Pragma("unroll") for (int k = 0; k < 2; ++k) \
;         acc[ai][bj][m][n] = __builtin_amdgcn_mfma_f32_16x16x32_bf16(Bt[n][k], At[m][k], acc[ai][bj][m][n], 0, 0, 0); __builtin_amdgcn_s_setprio(0); } while (0)
; #define PG8_WAIT_V(n) asm volatile("s_waitcnt vmcnt(" #n ")" ::: "memory")
; #define PG8_WAIT_L(n) asm volatile("s_waitcnt lgkmcnt(" #n ")" ::: "memory")
; #define PG8_BAR __builtin_amdgcn_s_barrier()
; #define PG8_SCHED __builtin_amdgcn_sched_barrier(0)
; template <class Epi, class Sched, bool ALIGN_EPI = false, bool SP2 = false>
; __device__ __forceinline__ void gemm_phase(PG8_LAS unsigned char* lds, const Gemm g, const Sched& S, const Epi& E) {
;     ...
;             if constexpr (SP2) {
;             PG8_LDB(B0, 0, 0); PG8_LDB(B1, 0, 1); PG8_SCHED; PG8_LDA(At, 0, 0); PG8_STAGE(PG8_SA(1, 1), a1 + hstep, voffA);
;             PG8_WAIT_V(8); PG8_WAIT_L(0); PG8_BAR; PG8_MMA(0, 0, At, B0); PG8_MMA(0, 1, At, B1); PG8_BAR; PG8_SCHED;
;             PG8_LDA(At, 0, 1); PG8_STAGE(PG8_SB(0, 0), b2, voffB); PG8_STAGE(PG8_SB(0, 1), b2 + hstep, voffB); PG8_STAGE(PG8_SA(0, 0), a2, voffA);
;             PG8_WAIT_V(8); PG8_WAIT_L(0); PG8_BAR; PG8_MMA(1, 0, At, B0); PG8_MMA(1, 1, At, B1); PG8_BAR; PG8_SCHED;
.LBB0_1051:
	ds_read_b128 v[84:87], v154
	ds_read_b128 v[88:91], v154 offset:1024
	ds_read_b128 v[162:165], v154 offset:2048
	ds_read_b128 v[166:169], v154 offset:3072
	ds_read_b128 v[170:173], v154 offset:16384
	ds_read_b128 v[174:177], v154 offset:17408
	ds_read_b128 v[178:181], v154 offset:18432
	ds_read_b128 v[182:185], v154 offset:19456
	ds_read_b128 v[186:189], v160
	ds_read_b128 v[190:193], v160 offset:1024
	ds_read_b128 v[194:197], v160 offset:2048
	ds_read_b128 v[214:217], v160 offset:3072
	ds_read_b128 v[218:221], v160 offset:4096
	ds_read_b128 v[234:237], v160 offset:5120
	ds_read_b128 v[238:241], v160 offset:6144
	ds_read_b128 v[242:245], v160 offset:7168
	s_setprio 0
	s_add_u32 s0, s52, 0xfffe0080
	s_addc_u32 s1, s53, -1
	s_add_i32 s63, 0, 0x10000
	s_cmp_eq_u32 s62, 4
	s_cselect_b32 s27, s45, s1
	s_cselect_b32 s26, s58, s0
	s_cselect_b32 s1, s43, s61
	s_cselect_b32 s0, s59, s60
	s_add_i32 s66, 0, 0x14000
	s_add_u32 s100, s52, 0xfffe0000
	s_addc_u32 s101, s53, -1
	s_mov_b32 m0, s54
	s_nop 0
	global_load_lds_dwordx4 v140, s[100:101]
	s_mov_b32 m0, s55
	s_nop 0
	global_load_lds_dwordx4 v142, s[100:101]
	s_add_i32 m0, s10, 0xc000
	s_nop 0
	global_load_lds_dwordx4 v150, s[52:53]
	s_add_i32 m0, s10, 0xe000
	s_nop 0
	global_load_lds_dwordx4 v152, s[52:53]
	s_setprio 1
	s_waitcnt vmcnt(8)
	s_waitcnt lgkmcnt(0)
	s_barrier
	v_mfma_f32_16x16x32_bf16 v[136:139], v[84:87], v[186:189], v[136:139]
	v_mfma_f32_16x16x32_bf16 v[136:139], v[88:91], v[190:193], v[136:139]
	v_mfma_f32_16x16x32_bf16 v[132:135], v[162:165], v[186:189], v[132:135]
	v_mfma_f32_16x16x32_bf16 v[132:135], v[166:169], v[190:193], v[132:135]
	v_mfma_f32_16x16x32_bf16 v[120:123], v[162:165], v[194:197], v[120:123]
	v_mfma_f32_16x16x32_bf16 v[120:123], v[166:169], v[214:217], v[120:123]
	v_mfma_f32_16x16x32_bf16 v[128:131], v[84:87], v[194:197], v[128:131]
	v_mfma_f32_16x16x32_bf16 v[128:131], v[88:91], v[214:217], v[128:131]
	v_mfma_f32_16x16x32_bf16 v[104:107], v[84:87], v[218:221], v[104:107]
	v_mfma_f32_16x16x32_bf16 v[104:107], v[88:91], v[234:237], v[104:107]
	v_mfma_f32_16x16x32_bf16 v[100:103], v[162:165], v[218:221], v[100:103]
	v_mfma_f32_16x16x32_bf16 v[100:103], v[166:169], v[234:237], v[100:103]
	v_mfma_f32_16x16x32_bf16 v[76:79], v[162:165], v[238:241], v[76:79]
	v_mfma_f32_16x16x32_bf16 v[76:79], v[166:169], v[242:245], v[76:79]
	v_mfma_f32_16x16x32_bf16 v[80:83], v[84:87], v[238:241], v[80:83]
	v_mfma_f32_16x16x32_bf16 v[80:83], v[88:91], v[242:245], v[80:83]
	s_setprio 0
	s_setprio 1
	v_mfma_f32_16x16x32_bf16 v[124:127], v[170:173], v[186:189], v[124:127]
	v_mfma_f32_16x16x32_bf16 v[124:127], v[174:177], v[190:193], v[124:127]
	v_mfma_f32_16x16x32_bf16 v[116:119], v[178:181], v[186:189], v[116:119]
	v_mfma_f32_16x16x32_bf16 v[116:119], v[182:185], v[190:193], v[116:119]
	v_mfma_f32_16x16x32_bf16 v[108:111], v[178:181], v[194:197], v[108:111]
	v_mfma_f32_16x16x32_bf16 v[108:111], v[182:185], v[214:217], v[108:111]
	v_mfma_f32_16x16x32_bf16 v[112:115], v[170:173], v[194:197], v[112:115]
	v_mfma_f32_16x16x32_bf16 v[112:115], v[174:177], v[214:217], v[112:115]
	v_mfma_f32_16x16x32_bf16 v[96:99], v[170:173], v[218:221], v[96:99]
	v_mfma_f32_16x16x32_bf16 v[96:99], v[174:177], v[234:237], v[96:99]
	v_mfma_f32_16x16x32_bf16 v[92:95], v[178:181], v[218:221], v[92:95]
	v_mfma_f32_16x16x32_bf16 v[92:95], v[182:185], v[234:237], v[92:95]
	v_mfma_f32_16x16x32_bf16 v[68:71], v[178:181], v[238:241], v[68:71]
	v_mfma_f32_16x16x32_bf16 v[68:71], v[182:185], v[242:245], v[68:71]
	v_mfma_f32_16x16x32_bf16 v[72:75], v[170:173], v[238:241], v[72:75]
	v_mfma_f32_16x16x32_bf16 v[72:75], v[174:177], v[242:245], v[72:75]
	s_barrier
	ds_read_b128 v[186:189], v160 offset:16384
	ds_read_b128 v[190:193], v160 offset:17408
	ds_read_b128 v[194:197], v160 offset:18432
	ds_read_b128 v[214:217], v160 offset:19456
	ds_read_b128 v[218:221], v160 offset:20480
	ds_read_b128 v[234:237], v160 offset:21504
	ds_read_b128 v[238:241], v160 offset:22528
	ds_read_b128 v[242:245], v160 offset:23552
	s_setprio 0
	s_add_i32 s63, s63, s9
	s_mov_b32 m0, s63
	s_nop 0
	global_load_lds_dwordx4 v2, s[0:1]
	s_add_i32 m0, s63, 0x2000
	s_add_u32 s64, s0, 0x20000
	s_addc_u32 s65, s1, 0
	s_add_i32 s63, s66, s9
	global_load_lds_dwordx4 v144, s[0:1]
	s_mov_b32 m0, s63
	s_nop 0
	global_load_lds_dwordx4 v2, s[64:65]
	s_add_i32 m0, s63, 0x2000
	s_nop 0
	global_load_lds_dwordx4 v144, s[64:65]
	s_setprio 1
	s_waitcnt vmcnt(6)
	s_waitcnt lgkmcnt(0)
	s_barrier
	v_mfma_f32_16x16x32_bf16 v[64:67], v[84:87], v[186:189], v[64:67]
	v_mfma_f32_16x16x32_bf16 v[64:67], v[88:91], v[190:193], v[64:67]
	v_mfma_f32_16x16x32_bf16 v[60:63], v[162:165], v[186:189], v[60:63]
	v_mfma_f32_16x16x32_bf16 v[60:63], v[166:169], v[190:193], v[60:63]
	v_mfma_f32_16x16x32_bf16 v[44:47], v[162:165], v[194:197], v[44:47]
	v_mfma_f32_16x16x32_bf16 v[44:47], v[166:169], v[214:217], v[44:47]
	v_mfma_f32_16x16x32_bf16 v[48:51], v[84:87], v[194:197], v[48:51]
	v_mfma_f32_16x16x32_bf16 v[48:51], v[88:91], v[214:217], v[48:51]
	v_mfma_f32_16x16x32_bf16 v[32:35], v[84:87], v[218:221], v[32:35]
	v_mfma_f32_16x16x32_bf16 v[32:35], v[88:91], v[234:237], v[32:35]
	v_mfma_f32_16x16x32_bf16 v[28:31], v[162:165], v[218:221], v[28:31]
	v_mfma_f32_16x16x32_bf16 v[28:31], v[166:169], v[234:237], v[28:31]
	v_mfma_f32_16x16x32_bf16 v[12:15], v[162:165], v[238:241], v[12:15]
	v_mfma_f32_16x16x32_bf16 v[12:15], v[166:169], v[242:245], v[12:15]
	v_mfma_f32_16x16x32_bf16 v[16:19], v[84:87], v[238:241], v[16:19]
	v_mfma_f32_16x16x32_bf16 v[16:19], v[88:91], v[242:245], v[16:19]
	s_setprio 0
	s_setprio 1
	v_mfma_f32_16x16x32_bf16 v[56:59], v[170:173], v[186:189], v[56:59]
	v_mfma_f32_16x16x32_bf16 v[56:59], v[174:177], v[190:193], v[56:59]
	v_mfma_f32_16x16x32_bf16 v[52:55], v[178:181], v[186:189], v[52:55]
	v_mfma_f32_16x16x32_bf16 v[52:55], v[182:185], v[190:193], v[52:55]
	v_mfma_f32_16x16x32_bf16 v[36:39], v[178:181], v[194:197], v[36:39]
	v_mfma_f32_16x16x32_bf16 v[36:39], v[182:185], v[214:217], v[36:39]
	v_mfma_f32_16x16x32_bf16 v[40:43], v[170:173], v[194:197], v[40:43]
	v_mfma_f32_16x16x32_bf16 v[40:43], v[174:177], v[214:217], v[40:43]
	v_mfma_f32_16x16x32_bf16 v[24:27], v[170:173], v[218:221], v[24:27]
	v_mfma_f32_16x16x32_bf16 v[24:27], v[174:177], v[234:237], v[24:27]
	v_mfma_f32_16x16x32_bf16 v[20:23], v[178:181], v[218:221], v[20:23]
	v_mfma_f32_16x16x32_bf16 v[20:23], v[182:185], v[234:237], v[20:23]
	v_mfma_f32_16x16x32_bf16 v[4:7], v[178:181], v[238:241], v[4:7]
	v_mfma_f32_16x16x32_bf16 v[4:7], v[182:185], v[242:245], v[4:7]
	v_mfma_f32_16x16x32_bf16 v[8:11], v[170:173], v[238:241], v[8:11]
	v_mfma_f32_16x16x32_bf16 v[8:11], v[174:177], v[242:245], v[8:11]
	s_barrier
; #define PG8_STAGE(bufoff, gbase, voff) do { _Pragma("unroll") for (int _i = 0; _i < 2; ++_i) \
;         __builtin_amdgcn_global_load_lds((const unsigned*)((const char*)(gbase) + (voff)[_i]), (PG8_LAS unsigned*)(lds + (bufoff) + ldsw + _i * 8192), 16, 0, 0); } while (0)
; #define PG8_LDA(dst, b, h) do { _Pragma("unroll") for (int m = 0; m < 4; ++m) _Pragma("unroll") for (int k = 0; k < 2; ++k) dst[m][k] = *(const PG8_LAS bf16x8*)(lds + PG8_SA(b, h) + aoff + m * 2048 + k * 1024); } while (0)
; #define PG8_LDB(dst, b, h) do { _Pragma("unroll") for (int n = 0; n < 2; ++n) _Pragma("unroll") for (int k = 0; k < 2; ++k) dst[n][k] = *(const PG8_LAS bf16x8*)(lds + PG8_SB(b, h) + boff + n * 2048 + k * 1024); } while (0)
; #define PG8_MMA(ai, bj, At, Bt) do { __builtin_amdgcn_s_setprio(1); _Pragma("unroll") for (int m = 0; m < 4; ++m) _Pragma("unroll") for (int n = 0; n < 2; ++n) _Pragma("unroll") for (int k = 0; k < 2; ++k) \
;         acc[ai][bj][m][n] = __builtin_amdgcn_mfma_f32_16x16x32_bf16(Bt[n][k], At[m][k], acc[ai][bj][m][n], 0, 0, 0); __builtin_amdgcn_s_setprio(0); } while (0)
; #define PG8_WAIT_V(n) asm volatile("s_waitcnt vmcnt(" #n ")" ::: "memory")
; #define PG8_WAIT_L(n) asm volatile("s_waitcnt lgkmcnt(" #n ")" ::: "memory")
; #define PG8_BAR __builtin_amdgcn_s_barrier()
; #define PG8_SCHED __builtin_amdgcn_sched_barrier(0)
; template <class Epi, class Sched, bool ALIGN_EPI = false, bool SP2 = false>
; __device__ __forceinline__ void gemm_phase(PG8_LAS unsigned char* lds, const Gemm g, const Sched& S, const Epi& E) {
;     ...
;             PG8_LDB(B0, 1, 0); PG8_LDB(B1, 1, 1); PG8_SCHED; PG8_LDA(At, 1, 0); PG8_STAGE(PG8_SA(0, 1), a2 + hstep, voffA);
;             PG8_WAIT_V(8); PG8_WAIT_L(0); PG8_BAR; PG8_MMA(0, 0, At, B0); PG8_MMA(0, 1, At, B1); PG8_BAR; PG8_SCHED;
;             PG8_LDA(At, 1, 1); PG8_STAGE(PG8_SB(1, 0), b3, voffB); PG8_STAGE(PG8_SB(1, 1), b3 + hstep, voffB); PG8_STAGE(PG8_SA(1, 0), a3, voffA);
;             PG8_WAIT_V(8); PG8_WAIT_L(0); PG8_BAR; PG8_MMA(1, 0, At, B0); PG8_MMA(1, 1, At, B1); PG8_BAR; PG8_SCHED;
	ds_read_b128 v[84:87], v154 offset:32768
	ds_read_b128 v[88:91], v154 offset:33792
	ds_read_b128 v[162:165], v154 offset:34816
	ds_read_b128 v[166:169], v154 offset:35840
	ds_read_b128 v[170:173], v154 offset:49152
	ds_read_b128 v[174:177], v154 offset:50176
	ds_read_b128 v[178:181], v154 offset:51200
	ds_read_b128 v[182:185], v154 offset:52224
	ds_read_b128 v[186:189], v160 offset:32768
	ds_read_b128 v[190:193], v160 offset:33792
	ds_read_b128 v[194:197], v160 offset:34816
	ds_read_b128 v[214:217], v160 offset:35840
	ds_read_b128 v[218:221], v160 offset:36864
	ds_read_b128 v[234:237], v160 offset:37888
	ds_read_b128 v[238:241], v160 offset:38912
	ds_read_b128 v[242:245], v160 offset:39936
	s_setprio 0
	s_add_i32 s63, 0, 0x18000
	s_add_i32 s64, 0, 0x1c000
	s_mov_b32 m0, s10
	s_nop 0
	global_load_lds_dwordx4 v140, s[26:27]
	s_mov_b32 m0, s11
	s_nop 0
	global_load_lds_dwordx4 v142, s[26:27]
	s_add_u32 s26, s26, 0x20000
	s_addc_u32 s27, s27, 0
	s_mov_b32 m0, s25
	s_nop 0
	global_load_lds_dwordx4 v140, s[26:27]
	s_mov_b32 m0, s51
	s_nop 0
	global_load_lds_dwordx4 v142, s[26:27]
	s_nop 0
	s_setprio 1
	s_waitcnt vmcnt(8)
	s_waitcnt lgkmcnt(0)
	s_barrier
	v_mfma_f32_16x16x32_bf16 v[136:139], v[84:87], v[186:189], v[136:139]
	v_mfma_f32_16x16x32_bf16 v[136:139], v[88:91], v[190:193], v[136:139]
	v_mfma_f32_16x16x32_bf16 v[132:135], v[162:165], v[186:189], v[132:135]
	v_mfma_f32_16x16x32_bf16 v[132:135], v[166:169], v[190:193], v[132:135]
	v_mfma_f32_16x16x32_bf16 v[120:123], v[162:165], v[194:197], v[120:123]
	v_mfma_f32_16x16x32_bf16 v[120:123], v[166:169], v[214:217], v[120:123]
	v_mfma_f32_16x16x32_bf16 v[128:131], v[84:87], v[194:197], v[128:131]
	v_mfma_f32_16x16x32_bf16 v[128:131], v[88:91], v[214:217], v[128:131]
	v_mfma_f32_16x16x32_bf16 v[104:107], v[84:87], v[218:221], v[104:107]
	v_mfma_f32_16x16x32_bf16 v[104:107], v[88:91], v[234:237], v[104:107]
	v_mfma_f32_16x16x32_bf16 v[100:103], v[162:165], v[218:221], v[100:103]
	v_mfma_f32_16x16x32_bf16 v[100:103], v[166:169], v[234:237], v[100:103]
	v_mfma_f32_16x16x32_bf16 v[76:79], v[162:165], v[238:241], v[76:79]
	v_mfma_f32_16x16x32_bf16 v[76:79], v[166:169], v[242:245], v[76:79]
	v_mfma_f32_16x16x32_bf16 v[80:83], v[84:87], v[238:241], v[80:83]
	v_mfma_f32_16x16x32_bf16 v[80:83], v[88:91], v[242:245], v[80:83]
	s_setprio 0
	s_setprio 1
	v_mfma_f32_16x16x32_bf16 v[124:127], v[170:173], v[186:189], v[124:127]
	v_mfma_f32_16x16x32_bf16 v[124:127], v[174:177], v[190:193], v[124:127]
	v_mfma_f32_16x16x32_bf16 v[116:119], v[178:181], v[186:189], v[116:119]
	v_mfma_f32_16x16x32_bf16 v[116:119], v[182:185], v[190:193], v[116:119]
	v_mfma_f32_16x16x32_bf16 v[108:111], v[178:181], v[194:197], v[108:111]
	v_mfma_f32_16x16x32_bf16 v[108:111], v[182:185], v[214:217], v[108:111]
	v_mfma_f32_16x16x32_bf16 v[112:115], v[170:173], v[194:197], v[112:115]
	v_mfma_f32_16x16x32_bf16 v[112:115], v[174:177], v[214:217], v[112:115]
	v_mfma_f32_16x16x32_bf16 v[96:99], v[170:173], v[218:221], v[96:99]
	v_mfma_f32_16x16x32_bf16 v[96:99], v[174:177], v[234:237], v[96:99]
	v_mfma_f32_16x16x32_bf16 v[92:95], v[178:181], v[218:221], v[92:95]
	v_mfma_f32_16x16x32_bf16 v[92:95], v[182:185], v[234:237], v[92:95]
	v_mfma_f32_16x16x32_bf16 v[68:71], v[178:181], v[238:241], v[68:71]
	v_mfma_f32_16x16x32_bf16 v[68:71], v[182:185], v[242:245], v[68:71]
	v_mfma_f32_16x16x32_bf16 v[72:75], v[170:173], v[238:241], v[72:75]
	v_mfma_f32_16x16x32_bf16 v[72:75], v[174:177], v[242:245], v[72:75]
	s_barrier
	ds_read_b128 v[186:189], v160 offset:49152
	ds_read_b128 v[190:193], v160 offset:50176
	ds_read_b128 v[194:197], v160 offset:51200
	ds_read_b128 v[214:217], v160 offset:52224
	ds_read_b128 v[218:221], v160 offset:53248
	ds_read_b128 v[234:237], v160 offset:54272
	ds_read_b128 v[238:241], v160 offset:55296
	ds_read_b128 v[242:245], v160 offset:56320
	s_setprio 0
	s_add_i32 s26, s63, s9
	s_mov_b32 m0, s26
	s_add_u32 s0, s0, 0x80
	s_addc_u32 s1, s1, 0
	global_load_lds_dwordx4 v2, s[0:1]
	s_add_i32 m0, s26, 0x2000
	s_add_i32 s26, s64, s9
	global_load_lds_dwordx4 v144, s[0:1]
	s_add_u32 s0, s0, 0x20000
	s_addc_u32 s1, s1, 0
	s_mov_b32 m0, s26
	s_nop 0
	global_load_lds_dwordx4 v2, s[0:1]
	s_add_i32 m0, s26, 0x2000
	s_nop 0
	global_load_lds_dwordx4 v144, s[0:1]
	s_setprio 1
	s_waitcnt vmcnt(6)
	s_waitcnt lgkmcnt(0)
	s_barrier
	v_mfma_f32_16x16x32_bf16 v[64:67], v[84:87], v[186:189], v[64:67]
	v_mfma_f32_16x16x32_bf16 v[64:67], v[88:91], v[190:193], v[64:67]
	v_mfma_f32_16x16x32_bf16 v[60:63], v[162:165], v[186:189], v[60:63]
	v_mfma_f32_16x16x32_bf16 v[60:63], v[166:169], v[190:193], v[60:63]
	v_mfma_f32_16x16x32_bf16 v[44:47], v[162:165], v[194:197], v[44:47]
	v_mfma_f32_16x16x32_bf16 v[44:47], v[166:169], v[214:217], v[44:47]
	v_mfma_f32_16x16x32_bf16 v[48:51], v[84:87], v[194:197], v[48:51]
	v_mfma_f32_16x16x32_bf16 v[48:51], v[88:91], v[214:217], v[48:51]
	v_mfma_f32_16x16x32_bf16 v[32:35], v[84:87], v[218:221], v[32:35]
	v_mfma_f32_16x16x32_bf16 v[32:35], v[88:91], v[234:237], v[32:35]
	v_mfma_f32_16x16x32_bf16 v[28:31], v[162:165], v[218:221], v[28:31]
	v_mfma_f32_16x16x32_bf16 v[28:31], v[166:169], v[234:237], v[28:31]
	v_mfma_f32_16x16x32_bf16 v[12:15], v[162:165], v[238:241], v[12:15]
	v_mfma_f32_16x16x32_bf16 v[12:15], v[166:169], v[242:245], v[12:15]
	v_mfma_f32_16x16x32_bf16 v[16:19], v[84:87], v[238:241], v[16:19]
	v_mfma_f32_16x16x32_bf16 v[16:19], v[88:91], v[242:245], v[16:19]
	s_setprio 0
	s_setprio 1
	s_add_i32 s62, s62, 2
	s_add_u32 s52, s52, 0x100
	s_addc_u32 s53, s53, 0
	s_add_u32 s60, s60, 0x100
	s_addc_u32 s61, s61, 0
	s_nop 0
	v_mfma_f32_16x16x32_bf16 v[56:59], v[170:173], v[186:189], v[56:59]
	v_mfma_f32_16x16x32_bf16 v[56:59], v[174:177], v[190:193], v[56:59]
	v_mfma_f32_16x16x32_bf16 v[52:55], v[178:181], v[186:189], v[52:55]
	v_mfma_f32_16x16x32_bf16 v[52:55], v[182:185], v[190:193], v[52:55]
	v_mfma_f32_16x16x32_bf16 v[36:39], v[178:181], v[194:197], v[36:39]
	v_mfma_f32_16x16x32_bf16 v[36:39], v[182:185], v[214:217], v[36:39]
	v_mfma_f32_16x16x32_bf16 v[40:43], v[170:173], v[194:197], v[40:43]
	v_mfma_f32_16x16x32_bf16 v[40:43], v[174:177], v[214:217], v[40:43]
	v_mfma_f32_16x16x32_bf16 v[24:27], v[170:173], v[218:221], v[24:27]
	v_mfma_f32_16x16x32_bf16 v[24:27], v[174:177], v[234:237], v[24:27]
	v_mfma_f32_16x16x32_bf16 v[20:23], v[178:181], v[218:221], v[20:23]
	v_mfma_f32_16x16x32_bf16 v[20:23], v[182:185], v[234:237], v[20:23]
	v_mfma_f32_16x16x32_bf16 v[4:7], v[178:181], v[238:241], v[4:7]
	v_mfma_f32_16x16x32_bf16 v[4:7], v[182:185], v[242:245], v[4:7]
	v_mfma_f32_16x16x32_bf16 v[8:11], v[170:173], v[238:241], v[8:11]
	v_mfma_f32_16x16x32_bf16 v[8:11], v[174:177], v[242:245], v[8:11]
	s_barrier
	s_cmp_gt_u32 s62, 5
	s_cbranch_scc0 .LBB0_1051
	s_setprio 0
	s_and_b64 vcc, exec, s[36:37]
	s_cbranch_vccz .LBB0_1054
	s_barrier

; #define PG8_STAGE(bufoff, gbase, voff) do { _Pragma("unroll") for (int _i = 0; _i < 2; ++_i) \
;         __builtin_amdgcn_global_load_lds((const unsigned*)((const char*)(gbase) + (voff)[_i]), (PG8_LAS unsigned*)(lds + (bufoff) + ldsw + _i * 8192), 16, 0, 0); } while (0)
; #define PG8_LDA(dst, b, h) do { _Pragma("unroll") for (int m = 0; m < 4; ++m) _Pragma("unroll") for (int k = 0; k < 2; ++k) dst[m][k] = *(const PG8_LAS bf16x8*)(lds + PG8_SA(b, h) + aoff + m * 2048 + k * 1024); } while (0)
; #define PG8_LDB(dst, b, h) do { _Pragma("unroll") for (int n = 0; n < 2; ++n) _Pragma("unroll") for (int k = 0; k < 2; ++k) dst[n][k] = *(const PG8_LAS bf16x8*)(lds + PG8_SB(b, h) + boff + n * 2048 + k * 1024); } while (0)
; #define PG8_MMA(ai, bj, At, Bt) do { __builtin_amdgcn_s_setprio(1); _Pragma("unroll") for (int m = 0; m < 4; ++m) _Pragma("unroll") for (int n = 0; n < 2; ++n) _Pragma("unroll") for (int k = 0; k < 2; ++k) \
;         acc[ai][bj][m][n] = __builtin_amdgcn_mfma_f32_16x16x32_bf16(Bt[n][k], At[m][k], acc[ai][bj][m][n], 0, 0, 0); __builtin_amdgcn_s_setprio(0); } while (0)
; #define PG8_WAIT_V(n) asm volatile("s_waitcnt vmcnt(" #n ")" ::: "memory")
; #define PG8_WAIT_L(n) asm volatile("s_waitcnt lgkmcnt(" #n ")" ::: "memory")
; #define PG8_BAR __builtin_amdgcn_s_barrier()
; #define PG8_SCHED __builtin_amdgcn_sched_barrier(0)
; template <class Epi, class Sched, bool ALIGN_EPI = false, bool SP2 = false>
; __device__ __forceinline__ void gemm_phase(PG8_LAS unsigned char* lds, const Gemm g, const Sched& S, const Epi& E) {
;     ...
;             if constexpr (SP2) {
;             PG8_LDB(B0, 0, 0); PG8_LDB(B1, 0, 1); PG8_SCHED; PG8_LDA(At, 0, 0); PG8_STAGE(PG8_SA(1, 1), a1 + hstep, voffA);
;             PG8_WAIT_V(8); PG8_WAIT_L(0); PG8_BAR; PG8_MMA(0, 0, At, B0); PG8_MMA(0, 1, At, B1); PG8_BAR; PG8_SCHED;
;             PG8_LDA(At, 0, 1); PG8_STAGE(PG8_SB(0, 0), b2, voffB); PG8_STAGE(PG8_SB(0, 1), b2 + hstep, voffB); PG8_STAGE(PG8_SA(0, 0), a2, voffA);
;             PG8_WAIT_V(8); PG8_WAIT_L(0); PG8_BAR; PG8_MMA(1, 0, At, B0); PG8_MMA(1, 1, At, B1); PG8_BAR; PG8_SCHED;
.LBB0_1624:
	ds_read_b128 v[142:145], v210
	ds_read_b128 v[150:153], v210 offset:1024
	ds_read_b128 v[154:157], v210 offset:2048
	ds_read_b128 v[158:161], v210 offset:3072
	ds_read_b128 v[162:165], v210 offset:16384
	ds_read_b128 v[166:169], v210 offset:17408
	ds_read_b128 v[170:173], v210 offset:18432
	ds_read_b128 v[174:177], v210 offset:19456
	ds_read_b128 v[178:181], v149
	ds_read_b128 v[182:185], v149 offset:1024
	ds_read_b128 v[186:189], v149 offset:2048
	ds_read_b128 v[190:193], v149 offset:3072
	ds_read_b128 v[194:197], v149 offset:4096
	ds_read_b128 v[198:201], v149 offset:5120
	ds_read_b128 v[202:205], v149 offset:6144
	ds_read_b128 v[206:209], v149 offset:7168
	s_setprio 0
	s_add_u32 s0, s56, 0xfff00080
	s_addc_u32 s1, s57, -1
	s_add_i32 s63, 0, 0x10000
	s_cmp_eq_u32 s62, 60
	s_cselect_b32 s27, s51, s1
	s_cselect_b32 s26, s50, s0
	s_cselect_b32 s1, s53, s49
	s_cselect_b32 s0, s52, s47
	s_add_i32 s66, 0, 0x14000
	s_add_u32 s100, s56, 0xfff00000
	s_addc_u32 s101, s57, -1
	s_mov_b32 m0, s58
	s_nop 0
	global_load_lds_dwordx4 v132, s[100:101]
	s_mov_b32 m0, s59
	s_nop 0
	global_load_lds_dwordx4 v134, s[100:101]
	s_add_i32 m0, s10, 0xc000
	s_nop 0
	global_load_lds_dwordx4 v138, s[56:57]
	s_add_i32 m0, s10, 0xe000
	s_nop 0
	global_load_lds_dwordx4 v140, s[56:57]
	s_nop 0
	s_setprio 1
	s_waitcnt vmcnt(8)
	s_waitcnt lgkmcnt(0)
	s_barrier
	v_mfma_f32_16x16x32_bf16 v[128:131], v[142:145], v[178:181], v[128:131]
	v_mfma_f32_16x16x32_bf16 v[128:131], v[150:153], v[182:185], v[128:131]
	v_mfma_f32_16x16x32_bf16 v[124:127], v[154:157], v[178:181], v[124:127]
	v_mfma_f32_16x16x32_bf16 v[124:127], v[158:161], v[182:185], v[124:127]
	v_mfma_f32_16x16x32_bf16 v[108:111], v[154:157], v[186:189], v[108:111]
	v_mfma_f32_16x16x32_bf16 v[108:111], v[158:161], v[190:193], v[108:111]
	v_mfma_f32_16x16x32_bf16 v[112:115], v[142:145], v[186:189], v[112:115]
	v_mfma_f32_16x16x32_bf16 v[112:115], v[150:153], v[190:193], v[112:115]
	v_mfma_f32_16x16x32_bf16 v[96:99], v[142:145], v[194:197], v[96:99]
	v_mfma_f32_16x16x32_bf16 v[96:99], v[150:153], v[198:201], v[96:99]
	v_mfma_f32_16x16x32_bf16 v[92:95], v[154:157], v[194:197], v[92:95]
	v_mfma_f32_16x16x32_bf16 v[92:95], v[158:161], v[198:201], v[92:95]
	v_mfma_f32_16x16x32_bf16 v[76:79], v[154:157], v[202:205], v[76:79]
	v_mfma_f32_16x16x32_bf16 v[76:79], v[158:161], v[206:209], v[76:79]
	v_mfma_f32_16x16x32_bf16 v[80:83], v[142:145], v[202:205], v[80:83]
	v_mfma_f32_16x16x32_bf16 v[80:83], v[150:153], v[206:209], v[80:83]
	s_setprio 0
	s_setprio 1
	v_mfma_f32_16x16x32_bf16 v[120:123], v[162:165], v[178:181], v[120:123]
	v_mfma_f32_16x16x32_bf16 v[120:123], v[166:169], v[182:185], v[120:123]
	v_mfma_f32_16x16x32_bf16 v[116:119], v[170:173], v[178:181], v[116:119]
	v_mfma_f32_16x16x32_bf16 v[116:119], v[174:177], v[182:185], v[116:119]
	v_mfma_f32_16x16x32_bf16 v[100:103], v[170:173], v[186:189], v[100:103]
	v_mfma_f32_16x16x32_bf16 v[100:103], v[174:177], v[190:193], v[100:103]
	v_mfma_f32_16x16x32_bf16 v[104:107], v[162:165], v[186:189], v[104:107]
	v_mfma_f32_16x16x32_bf16 v[104:107], v[166:169], v[190:193], v[104:107]
	v_mfma_f32_16x16x32_bf16 v[88:91], v[162:165], v[194:197], v[88:91]
	v_mfma_f32_16x16x32_bf16 v[88:91], v[166:169], v[198:201], v[88:91]
	v_mfma_f32_16x16x32_bf16 v[84:87], v[170:173], v[194:197], v[84:87]
	v_mfma_f32_16x16x32_bf16 v[84:87], v[174:177], v[198:201], v[84:87]
	v_mfma_f32_16x16x32_bf16 v[68:71], v[170:173], v[202:205], v[68:71]
	v_mfma_f32_16x16x32_bf16 v[68:71], v[174:177], v[206:209], v[68:71]
	v_mfma_f32_16x16x32_bf16 v[72:75], v[162:165], v[202:205], v[72:75]
	v_mfma_f32_16x16x32_bf16 v[72:75], v[166:169], v[206:209], v[72:75]
	s_barrier
	ds_read_b128 v[178:181], v149 offset:16384
	ds_read_b128 v[182:185], v149 offset:17408
	ds_read_b128 v[186:189], v149 offset:18432
	ds_read_b128 v[190:193], v149 offset:19456
	ds_read_b128 v[194:197], v149 offset:20480
	ds_read_b128 v[198:201], v149 offset:21504
	ds_read_b128 v[202:205], v149 offset:22528
	ds_read_b128 v[206:209], v149 offset:23552
	s_setprio 0
	s_add_i32 s63, s63, s9
	s_mov_b32 m0, s63
	s_nop 0
	global_load_lds_dwordx4 v2, s[0:1]
	s_add_i32 m0, s63, 0x2000
	s_add_u32 s64, s0, 0x100000
	s_addc_u32 s65, s1, 0
	s_add_i32 s63, s66, s9
	global_load_lds_dwordx4 v136, s[0:1]
	s_mov_b32 m0, s63
	s_nop 0
	global_load_lds_dwordx4 v2, s[64:65]
	s_add_i32 m0, s63, 0x2000
	s_nop 0
	global_load_lds_dwordx4 v136, s[64:65]
	s_setprio 1
	s_waitcnt vmcnt(6)
	s_waitcnt lgkmcnt(0)
	s_barrier
	v_mfma_f32_16x16x32_bf16 v[64:67], v[142:145], v[178:181], v[64:67]
	v_mfma_f32_16x16x32_bf16 v[64:67], v[150:153], v[182:185], v[64:67]
	v_mfma_f32_16x16x32_bf16 v[60:63], v[154:157], v[178:181], v[60:63]
	v_mfma_f32_16x16x32_bf16 v[60:63], v[158:161], v[182:185], v[60:63]
	v_mfma_f32_16x16x32_bf16 v[44:47], v[154:157], v[186:189], v[44:47]
	v_mfma_f32_16x16x32_bf16 v[44:47], v[158:161], v[190:193], v[44:47]
	v_mfma_f32_16x16x32_bf16 v[48:51], v[142:145], v[186:189], v[48:51]
	v_mfma_f32_16x16x32_bf16 v[48:51], v[150:153], v[190:193], v[48:51]
	v_mfma_f32_16x16x32_bf16 v[32:35], v[142:145], v[194:197], v[32:35]
	v_mfma_f32_16x16x32_bf16 v[32:35], v[150:153], v[198:201], v[32:35]
	v_mfma_f32_16x16x32_bf16 v[28:31], v[154:157], v[194:197], v[28:31]
	v_mfma_f32_16x16x32_bf16 v[28:31], v[158:161], v[198:201], v[28:31]
	v_mfma_f32_16x16x32_bf16 v[12:15], v[154:157], v[202:205], v[12:15]
	v_mfma_f32_16x16x32_bf16 v[12:15], v[158:161], v[206:209], v[12:15]
	v_mfma_f32_16x16x32_bf16 v[16:19], v[142:145], v[202:205], v[16:19]
	v_mfma_f32_16x16x32_bf16 v[16:19], v[150:153], v[206:209], v[16:19]
	s_setprio 0
	s_setprio 1
	v_mfma_f32_16x16x32_bf16 v[56:59], v[162:165], v[178:181], v[56:59]
	v_mfma_f32_16x16x32_bf16 v[56:59], v[166:169], v[182:185], v[56:59]
	v_mfma_f32_16x16x32_bf16 v[52:55], v[170:173], v[178:181], v[52:55]
	v_mfma_f32_16x16x32_bf16 v[52:55], v[174:177], v[182:185], v[52:55]
	v_mfma_f32_16x16x32_bf16 v[36:39], v[170:173], v[186:189], v[36:39]
	v_mfma_f32_16x16x32_bf16 v[36:39], v[174:177], v[190:193], v[36:39]
	v_mfma_f32_16x16x32_bf16 v[40:43], v[162:165], v[186:189], v[40:43]
	v_mfma_f32_16x16x32_bf16 v[40:43], v[166:169], v[190:193], v[40:43]
	v_mfma_f32_16x16x32_bf16 v[24:27], v[162:165], v[194:197], v[24:27]
	v_mfma_f32_16x16x32_bf16 v[24:27], v[166:169], v[198:201], v[24:27]
	v_mfma_f32_16x16x32_bf16 v[20:23], v[170:173], v[194:197], v[20:23]
	v_mfma_f32_16x16x32_bf16 v[20:23], v[174:177], v[198:201], v[20:23]
	v_mfma_f32_16x16x32_bf16 v[4:7], v[170:173], v[202:205], v[4:7]
	v_mfma_f32_16x16x32_bf16 v[4:7], v[174:177], v[206:209], v[4:7]
	v_mfma_f32_16x16x32_bf16 v[8:11], v[162:165], v[202:205], v[8:11]
	v_mfma_f32_16x16x32_bf16 v[8:11], v[166:169], v[206:209], v[8:11]
	s_barrier
; #define PG8_STAGE(bufoff, gbase, voff) do { _Pragma("unroll") for (int _i = 0; _i < 2; ++_i) \
;         __builtin_amdgcn_global_load_lds((const unsigned*)((const char*)(gbase) + (voff)[_i]), (PG8_LAS unsigned*)(lds + (bufoff) + ldsw + _i * 8192), 16, 0, 0); } while (0)
; #define PG8_LDA(dst, b, h) do { _Pragma("unroll") for (int m = 0; m < 4; ++m) _Pragma("unroll") for (int k = 0; k < 2; ++k) dst[m][k] = *(const PG8_LAS bf16x8*)(lds + PG8_SA(b, h) + aoff + m * 2048 + k * 1024); } while (0)
; #define PG8_LDB(dst, b, h) do { _Pragma("unroll") for (int n = 0; n < 2; ++n) _Pragma("unroll") for (int k = 0; k < 2; ++k) dst[n][k] = *(const PG8_LAS bf16x8*)(lds + PG8_SB(b, h) + boff + n * 2048 + k * 1024); } while (0)
; #define PG8_MMA(ai, bj, At, Bt) do { __builtin_amdgcn_s_setprio(1); _Pragma("unroll") for (int m = 0; m < 4; ++m) _Pragma("unroll") for (int n = 0; n < 2; ++n) _Pragma("unroll") for (int k = 0; k < 2; ++k) \
;         acc[ai][bj][m][n] = __builtin_amdgcn_mfma_f32_16x16x32_bf16(Bt[n][k], At[m][k], acc[ai][bj][m][n], 0, 0, 0); __builtin_amdgcn_s_setprio(0); } while (0)
; #define PG8_WAIT_V(n) asm volatile("s_waitcnt vmcnt(" #n ")" ::: "memory")
; #define PG8_WAIT_L(n) asm volatile("s_waitcnt lgkmcnt(" #n ")" ::: "memory")
; #define PG8_BAR __builtin_amdgcn_s_barrier()
; #define PG8_SCHED __builtin_amdgcn_sched_barrier(0)
; template <class Epi, class Sched, bool ALIGN_EPI = false, bool SP2 = false>
; __device__ __forceinline__ void gemm_phase(PG8_LAS unsigned char* lds, const Gemm g, const Sched& S, const Epi& E) {
;     ...
;             PG8_LDB(B0, 1, 0); PG8_LDB(B1, 1, 1); PG8_SCHED; PG8_LDA(At, 1, 0); PG8_STAGE(PG8_SA(0, 1), a2 + hstep, voffA);
;             PG8_WAIT_V(8); PG8_WAIT_L(0); PG8_BAR; PG8_MMA(0, 0, At, B0); PG8_MMA(0, 1, At, B1); PG8_BAR; PG8_SCHED;
;             PG8_LDA(At, 1, 1); PG8_STAGE(PG8_SB(1, 0), b3, voffB); PG8_STAGE(PG8_SB(1, 1), b3 + hstep, voffB); PG8_STAGE(PG8_SA(1, 0), a3, voffA);
;             PG8_WAIT_V(8); PG8_WAIT_L(0); PG8_BAR; PG8_MMA(1, 0, At, B0); PG8_MMA(1, 1, At, B1); PG8_BAR; PG8_SCHED;
	ds_read_b128 v[142:145], v210 offset:32768
	ds_read_b128 v[150:153], v210 offset:33792
	ds_read_b128 v[154:157], v210 offset:34816
	ds_read_b128 v[158:161], v210 offset:35840
	ds_read_b128 v[162:165], v210 offset:49152
	ds_read_b128 v[166:169], v210 offset:50176
	ds_read_b128 v[170:173], v210 offset:51200
	ds_read_b128 v[174:177], v210 offset:52224
	ds_read_b128 v[178:181], v149 offset:32768
	ds_read_b128 v[182:185], v149 offset:33792
	ds_read_b128 v[186:189], v149 offset:34816
	ds_read_b128 v[190:193], v149 offset:35840
	ds_read_b128 v[194:197], v149 offset:36864
	ds_read_b128 v[198:201], v149 offset:37888
	ds_read_b128 v[202:205], v149 offset:38912
	ds_read_b128 v[206:209], v149 offset:39936
	s_setprio 0
	s_add_i32 s63, 0, 0x18000
	s_add_i32 s64, 0, 0x1c000
	s_mov_b32 m0, s10
	s_nop 0
	global_load_lds_dwordx4 v132, s[26:27]
	s_mov_b32 m0, s11
	s_nop 0
	global_load_lds_dwordx4 v134, s[26:27]
	s_add_u32 s26, s26, 0x100000
	s_addc_u32 s27, s27, 0
	s_mov_b32 m0, s25
	s_nop 0
	global_load_lds_dwordx4 v132, s[26:27]
	s_mov_b32 m0, s55
	s_nop 0
	global_load_lds_dwordx4 v134, s[26:27]
	s_nop 0
	s_setprio 1
	s_waitcnt vmcnt(8)
	s_waitcnt lgkmcnt(0)
	s_barrier
	v_mfma_f32_16x16x32_bf16 v[128:131], v[142:145], v[178:181], v[128:131]
	v_mfma_f32_16x16x32_bf16 v[128:131], v[150:153], v[182:185], v[128:131]
	v_mfma_f32_16x16x32_bf16 v[124:127], v[154:157], v[178:181], v[124:127]
	v_mfma_f32_16x16x32_bf16 v[124:127], v[158:161], v[182:185], v[124:127]
	v_mfma_f32_16x16x32_bf16 v[108:111], v[154:157], v[186:189], v[108:111]
	v_mfma_f32_16x16x32_bf16 v[108:111], v[158:161], v[190:193], v[108:111]
	v_mfma_f32_16x16x32_bf16 v[112:115], v[142:145], v[186:189], v[112:115]
	v_mfma_f32_16x16x32_bf16 v[112:115], v[150:153], v[190:193], v[112:115]
	v_mfma_f32_16x16x32_bf16 v[96:99], v[142:145], v[194:197], v[96:99]
	v_mfma_f32_16x16x32_bf16 v[96:99], v[150:153], v[198:201], v[96:99]
	v_mfma_f32_16x16x32_bf16 v[92:95], v[154:157], v[194:197], v[92:95]
	v_mfma_f32_16x16x32_bf16 v[92:95], v[158:161], v[198:201], v[92:95]
	v_mfma_f32_16x16x32_bf16 v[76:79], v[154:157], v[202:205], v[76:79]
	v_mfma_f32_16x16x32_bf16 v[76:79], v[158:161], v[206:209], v[76:79]
	v_mfma_f32_16x16x32_bf16 v[80:83], v[142:145], v[202:205], v[80:83]
	v_mfma_f32_16x16x32_bf16 v[80:83], v[150:153], v[206:209], v[80:83]
	s_setprio 0
	s_setprio 1
	v_mfma_f32_16x16x32_bf16 v[120:123], v[162:165], v[178:181], v[120:123]
	v_mfma_f32_16x16x32_bf16 v[120:123], v[166:169], v[182:185], v[120:123]
	v_mfma_f32_16x16x32_bf16 v[116:119], v[170:173], v[178:181], v[116:119]
	v_mfma_f32_16x16x32_bf16 v[116:119], v[174:177], v[182:185], v[116:119]
	v_mfma_f32_16x16x32_bf16 v[100:103], v[170:173], v[186:189], v[100:103]
	v_mfma_f32_16x16x32_bf16 v[100:103], v[174:177], v[190:193], v[100:103]
	v_mfma_f32_16x16x32_bf16 v[104:107], v[162:165], v[186:189], v[104:107]
	v_mfma_f32_16x16x32_bf16 v[104:107], v[166:169], v[190:193], v[104:107]
	v_mfma_f32_16x16x32_bf16 v[88:91], v[162:165], v[194:197], v[88:91]
	v_mfma_f32_16x16x32_bf16 v[88:91], v[166:169], v[198:201], v[88:91]
	v_mfma_f32_16x16x32_bf16 v[84:87], v[170:173], v[194:197], v[84:87]
	v_mfma_f32_16x16x32_bf16 v[84:87], v[174:177], v[198:201], v[84:87]
	v_mfma_f32_16x16x32_bf16 v[68:71], v[170:173], v[202:205], v[68:71]
	v_mfma_f32_16x16x32_bf16 v[68:71], v[174:177], v[206:209], v[68:71]
	v_mfma_f32_16x16x32_bf16 v[72:75], v[162:165], v[202:205], v[72:75]
	v_mfma_f32_16x16x32_bf16 v[72:75], v[166:169], v[206:209], v[72:75]
	s_barrier
	ds_read_b128 v[178:181], v149 offset:49152
	ds_read_b128 v[182:185], v149 offset:50176
	ds_read_b128 v[186:189], v149 offset:51200
	ds_read_b128 v[190:193], v149 offset:52224
	ds_read_b128 v[194:197], v149 offset:53248
	ds_read_b128 v[198:201], v149 offset:54272
	ds_read_b128 v[202:205], v149 offset:55296
	ds_read_b128 v[206:209], v149 offset:56320
	s_setprio 0
	s_add_i32 s26, s63, s9
	s_mov_b32 m0, s26
	s_add_u32 s0, s0, 0x80
	s_addc_u32 s1, s1, 0
	global_load_lds_dwordx4 v2, s[0:1]
	s_add_i32 m0, s26, 0x2000
	s_add_i32 s26, s64, s9
	global_load_lds_dwordx4 v136, s[0:1]
	s_add_u32 s0, s0, 0x100000
	s_addc_u32 s1, s1, 0
	s_mov_b32 m0, s26
	s_nop 0
	global_load_lds_dwordx4 v2, s[0:1]
	s_add_i32 m0, s26, 0x2000
	s_nop 0
	global_load_lds_dwordx4 v136, s[0:1]
	s_setprio 1
	s_waitcnt vmcnt(6)
	s_waitcnt lgkmcnt(0)
	s_barrier
	v_mfma_f32_16x16x32_bf16 v[64:67], v[142:145], v[178:181], v[64:67]
	v_mfma_f32_16x16x32_bf16 v[64:67], v[150:153], v[182:185], v[64:67]
	v_mfma_f32_16x16x32_bf16 v[60:63], v[154:157], v[178:181], v[60:63]
	v_mfma_f32_16x16x32_bf16 v[60:63], v[158:161], v[182:185], v[60:63]
	v_mfma_f32_16x16x32_bf16 v[44:47], v[154:157], v[186:189], v[44:47]
	v_mfma_f32_16x16x32_bf16 v[44:47], v[158:161], v[190:193], v[44:47]
	v_mfma_f32_16x16x32_bf16 v[48:51], v[142:145], v[186:189], v[48:51]
	v_mfma_f32_16x16x32_bf16 v[48:51], v[150:153], v[190:193], v[48:51]
	v_mfma_f32_16x16x32_bf16 v[32:35], v[142:145], v[194:197], v[32:35]
	v_mfma_f32_16x16x32_bf16 v[32:35], v[150:153], v[198:201], v[32:35]
	v_mfma_f32_16x16x32_bf16 v[28:31], v[154:157], v[194:197], v[28:31]
	v_mfma_f32_16x16x32_bf16 v[28:31], v[158:161], v[198:201], v[28:31]
	v_mfma_f32_16x16x32_bf16 v[12:15], v[154:157], v[202:205], v[12:15]
	v_mfma_f32_16x16x32_bf16 v[12:15], v[158:161], v[206:209], v[12:15]
	v_mfma_f32_16x16x32_bf16 v[16:19], v[142:145], v[202:205], v[16:19]
	v_mfma_f32_16x16x32_bf16 v[16:19], v[150:153], v[206:209], v[16:19]
	s_setprio 0
	s_setprio 1
	s_add_i32 s62, s62, 2
	s_add_u32 s56, s56, 0x100
	s_addc_u32 s57, s57, 0
	s_add_u32 s47, s47, 0x100
	s_addc_u32 s49, s49, 0
	s_nop 0
	v_mfma_f32_16x16x32_bf16 v[56:59], v[162:165], v[178:181], v[56:59]
	v_mfma_f32_16x16x32_bf16 v[56:59], v[166:169], v[182:185], v[56:59]
	v_mfma_f32_16x16x32_bf16 v[52:55], v[170:173], v[178:181], v[52:55]
	v_mfma_f32_16x16x32_bf16 v[52:55], v[174:177], v[182:185], v[52:55]
	v_mfma_f32_16x16x32_bf16 v[36:39], v[170:173], v[186:189], v[36:39]
	v_mfma_f32_16x16x32_bf16 v[36:39], v[174:177], v[190:193], v[36:39]
	v_mfma_f32_16x16x32_bf16 v[40:43], v[162:165], v[186:189], v[40:43]
	v_mfma_f32_16x16x32_bf16 v[40:43], v[166:169], v[190:193], v[40:43]
	v_mfma_f32_16x16x32_bf16 v[24:27], v[162:165], v[194:197], v[24:27]
	v_mfma_f32_16x16x32_bf16 v[24:27], v[166:169], v[198:201], v[24:27]
	v_mfma_f32_16x16x32_bf16 v[20:23], v[170:173], v[194:197], v[20:23]
	v_mfma_f32_16x16x32_bf16 v[20:23], v[174:177], v[198:201], v[20:23]
	v_mfma_f32_16x16x32_bf16 v[4:7], v[170:173], v[202:205], v[4:7]
	v_mfma_f32_16x16x32_bf16 v[4:7], v[174:177], v[206:209], v[4:7]
	v_mfma_f32_16x16x32_bf16 v[8:11], v[162:165], v[202:205], v[8:11]
	v_mfma_f32_16x16x32_bf16 v[8:11], v[166:169], v[206:209], v[8:11]
	s_barrier
	s_cmp_gt_u32 s62, 61
	s_cbranch_scc0 .LBB0_1624
	s_setprio 0
	s_and_b64 vcc, exec, s[44:45]
	s_cbranch_vccz .LBB0_1627
	s_barrier

; #define PG8_STAGE(bufoff, gbase, voff) do { _Pragma("unroll") for (int _i = 0; _i < 2; ++_i) \
;         __builtin_amdgcn_global_load_lds((const unsigned*)((const char*)(gbase) + (voff)[_i]), (PG8_LAS unsigned*)(lds + (bufoff) + ldsw + _i * 8192), 16, 0, 0); } while (0)
; #define PG8_LDA(dst, b, h) do { _Pragma("unroll") for (int m = 0; m < 4; ++m) _Pragma("unroll") for (int k = 0; k < 2; ++k) dst[m][k] = *(const PG8_LAS bf16x8*)(lds + PG8_SA(b, h) + aoff + m * 2048 + k * 1024); } while (0)
; #define PG8_LDB(dst, b, h) do { _Pragma("unroll") for (int n = 0; n < 2; ++n) _Pragma("unroll") for (int k = 0; k < 2; ++k) dst[n][k] = *(const PG8_LAS bf16x8*)(lds + PG8_SB(b, h) + boff + n * 2048 + k * 1024); } while (0)
; #define PG8_MMA(ai, bj, At, Bt) do { __builtin_amdgcn_s_setprio(1); _Pragma("unroll") for (int m = 0; m < 4; ++m) _Pragma("unroll") for (int n = 0; n < 2; ++n) _Pragma("unroll") for (int k = 0; k < 2; ++k) \
;         acc[ai][bj][m][n] = __builtin_amdgcn_mfma_f32_16x16x32_bf16(Bt[n][k], At[m][k], acc[ai][bj][m][n], 0, 0, 0); __builtin_amdgcn_s_setprio(0); } while (0)
; #define PG8_WAIT_V(n) asm volatile("s_waitcnt vmcnt(" #n ")" ::: "memory")
; #define PG8_WAIT_L(n) asm volatile("s_waitcnt lgkmcnt(" #n ")" ::: "memory")
; #define PG8_BAR __builtin_amdgcn_s_barrier()
; #define PG8_SCHED __builtin_amdgcn_sched_barrier(0)
; template <class Epi, class Sched, bool ALIGN_EPI = false, bool SP2 = false>
; __device__ __forceinline__ void gemm_phase(PG8_LAS unsigned char* lds, const Gemm g, const Sched& S, const Epi& E) {
;     ...
;             if constexpr (SP2) {
;             PG8_LDB(B0, 0, 0); PG8_LDB(B1, 0, 1); PG8_SCHED; PG8_LDA(At, 0, 0); PG8_STAGE(PG8_SA(1, 1), a1 + hstep, voffA);
;             PG8_WAIT_V(8); PG8_WAIT_L(0); PG8_BAR; PG8_MMA(0, 0, At, B0); PG8_MMA(0, 1, At, B1); PG8_BAR; PG8_SCHED;
;             PG8_LDA(At, 0, 1); PG8_STAGE(PG8_SB(0, 0), b2, voffB); PG8_STAGE(PG8_SB(0, 1), b2 + hstep, voffB); PG8_STAGE(PG8_SA(0, 0), a2, voffA);
;             PG8_WAIT_V(8); PG8_WAIT_L(0); PG8_BAR; PG8_MMA(1, 0, At, B0); PG8_MMA(1, 1, At, B1); PG8_BAR; PG8_SCHED;
.LBB0_2089:
	ds_read_b128 v[142:145], v210
	ds_read_b128 v[146:149], v210 offset:1024
	ds_read_b128 v[154:157], v210 offset:2048
	ds_read_b128 v[158:161], v210 offset:3072
	ds_read_b128 v[162:165], v210 offset:16384
	ds_read_b128 v[166:169], v210 offset:17408
	ds_read_b128 v[170:173], v210 offset:18432
	ds_read_b128 v[174:177], v210 offset:19456
	ds_read_b128 v[178:181], v153
	ds_read_b128 v[182:185], v153 offset:1024
	ds_read_b128 v[186:189], v153 offset:2048
	ds_read_b128 v[190:193], v153 offset:3072
	ds_read_b128 v[194:197], v153 offset:4096
	ds_read_b128 v[198:201], v153 offset:5120
	ds_read_b128 v[202:205], v153 offset:6144
	ds_read_b128 v[206:209], v153 offset:7168
	s_setprio 0
	s_add_u32 s0, s50, 0xfff00080
	s_addc_u32 s1, s51, -1
	s_add_i32 s61, 0, 0x10000
	s_cmp_eq_u32 s60, 60
	s_cselect_b32 s27, s47, s1
	s_cselect_b32 s26, s46, s0
	s_cselect_b32 s1, s49, s45
	s_cselect_b32 s0, s48, s43
	s_add_i32 s64, 0, 0x14000
	s_add_u32 s100, s50, 0xfff00000
	s_addc_u32 s101, s51, -1
	s_mov_b32 m0, s54
	s_nop 0
	global_load_lds_dwordx4 v136, s[100:101]
	s_mov_b32 m0, s55
	s_nop 0
	global_load_lds_dwordx4 v134, s[100:101]
	s_add_i32 m0, s10, 0xc000
	s_nop 0
	global_load_lds_dwordx4 v138, s[50:51]
	s_add_i32 m0, s10, 0xe000
	s_nop 0
	global_load_lds_dwordx4 v140, s[50:51]
	s_setprio 1
	s_waitcnt vmcnt(8)
	s_waitcnt lgkmcnt(0)
	s_barrier
	v_mfma_f32_16x16x32_bf16 v[128:131], v[142:145], v[178:181], v[128:131]
	v_mfma_f32_16x16x32_bf16 v[128:131], v[146:149], v[182:185], v[128:131]
	v_mfma_f32_16x16x32_bf16 v[124:127], v[154:157], v[178:181], v[124:127]
	v_mfma_f32_16x16x32_bf16 v[124:127], v[158:161], v[182:185], v[124:127]
	v_mfma_f32_16x16x32_bf16 v[108:111], v[154:157], v[186:189], v[108:111]
	v_mfma_f32_16x16x32_bf16 v[108:111], v[158:161], v[190:193], v[108:111]
	v_mfma_f32_16x16x32_bf16 v[112:115], v[142:145], v[186:189], v[112:115]
	v_mfma_f32_16x16x32_bf16 v[112:115], v[146:149], v[190:193], v[112:115]
	v_mfma_f32_16x16x32_bf16 v[96:99], v[142:145], v[194:197], v[96:99]
	v_mfma_f32_16x16x32_bf16 v[96:99], v[146:149], v[198:201], v[96:99]
	v_mfma_f32_16x16x32_bf16 v[92:95], v[154:157], v[194:197], v[92:95]
	v_mfma_f32_16x16x32_bf16 v[92:95], v[158:161], v[198:201], v[92:95]
	v_mfma_f32_16x16x32_bf16 v[76:79], v[154:157], v[202:205], v[76:79]
	v_mfma_f32_16x16x32_bf16 v[76:79], v[158:161], v[206:209], v[76:79]
	v_mfma_f32_16x16x32_bf16 v[80:83], v[142:145], v[202:205], v[80:83]
	v_mfma_f32_16x16x32_bf16 v[80:83], v[146:149], v[206:209], v[80:83]
	s_setprio 0
	s_setprio 1
	v_mfma_f32_16x16x32_bf16 v[120:123], v[162:165], v[178:181], v[120:123]
	v_mfma_f32_16x16x32_bf16 v[120:123], v[166:169], v[182:185], v[120:123]
	v_mfma_f32_16x16x32_bf16 v[116:119], v[170:173], v[178:181], v[116:119]
	v_mfma_f32_16x16x32_bf16 v[116:119], v[174:177], v[182:185], v[116:119]
	v_mfma_f32_16x16x32_bf16 v[100:103], v[170:173], v[186:189], v[100:103]
	v_mfma_f32_16x16x32_bf16 v[100:103], v[174:177], v[190:193], v[100:103]
	v_mfma_f32_16x16x32_bf16 v[104:107], v[162:165], v[186:189], v[104:107]
	v_mfma_f32_16x16x32_bf16 v[104:107], v[166:169], v[190:193], v[104:107]
	v_mfma_f32_16x16x32_bf16 v[88:91], v[162:165], v[194:197], v[88:91]
	v_mfma_f32_16x16x32_bf16 v[88:91], v[166:169], v[198:201], v[88:91]
	v_mfma_f32_16x16x32_bf16 v[84:87], v[170:173], v[194:197], v[84:87]
	v_mfma_f32_16x16x32_bf16 v[84:87], v[174:177], v[198:201], v[84:87]
	v_mfma_f32_16x16x32_bf16 v[68:71], v[170:173], v[202:205], v[68:71]
	v_mfma_f32_16x16x32_bf16 v[68:71], v[174:177], v[206:209], v[68:71]
	v_mfma_f32_16x16x32_bf16 v[72:75], v[162:165], v[202:205], v[72:75]
	v_mfma_f32_16x16x32_bf16 v[72:75], v[166:169], v[206:209], v[72:75]
	s_barrier
	ds_read_b128 v[178:181], v153 offset:16384
	ds_read_b128 v[182:185], v153 offset:17408
	ds_read_b128 v[186:189], v153 offset:18432
	ds_read_b128 v[190:193], v153 offset:19456
	ds_read_b128 v[194:197], v153 offset:20480
	ds_read_b128 v[198:201], v153 offset:21504
	ds_read_b128 v[202:205], v153 offset:22528
	ds_read_b128 v[206:209], v153 offset:23552
	s_setprio 0
	s_add_i32 s61, s61, s9
	s_mov_b32 m0, s61
	s_nop 0
	global_load_lds_dwordx4 v2, s[0:1]
	s_add_i32 m0, s61, 0x2000
	s_add_u32 s62, s0, 0x100000
	s_addc_u32 s63, s1, 0
	s_add_i32 s61, s64, s9
	global_load_lds_dwordx4 v132, s[0:1]
	s_mov_b32 m0, s61
	s_nop 0
	global_load_lds_dwordx4 v2, s[62:63]
	s_add_i32 m0, s61, 0x2000
	s_nop 0
	global_load_lds_dwordx4 v132, s[62:63]
	s_setprio 1
	s_waitcnt vmcnt(6)
	s_waitcnt lgkmcnt(0)
	s_barrier
	v_mfma_f32_16x16x32_bf16 v[64:67], v[142:145], v[178:181], v[64:67]
	v_mfma_f32_16x16x32_bf16 v[64:67], v[146:149], v[182:185], v[64:67]
	v_mfma_f32_16x16x32_bf16 v[60:63], v[154:157], v[178:181], v[60:63]
	v_mfma_f32_16x16x32_bf16 v[60:63], v[158:161], v[182:185], v[60:63]
	v_mfma_f32_16x16x32_bf16 v[44:47], v[154:157], v[186:189], v[44:47]
	v_mfma_f32_16x16x32_bf16 v[44:47], v[158:161], v[190:193], v[44:47]
	v_mfma_f32_16x16x32_bf16 v[48:51], v[142:145], v[186:189], v[48:51]
	v_mfma_f32_16x16x32_bf16 v[48:51], v[146:149], v[190:193], v[48:51]
	v_mfma_f32_16x16x32_bf16 v[32:35], v[142:145], v[194:197], v[32:35]
	v_mfma_f32_16x16x32_bf16 v[32:35], v[146:149], v[198:201], v[32:35]
	v_mfma_f32_16x16x32_bf16 v[28:31], v[154:157], v[194:197], v[28:31]
	v_mfma_f32_16x16x32_bf16 v[28:31], v[158:161], v[198:201], v[28:31]
	v_mfma_f32_16x16x32_bf16 v[12:15], v[154:157], v[202:205], v[12:15]
	v_mfma_f32_16x16x32_bf16 v[12:15], v[158:161], v[206:209], v[12:15]
	v_mfma_f32_16x16x32_bf16 v[16:19], v[142:145], v[202:205], v[16:19]
	v_mfma_f32_16x16x32_bf16 v[16:19], v[146:149], v[206:209], v[16:19]
	s_setprio 0
	s_setprio 1
	v_mfma_f32_16x16x32_bf16 v[56:59], v[162:165], v[178:181], v[56:59]
	v_mfma_f32_16x16x32_bf16 v[56:59], v[166:169], v[182:185], v[56:59]
	v_mfma_f32_16x16x32_bf16 v[52:55], v[170:173], v[178:181], v[52:55]
	v_mfma_f32_16x16x32_bf16 v[52:55], v[174:177], v[182:185], v[52:55]
	v_mfma_f32_16x16x32_bf16 v[36:39], v[170:173], v[186:189], v[36:39]
	v_mfma_f32_16x16x32_bf16 v[36:39], v[174:177], v[190:193], v[36:39]
	v_mfma_f32_16x16x32_bf16 v[40:43], v[162:165], v[186:189], v[40:43]
	v_mfma_f32_16x16x32_bf16 v[40:43], v[166:169], v[190:193], v[40:43]
	v_mfma_f32_16x16x32_bf16 v[24:27], v[162:165], v[194:197], v[24:27]
	v_mfma_f32_16x16x32_bf16 v[24:27], v[166:169], v[198:201], v[24:27]
	v_mfma_f32_16x16x32_bf16 v[20:23], v[170:173], v[194:197], v[20:23]
	v_mfma_f32_16x16x32_bf16 v[20:23], v[174:177], v[198:201], v[20:23]
	v_mfma_f32_16x16x32_bf16 v[4:7], v[170:173], v[202:205], v[4:7]
	v_mfma_f32_16x16x32_bf16 v[4:7], v[174:177], v[206:209], v[4:7]
	v_mfma_f32_16x16x32_bf16 v[8:11], v[162:165], v[202:205], v[8:11]
	v_mfma_f32_16x16x32_bf16 v[8:11], v[166:169], v[206:209], v[8:11]
	s_barrier
; #define PG8_STAGE(bufoff, gbase, voff) do { _Pragma("unroll") for (int _i = 0; _i < 2; ++_i) \
;         __builtin_amdgcn_global_load_lds((const unsigned*)((const char*)(gbase) + (voff)[_i]), (PG8_LAS unsigned*)(lds + (bufoff) + ldsw + _i * 8192), 16, 0, 0); } while (0)
; #define PG8_LDA(dst, b, h) do { _Pragma("unroll") for (int m = 0; m < 4; ++m) _Pragma("unroll") for (int k = 0; k < 2; ++k) dst[m][k] = *(const PG8_LAS bf16x8*)(lds + PG8_SA(b, h) + aoff + m * 2048 + k * 1024); } while (0)
; #define PG8_LDB(dst, b, h) do { _Pragma("unroll") for (int n = 0; n < 2; ++n) _Pragma("unroll") for (int k = 0; k < 2; ++k) dst[n][k] = *(const PG8_LAS bf16x8*)(lds + PG8_SB(b, h) + boff + n * 2048 + k * 1024); } while (0)
; #define PG8_MMA(ai, bj, At, Bt) do { __builtin_amdgcn_s_setprio(1); _Pragma("unroll") for (int m = 0; m < 4; ++m) _Pragma("unroll") for (int n = 0; n < 2; ++n) _Pragma("unroll") for (int k = 0; k < 2; ++k) \
;         acc[ai][bj][m][n] = __builtin_amdgcn_mfma_f32_16x16x32_bf16(Bt[n][k], At[m][k], acc[ai][bj][m][n], 0, 0, 0); __builtin_amdgcn_s_setprio(0); } while (0)
; #define PG8_WAIT_V(n) asm volatile("s_waitcnt vmcnt(" #n ")" ::: "memory")
; #define PG8_WAIT_L(n) asm volatile("s_waitcnt lgkmcnt(" #n ")" ::: "memory")
; #define PG8_BAR __builtin_amdgcn_s_barrier()
; #define PG8_SCHED __builtin_amdgcn_sched_barrier(0)
; template <class Epi, class Sched, bool ALIGN_EPI = false, bool SP2 = false>
; __device__ __forceinline__ void gemm_phase(PG8_LAS unsigned char* lds, const Gemm g, const Sched& S, const Epi& E) {
;     ...
;             PG8_LDB(B0, 1, 0); PG8_LDB(B1, 1, 1); PG8_SCHED; PG8_LDA(At, 1, 0); PG8_STAGE(PG8_SA(0, 1), a2 + hstep, voffA);
;             PG8_WAIT_V(8); PG8_WAIT_L(0); PG8_BAR; PG8_MMA(0, 0, At, B0); PG8_MMA(0, 1, At, B1); PG8_BAR; PG8_SCHED;
;             PG8_LDA(At, 1, 1); PG8_STAGE(PG8_SB(1, 0), b3, voffB); PG8_STAGE(PG8_SB(1, 1), b3 + hstep, voffB); PG8_STAGE(PG8_SA(1, 0), a3, voffA);
;             PG8_WAIT_V(8); PG8_WAIT_L(0); PG8_BAR; PG8_MMA(1, 0, At, B0); PG8_MMA(1, 1, At, B1); PG8_BAR; PG8_SCHED;
	ds_read_b128 v[142:145], v210 offset:32768
	ds_read_b128 v[146:149], v210 offset:33792
	ds_read_b128 v[154:157], v210 offset:34816
	ds_read_b128 v[158:161], v210 offset:35840
	ds_read_b128 v[162:165], v210 offset:49152
	ds_read_b128 v[166:169], v210 offset:50176
	ds_read_b128 v[170:173], v210 offset:51200
	ds_read_b128 v[174:177], v210 offset:52224
	ds_read_b128 v[178:181], v153 offset:32768
	ds_read_b128 v[182:185], v153 offset:33792
	ds_read_b128 v[186:189], v153 offset:34816
	ds_read_b128 v[190:193], v153 offset:35840
	ds_read_b128 v[194:197], v153 offset:36864
	ds_read_b128 v[198:201], v153 offset:37888
	ds_read_b128 v[202:205], v153 offset:38912
	ds_read_b128 v[206:209], v153 offset:39936
	s_setprio 0
	s_add_i32 s61, 0, 0x18000
	s_add_i32 s62, 0, 0x1c000
	s_mov_b32 m0, s10
	s_nop 0
	global_load_lds_dwordx4 v136, s[26:27]
	s_mov_b32 m0, s11
	s_nop 0
	global_load_lds_dwordx4 v134, s[26:27]
	s_add_u32 s26, s26, 0x100000
	s_addc_u32 s27, s27, 0
	s_mov_b32 m0, s52
	s_nop 0
	global_load_lds_dwordx4 v136, s[26:27]
	s_mov_b32 m0, s53
	s_nop 0
	global_load_lds_dwordx4 v134, s[26:27]
	s_nop 0
	s_setprio 1
	s_waitcnt vmcnt(8)
	s_waitcnt lgkmcnt(0)
	s_barrier
	v_mfma_f32_16x16x32_bf16 v[128:131], v[142:145], v[178:181], v[128:131]
	v_mfma_f32_16x16x32_bf16 v[128:131], v[146:149], v[182:185], v[128:131]
	v_mfma_f32_16x16x32_bf16 v[124:127], v[154:157], v[178:181], v[124:127]
	v_mfma_f32_16x16x32_bf16 v[124:127], v[158:161], v[182:185], v[124:127]
	v_mfma_f32_16x16x32_bf16 v[108:111], v[154:157], v[186:189], v[108:111]
	v_mfma_f32_16x16x32_bf16 v[108:111], v[158:161], v[190:193], v[108:111]
	v_mfma_f32_16x16x32_bf16 v[112:115], v[142:145], v[186:189], v[112:115]
	v_mfma_f32_16x16x32_bf16 v[112:115], v[146:149], v[190:193], v[112:115]
	v_mfma_f32_16x16x32_bf16 v[96:99], v[142:145], v[194:197], v[96:99]
	v_mfma_f32_16x16x32_bf16 v[96:99], v[146:149], v[198:201], v[96:99]
	v_mfma_f32_16x16x32_bf16 v[92:95], v[154:157], v[194:197], v[92:95]
	v_mfma_f32_16x16x32_bf16 v[92:95], v[158:161], v[198:201], v[92:95]
	v_mfma_f32_16x16x32_bf16 v[76:79], v[154:157], v[202:205], v[76:79]
	v_mfma_f32_16x16x32_bf16 v[76:79], v[158:161], v[206:209], v[76:79]
	v_mfma_f32_16x16x32_bf16 v[80:83], v[142:145], v[202:205], v[80:83]
	v_mfma_f32_16x16x32_bf16 v[80:83], v[146:149], v[206:209], v[80:83]
	s_setprio 0
	s_setprio 1
	v_mfma_f32_16x16x32_bf16 v[120:123], v[162:165], v[178:181], v[120:123]
	v_mfma_f32_16x16x32_bf16 v[120:123], v[166:169], v[182:185], v[120:123]
	v_mfma_f32_16x16x32_bf16 v[116:119], v[170:173], v[178:181], v[116:119]
	v_mfma_f32_16x16x32_bf16 v[116:119], v[174:177], v[182:185], v[116:119]
	v_mfma_f32_16x16x32_bf16 v[100:103], v[170:173], v[186:189], v[100:103]
	v_mfma_f32_16x16x32_bf16 v[100:103], v[174:177], v[190:193], v[100:103]
	v_mfma_f32_16x16x32_bf16 v[104:107], v[162:165], v[186:189], v[104:107]
	v_mfma_f32_16x16x32_bf16 v[104:107], v[166:169], v[190:193], v[104:107]
	v_mfma_f32_16x16x32_bf16 v[88:91], v[162:165], v[194:197], v[88:91]
	v_mfma_f32_16x16x32_bf16 v[88:91], v[166:169], v[198:201], v[88:91]
	v_mfma_f32_16x16x32_bf16 v[84:87], v[170:173], v[194:197], v[84:87]
	v_mfma_f32_16x16x32_bf16 v[84:87], v[174:177], v[198:201], v[84:87]
	v_mfma_f32_16x16x32_bf16 v[68:71], v[170:173], v[202:205], v[68:71]
	v_mfma_f32_16x16x32_bf16 v[68:71], v[174:177], v[206:209], v[68:71]
	v_mfma_f32_16x16x32_bf16 v[72:75], v[162:165], v[202:205], v[72:75]
	v_mfma_f32_16x16x32_bf16 v[72:75], v[166:169], v[206:209], v[72:75]
	s_barrier
	ds_read_b128 v[178:181], v153 offset:49152
	ds_read_b128 v[182:185], v153 offset:50176
	ds_read_b128 v[186:189], v153 offset:51200
	ds_read_b128 v[190:193], v153 offset:52224
	ds_read_b128 v[194:197], v153 offset:53248
	ds_read_b128 v[198:201], v153 offset:54272
	ds_read_b128 v[202:205], v153 offset:55296
	ds_read_b128 v[206:209], v153 offset:56320
	s_setprio 0
	s_add_i32 s26, s61, s9
	s_mov_b32 m0, s26
	s_add_u32 s0, s0, 0x80
	s_addc_u32 s1, s1, 0
	global_load_lds_dwordx4 v2, s[0:1]
	s_add_i32 m0, s26, 0x2000
	s_add_i32 s26, s62, s9
	global_load_lds_dwordx4 v132, s[0:1]
	s_add_u32 s0, s0, 0x100000
	s_addc_u32 s1, s1, 0
	s_mov_b32 m0, s26
	s_nop 0
	global_load_lds_dwordx4 v2, s[0:1]
	s_add_i32 m0, s26, 0x2000
	s_nop 0
	global_load_lds_dwordx4 v132, s[0:1]
	s_setprio 1
	s_waitcnt vmcnt(6)
	s_waitcnt lgkmcnt(0)
	s_barrier
	v_mfma_f32_16x16x32_bf16 v[64:67], v[142:145], v[178:181], v[64:67]
	v_mfma_f32_16x16x32_bf16 v[64:67], v[146:149], v[182:185], v[64:67]
	v_mfma_f32_16x16x32_bf16 v[60:63], v[154:157], v[178:181], v[60:63]
	v_mfma_f32_16x16x32_bf16 v[60:63], v[158:161], v[182:185], v[60:63]
	v_mfma_f32_16x16x32_bf16 v[44:47], v[154:157], v[186:189], v[44:47]
	v_mfma_f32_16x16x32_bf16 v[44:47], v[158:161], v[190:193], v[44:47]
	v_mfma_f32_16x16x32_bf16 v[48:51], v[142:145], v[186:189], v[48:51]
	v_mfma_f32_16x16x32_bf16 v[48:51], v[146:149], v[190:193], v[48:51]
	v_mfma_f32_16x16x32_bf16 v[32:35], v[142:145], v[194:197], v[32:35]
	v_mfma_f32_16x16x32_bf16 v[32:35], v[146:149], v[198:201], v[32:35]
	v_mfma_f32_16x16x32_bf16 v[28:31], v[154:157], v[194:197], v[28:31]
	v_mfma_f32_16x16x32_bf16 v[28:31], v[158:161], v[198:201], v[28:31]
	v_mfma_f32_16x16x32_bf16 v[12:15], v[154:157], v[202:205], v[12:15]
	v_mfma_f32_16x16x32_bf16 v[12:15], v[158:161], v[206:209], v[12:15]
	v_mfma_f32_16x16x32_bf16 v[16:19], v[142:145], v[202:205], v[16:19]
	v_mfma_f32_16x16x32_bf16 v[16:19], v[146:149], v[206:209], v[16:19]
	s_setprio 0
	s_setprio 1
	s_add_i32 s60, s60, 2
	s_add_u32 s50, s50, 0x100
	s_addc_u32 s51, s51, 0
	s_add_u32 s43, s43, 0x100
	s_addc_u32 s45, s45, 0
	s_nop 0
	v_mfma_f32_16x16x32_bf16 v[56:59], v[162:165], v[178:181], v[56:59]
	v_mfma_f32_16x16x32_bf16 v[56:59], v[166:169], v[182:185], v[56:59]
	v_mfma_f32_16x16x32_bf16 v[52:55], v[170:173], v[178:181], v[52:55]
	v_mfma_f32_16x16x32_bf16 v[52:55], v[174:177], v[182:185], v[52:55]
	v_mfma_f32_16x16x32_bf16 v[36:39], v[170:173], v[186:189], v[36:39]
	v_mfma_f32_16x16x32_bf16 v[36:39], v[174:177], v[190:193], v[36:39]
	v_mfma_f32_16x16x32_bf16 v[40:43], v[162:165], v[186:189], v[40:43]
	v_mfma_f32_16x16x32_bf16 v[40:43], v[166:169], v[190:193], v[40:43]
	v_mfma_f32_16x16x32_bf16 v[24:27], v[162:165], v[194:197], v[24:27]
	v_mfma_f32_16x16x32_bf16 v[24:27], v[166:169], v[198:201], v[24:27]
	v_mfma_f32_16x16x32_bf16 v[20:23], v[170:173], v[194:197], v[20:23]
	v_mfma_f32_16x16x32_bf16 v[20:23], v[174:177], v[198:201], v[20:23]
	v_mfma_f32_16x16x32_bf16 v[4:7], v[170:173], v[202:205], v[4:7]
	v_mfma_f32_16x16x32_bf16 v[4:7], v[174:177], v[206:209], v[4:7]
	v_mfma_f32_16x16x32_bf16 v[8:11], v[162:165], v[202:205], v[8:11]
	v_mfma_f32_16x16x32_bf16 v[8:11], v[166:169], v[206:209], v[8:11]
	s_barrier
	s_cmp_gt_u32 s60, 61
	s_cbranch_scc0 .LBB0_2089
	s_setprio 0
	s_and_b64 vcc, exec, s[40:41]
	s_cbranch_vccz .LBB0_2092
	s_barrier

; #define PG8_STAGE(bufoff, gbase, voff) do { _Pragma("unroll") for (int _i = 0; _i < 2; ++_i) \
;         __builtin_amdgcn_global_load_lds((const unsigned*)((const char*)(gbase) + (voff)[_i]), (PG8_LAS unsigned*)(lds + (bufoff) + ldsw + _i * 8192), 16, 0, 0); } while (0)
; #define PG8_LDA(dst, b, h) do { _Pragma("unroll") for (int m = 0; m < 4; ++m) _Pragma("unroll") for (int k = 0; k < 2; ++k) dst[m][k] = *(const PG8_LAS bf16x8*)(lds + PG8_SA(b, h) + aoff + m * 2048 + k * 1024); } while (0)
; #define PG8_LDB(dst, b, h) do { _Pragma("unroll") for (int n = 0; n < 2; ++n) _Pragma("unroll") for (int k = 0; k < 2; ++k) dst[n][k] = *(const PG8_LAS bf16x8*)(lds + PG8_SB(b, h) + boff + n * 2048 + k * 1024); } while (0)
; #define PG8_WAIT_V(n) asm volatile("s_waitcnt vmcnt(" #n ")" ::: "memory")
; #define PG8_BAR __builtin_amdgcn_s_barrier()
; template <class Epi, class Sched, bool ALIGN_EPI = false, bool SP2 = false>
; __device__ __forceinline__ void gemm_phase(PG8_LAS unsigned char* lds, const Gemm g, const Sched& S, const Epi& E) {
;     ...
;         const bool has_next = S.next(ui + 1, nxt);
;         const char* nA = has_next ? (const char*)g.A + (size_t)nxt.pm * tstep + (size_t)nxt.kt0 * kstep : cA; const char* nB = has_next ? (const char*)g.Bt + (size_t)nxt.pn * tstep + (size_t)nxt.kt0 * kstep : cB;
;         const int nt = cur.nt;
;         for (int t = 0; t < nt; t += 2) {
;             const bool last = (t == nt - 2);
;             const char* a1 = cA + (size_t)(t + 1) * kstep;
;             const char* a2 = last ? nA : cA + (size_t)(t + 2) * kstep; const char* b2 = last ? nB : cB + (size_t)(t + 2) * kstep;
;             const char* a3 = a2 + kstep; const char* b3 = b2 + kstep;
;             if (last && has_next) S.a_ready(nxt);
;             if constexpr (SP2) {
;             PG8_LDB(B0, 0, 0); PG8_LDB(B1, 0, 1); PG8_SCHED; PG8_LDA(At, 0, 0); PG8_STAGE(PG8_SA(1, 1), a1 + hstep, voffA);
;             PG8_WAIT_V(8); PG8_WAIT_L(0); PG8_BAR; PG8_MMA(0, 0, At, B0); PG8_MMA(0, 1, At, B1); PG8_BAR; PG8_SCHED;
;     ...
; #pragma unroll
;         for (int a = 0; a < 2; ++a)
; #pragma unroll
;             for (int b = 0; b < 2; ++b)
; #pragma unroll
;                 for (int m = 0; m < 4; ++m)
; #pragma unroll
;                     for (int n = 0; n < 2; ++n) acc[a][b][m][n] = (f32x4){0.f, 0.f, 0.f, 0.f};
;         cur = nxt; cA = nA; cB = nB; ++ui;
.LBB0_2114:
	s_ashr_i32 s49, s48, 31
	s_lshl_b64 s[26:27], s[48:49], 21
	s_add_u32 s50, s6, s26
	s_addc_u32 s51, s7, s27
	s_and_b64 s[26:27], s[44:45], exec
	s_cselect_b32 s49, s51, s1
	s_cselect_b32 s57, s50, s0
	s_ashr_i32 s47, s46, 31
	s_lshl_b64 s[26:27], s[46:47], 21
	s_add_u32 s52, s8, s26
	s_addc_u32 s53, s9, s27
	s_and_b64 s[26:27], s[44:45], exec
	s_cselect_b32 s47, s53, s59
	s_cselect_b32 s73, s52, s58
	s_add_u32 s40, s0, 0x100080
	s_addc_u32 s41, s1, 0
	s_add_u32 s58, s58, 0x100
	v_mov_b64_e32 v[4:5], 0
	s_addc_u32 s59, s59, 0
	s_mov_b32 s76, -2
	v_mov_b64_e32 v[6:7], 0
	v_mov_b64_e32 v[8:9], 0
	v_mov_b64_e32 v[10:11], 0
	v_mov_b64_e32 v[20:21], 0
	v_mov_b64_e32 v[22:23], 0
	v_mov_b64_e32 v[24:25], 0
	v_mov_b64_e32 v[26:27], 0
	v_mov_b64_e32 v[36:37], 0
	v_mov_b64_e32 v[38:39], 0
	v_mov_b64_e32 v[40:41], 0
	v_mov_b64_e32 v[42:43], 0
	v_mov_b64_e32 v[52:53], 0
	v_mov_b64_e32 v[54:55], 0
	v_mov_b64_e32 v[56:57], 0
	v_mov_b64_e32 v[58:59], 0
	v_mov_b64_e32 v[12:13], 0
	v_mov_b64_e32 v[14:15], 0
	v_mov_b64_e32 v[16:17], 0
	v_mov_b64_e32 v[18:19], 0
	v_mov_b64_e32 v[28:29], 0
	v_mov_b64_e32 v[30:31], 0
	v_mov_b64_e32 v[32:33], 0
	v_mov_b64_e32 v[34:35], 0
	v_mov_b64_e32 v[44:45], 0
	v_mov_b64_e32 v[46:47], 0
	v_mov_b64_e32 v[48:49], 0
	v_mov_b64_e32 v[50:51], 0
	v_mov_b64_e32 v[60:61], 0
	v_mov_b64_e32 v[62:63], 0
	v_mov_b64_e32 v[64:65], 0
	v_mov_b64_e32 v[66:67], 0
	v_mov_b64_e32 v[68:69], 0
	v_mov_b64_e32 v[70:71], 0
	v_mov_b64_e32 v[72:73], 0
	v_mov_b64_e32 v[74:75], 0
	v_mov_b64_e32 v[84:85], 0
	v_mov_b64_e32 v[86:87], 0
	v_mov_b64_e32 v[88:89], 0
	v_mov_b64_e32 v[90:91], 0
	v_mov_b64_e32 v[100:101], 0
	v_mov_b64_e32 v[102:103], 0
	v_mov_b64_e32 v[104:105], 0
	v_mov_b64_e32 v[106:107], 0
	v_mov_b64_e32 v[116:117], 0
	v_mov_b64_e32 v[118:119], 0
	v_mov_b64_e32 v[120:121], 0
	v_mov_b64_e32 v[122:123], 0
	v_mov_b64_e32 v[76:77], 0
	v_mov_b64_e32 v[78:79], 0
	v_mov_b64_e32 v[80:81], 0
	v_mov_b64_e32 v[82:83], 0
	v_mov_b64_e32 v[92:93], 0
	v_mov_b64_e32 v[94:95], 0
	v_mov_b64_e32 v[96:97], 0
	v_mov_b64_e32 v[98:99], 0
	v_mov_b64_e32 v[108:109], 0
	v_mov_b64_e32 v[110:111], 0
	v_mov_b64_e32 v[112:113], 0
	v_mov_b64_e32 v[114:115], 0
	v_mov_b64_e32 v[124:125], 0
	v_mov_b64_e32 v[126:127], 0
	v_mov_b64_e32 v[128:129], 0
	v_mov_b64_e32 v[130:131], 0
	v_add_u32_e32 v188, 0x10000, v191
	s_waitcnt vmcnt(0)
.LBB0_2115:
	ds_read_b128 v[132:135], v188
	ds_read_b128 v[136:139], v188 offset:1024
	ds_read_b128 v[152:155], v188 offset:2048
	ds_read_b128 v[156:159], v188 offset:3072
	ds_read_b128 v[160:163], v188 offset:16384
	ds_read_b128 v[164:167], v188 offset:17408
	ds_read_b128 v[168:171], v188 offset:18432
	ds_read_b128 v[172:175], v188 offset:19456
	ds_read_b128 v[176:179], v194
	ds_read_b128 v[180:183], v194 offset:1024
	ds_read_b128 v[184:187], v194 offset:2048
	ds_read_b128 v[196:199], v194 offset:3072
	ds_read_b128 v[200:203], v194 offset:4096
	ds_read_b128 v[204:207], v194 offset:5120
	ds_read_b128 v[208:211], v194 offset:6144
	ds_read_b128 v[212:215], v194 offset:7168
	s_setprio 0
	s_add_u32 s0, s40, 0xfff00080
	s_addc_u32 s1, s41, -1
	s_add_i32 s77, 0, 0x10000
	s_cmp_eq_u32 s76, 60
	s_cselect_b32 s27, s49, s1
	s_cselect_b32 s26, s57, s0
	s_cselect_b32 s1, s47, s59
	s_cselect_b32 s0, s73, s58
	s_add_i32 s80, 0, 0x14000
	s_add_u32 s100, s40, 0xfff00000
	s_addc_u32 s101, s41, -1
	s_mov_b32 m0, s62
	s_nop 0
	global_load_lds_dwordx4 v140, s[100:101]
	s_mov_b32 m0, s63
	s_nop 0
	global_load_lds_dwordx4 v142, s[100:101]
	s_add_i32 m0, s11, 0xc000
	s_nop 0
	global_load_lds_dwordx4 v148, s[40:41]
	s_add_i32 m0, s11, 0xe000
	s_nop 0
	global_load_lds_dwordx4 v150, s[40:41]
	s_nop 0
	s_setprio 1
	s_waitcnt vmcnt(8)
	s_waitcnt lgkmcnt(0)
	s_barrier
	v_mfma_f32_16x16x32_bf16 v[128:131], v[132:135], v[176:179], v[128:131]
	v_mfma_f32_16x16x32_bf16 v[128:131], v[136:139], v[180:183], v[128:131]
	v_mfma_f32_16x16x32_bf16 v[124:127], v[152:155], v[176:179], v[124:127]
	v_mfma_f32_16x16x32_bf16 v[124:127], v[156:159], v[180:183], v[124:127]
	v_mfma_f32_16x16x32_bf16 v[108:111], v[152:155], v[184:187], v[108:111]
	v_mfma_f32_16x16x32_bf16 v[108:111], v[156:159], v[196:199], v[108:111]
	v_mfma_f32_16x16x32_bf16 v[112:115], v[132:135], v[184:187], v[112:115]
	v_mfma_f32_16x16x32_bf16 v[112:115], v[136:139], v[196:199], v[112:115]
	v_mfma_f32_16x16x32_bf16 v[96:99], v[132:135], v[200:203], v[96:99]
	v_mfma_f32_16x16x32_bf16 v[96:99], v[136:139], v[204:207], v[96:99]
	v_mfma_f32_16x16x32_bf16 v[92:95], v[152:155], v[200:203], v[92:95]
	v_mfma_f32_16x16x32_bf16 v[92:95], v[156:159], v[204:207], v[92:95]
	v_mfma_f32_16x16x32_bf16 v[76:79], v[152:155], v[208:211], v[76:79]
	v_mfma_f32_16x16x32_bf16 v[76:79], v[156:159], v[212:215], v[76:79]
	v_mfma_f32_16x16x32_bf16 v[80:83], v[132:135], v[208:211], v[80:83]
	v_mfma_f32_16x16x32_bf16 v[80:83], v[136:139], v[212:215], v[80:83]
	s_setprio 0
	s_setprio 1
	v_mfma_f32_16x16x32_bf16 v[120:123], v[160:163], v[176:179], v[120:123]
	v_mfma_f32_16x16x32_bf16 v[120:123], v[164:167], v[180:183], v[120:123]
	v_mfma_f32_16x16x32_bf16 v[116:119], v[168:171], v[176:179], v[116:119]
	v_mfma_f32_16x16x32_bf16 v[116:119], v[172:175], v[180:183], v[116:119]
	v_mfma_f32_16x16x32_bf16 v[100:103], v[168:171], v[184:187], v[100:103]
	v_mfma_f32_16x16x32_bf16 v[100:103], v[172:175], v[196:199], v[100:103]
	v_mfma_f32_16x16x32_bf16 v[104:107], v[160:163], v[184:187], v[104:107]
	v_mfma_f32_16x16x32_bf16 v[104:107], v[164:167], v[196:199], v[104:107]
	v_mfma_f32_16x16x32_bf16 v[88:91], v[160:163], v[200:203], v[88:91]
	v_mfma_f32_16x16x32_bf16 v[88:91], v[164:167], v[204:207], v[88:91]
	v_mfma_f32_16x16x32_bf16 v[84:87], v[168:171], v[200:203], v[84:87]
	v_mfma_f32_16x16x32_bf16 v[84:87], v[172:175], v[204:207], v[84:87]
	v_mfma_f32_16x16x32_bf16 v[68:71], v[168:171], v[208:211], v[68:71]
	v_mfma_f32_16x16x32_bf16 v[68:71], v[172:175], v[212:215], v[68:71]
	v_mfma_f32_16x16x32_bf16 v[72:75], v[160:163], v[208:211], v[72:75]
	v_mfma_f32_16x16x32_bf16 v[72:75], v[164:167], v[212:215], v[72:75]
	s_barrier
; #define PG8_STAGE(bufoff, gbase, voff) do { _Pragma("unroll") for (int _i = 0; _i < 2; ++_i) \
;         __builtin_amdgcn_global_load_lds((const unsigned*)((const char*)(gbase) + (voff)[_i]), (PG8_LAS unsigned*)(lds + (bufoff) + ldsw + _i * 8192), 16, 0, 0); } while (0)
; #define PG8_LDA(dst, b, h) do { _Pragma("unroll") for (int m = 0; m < 4; ++m) _Pragma("unroll") for (int k = 0; k < 2; ++k) dst[m][k] = *(const PG8_LAS bf16x8*)(lds + PG8_SA(b, h) + aoff + m * 2048 + k * 1024); } while (0)
; #define PG8_LDB(dst, b, h) do { _Pragma("unroll") for (int n = 0; n < 2; ++n) _Pragma("unroll") for (int k = 0; k < 2; ++k) dst[n][k] = *(const PG8_LAS bf16x8*)(lds + PG8_SB(b, h) + boff + n * 2048 + k * 1024); } while (0)
; #define PG8_MMA(ai, bj, At, Bt) do { __builtin_amdgcn_s_setprio(1); _Pragma("unroll") for (int m = 0; m < 4; ++m) _Pragma("unroll") for (int n = 0; n < 2; ++n) _Pragma("unroll") for (int k = 0; k < 2; ++k) \
;         acc[ai][bj][m][n] = __builtin_amdgcn_mfma_f32_16x16x32_bf16(Bt[n][k], At[m][k], acc[ai][bj][m][n], 0, 0, 0); __builtin_amdgcn_s_setprio(0); } while (0)
; #define PG8_WAIT_V(n) asm volatile("s_waitcnt vmcnt(" #n ")" ::: "memory")
; #define PG8_WAIT_L(n) asm volatile("s_waitcnt lgkmcnt(" #n ")" ::: "memory")
; #define PG8_BAR __builtin_amdgcn_s_barrier()
; #define PG8_SCHED __builtin_amdgcn_sched_barrier(0)
; template <class Epi, class Sched, bool ALIGN_EPI = false, bool SP2 = false>
; __device__ __forceinline__ void gemm_phase(PG8_LAS unsigned char* lds, const Gemm g, const Sched& S, const Epi& E) {
;     ...
;             PG8_LDA(At, 0, 1); PG8_STAGE(PG8_SB(0, 0), b2, voffB); PG8_STAGE(PG8_SB(0, 1), b2 + hstep, voffB); PG8_STAGE(PG8_SA(0, 0), a2, voffA);
;             PG8_WAIT_V(8); PG8_WAIT_L(0); PG8_BAR; PG8_MMA(1, 0, At, B0); PG8_MMA(1, 1, At, B1); PG8_BAR; PG8_SCHED;
;             PG8_LDB(B0, 1, 0); PG8_LDB(B1, 1, 1); PG8_SCHED; PG8_LDA(At, 1, 0); PG8_STAGE(PG8_SA(0, 1), a2 + hstep, voffA);
;             PG8_WAIT_V(8); PG8_WAIT_L(0); PG8_BAR; PG8_MMA(0, 0, At, B0); PG8_MMA(0, 1, At, B1); PG8_BAR; PG8_SCHED;
	ds_read_b128 v[176:179], v194 offset:16384
	ds_read_b128 v[180:183], v194 offset:17408
	ds_read_b128 v[184:187], v194 offset:18432
	ds_read_b128 v[196:199], v194 offset:19456
	ds_read_b128 v[200:203], v194 offset:20480
	ds_read_b128 v[204:207], v194 offset:21504
	ds_read_b128 v[208:211], v194 offset:22528
	ds_read_b128 v[212:215], v194 offset:23552
	s_setprio 0
	s_add_i32 s77, s77, s10
	s_mov_b32 m0, s77
	s_nop 0
	global_load_lds_dwordx4 v2, s[0:1]
	s_add_i32 m0, s77, 0x2000
	s_add_u32 s78, s0, 0x100000
	s_addc_u32 s79, s1, 0
	s_add_i32 s77, s80, s10
	global_load_lds_dwordx4 v144, s[0:1]
	s_mov_b32 m0, s77
	s_nop 0
	global_load_lds_dwordx4 v2, s[78:79]
	s_add_i32 m0, s77, 0x2000
	s_nop 0
	global_load_lds_dwordx4 v144, s[78:79]
	s_setprio 1
	s_waitcnt vmcnt(6)
	s_waitcnt lgkmcnt(0)
	s_barrier
	v_mfma_f32_16x16x32_bf16 v[64:67], v[132:135], v[176:179], v[64:67]
	v_mfma_f32_16x16x32_bf16 v[64:67], v[136:139], v[180:183], v[64:67]
	v_mfma_f32_16x16x32_bf16 v[60:63], v[152:155], v[176:179], v[60:63]
	v_mfma_f32_16x16x32_bf16 v[60:63], v[156:159], v[180:183], v[60:63]
	v_mfma_f32_16x16x32_bf16 v[44:47], v[152:155], v[184:187], v[44:47]
	v_mfma_f32_16x16x32_bf16 v[44:47], v[156:159], v[196:199], v[44:47]
	v_mfma_f32_16x16x32_bf16 v[48:51], v[132:135], v[184:187], v[48:51]
	v_mfma_f32_16x16x32_bf16 v[48:51], v[136:139], v[196:199], v[48:51]
	v_mfma_f32_16x16x32_bf16 v[32:35], v[132:135], v[200:203], v[32:35]
	v_mfma_f32_16x16x32_bf16 v[32:35], v[136:139], v[204:207], v[32:35]
	v_mfma_f32_16x16x32_bf16 v[28:31], v[152:155], v[200:203], v[28:31]
	v_mfma_f32_16x16x32_bf16 v[28:31], v[156:159], v[204:207], v[28:31]
	v_mfma_f32_16x16x32_bf16 v[12:15], v[152:155], v[208:211], v[12:15]
	v_mfma_f32_16x16x32_bf16 v[12:15], v[156:159], v[212:215], v[12:15]
	v_mfma_f32_16x16x32_bf16 v[16:19], v[132:135], v[208:211], v[16:19]
	v_mfma_f32_16x16x32_bf16 v[16:19], v[136:139], v[212:215], v[16:19]
	s_setprio 0
	s_setprio 1
	v_mfma_f32_16x16x32_bf16 v[56:59], v[160:163], v[176:179], v[56:59]
	v_mfma_f32_16x16x32_bf16 v[56:59], v[164:167], v[180:183], v[56:59]
	v_mfma_f32_16x16x32_bf16 v[52:55], v[168:171], v[176:179], v[52:55]
	v_mfma_f32_16x16x32_bf16 v[52:55], v[172:175], v[180:183], v[52:55]
	v_mfma_f32_16x16x32_bf16 v[36:39], v[168:171], v[184:187], v[36:39]
	v_mfma_f32_16x16x32_bf16 v[36:39], v[172:175], v[196:199], v[36:39]
	v_mfma_f32_16x16x32_bf16 v[40:43], v[160:163], v[184:187], v[40:43]
	v_mfma_f32_16x16x32_bf16 v[40:43], v[164:167], v[196:199], v[40:43]
	v_mfma_f32_16x16x32_bf16 v[24:27], v[160:163], v[200:203], v[24:27]
	v_mfma_f32_16x16x32_bf16 v[24:27], v[164:167], v[204:207], v[24:27]
	v_mfma_f32_16x16x32_bf16 v[20:23], v[168:171], v[200:203], v[20:23]
	v_mfma_f32_16x16x32_bf16 v[20:23], v[172:175], v[204:207], v[20:23]
	v_mfma_f32_16x16x32_bf16 v[4:7], v[168:171], v[208:211], v[4:7]
	v_mfma_f32_16x16x32_bf16 v[4:7], v[172:175], v[212:215], v[4:7]
	v_mfma_f32_16x16x32_bf16 v[8:11], v[160:163], v[208:211], v[8:11]
	v_mfma_f32_16x16x32_bf16 v[8:11], v[164:167], v[212:215], v[8:11]
	s_barrier
	ds_read_b128 v[132:135], v188 offset:32768
	ds_read_b128 v[136:139], v188 offset:33792
	ds_read_b128 v[152:155], v188 offset:34816
	ds_read_b128 v[156:159], v188 offset:35840
	ds_read_b128 v[160:163], v188 offset:49152
	ds_read_b128 v[164:167], v188 offset:50176
	ds_read_b128 v[168:171], v188 offset:51200
	ds_read_b128 v[172:175], v188 offset:52224
	ds_read_b128 v[176:179], v194 offset:32768
	ds_read_b128 v[180:183], v194 offset:33792
	ds_read_b128 v[184:187], v194 offset:34816
	ds_read_b128 v[196:199], v194 offset:35840
	ds_read_b128 v[200:203], v194 offset:36864
	ds_read_b128 v[204:207], v194 offset:37888
	ds_read_b128 v[208:211], v194 offset:38912
	ds_read_b128 v[212:215], v194 offset:39936
	s_setprio 0
	s_add_i32 s77, 0, 0x18000
	s_add_i32 s78, 0, 0x1c000
	s_mov_b32 m0, s11
	s_nop 0
	global_load_lds_dwordx4 v140, s[26:27]
	s_mov_b32 m0, s55
	s_nop 0
	global_load_lds_dwordx4 v142, s[26:27]
	s_add_u32 s26, s26, 0x100000
	s_addc_u32 s27, s27, 0
	s_mov_b32 m0, s60
	s_nop 0
	global_load_lds_dwordx4 v140, s[26:27]
	s_mov_b32 m0, s61
	s_nop 0
	global_load_lds_dwordx4 v142, s[26:27]
	s_nop 0
	s_setprio 1
	s_waitcnt vmcnt(8)
	s_waitcnt lgkmcnt(0)
	s_barrier
; #define PG8_STAGE(bufoff, gbase, voff) do { _Pragma("unroll") for (int _i = 0; _i < 2; ++_i) \
;         __builtin_amdgcn_global_load_lds((const unsigned*)((const char*)(gbase) + (voff)[_i]), (PG8_LAS unsigned*)(lds + (bufoff) + ldsw + _i * 8192), 16, 0, 0); } while (0)
; #define PG8_LDA(dst, b, h) do { _Pragma("unroll") for (int m = 0; m < 4; ++m) _Pragma("unroll") for (int k = 0; k < 2; ++k) dst[m][k] = *(const PG8_LAS bf16x8*)(lds + PG8_SA(b, h) + aoff + m * 2048 + k * 1024); } while (0)
; #define PG8_MMA(ai, bj, At, Bt) do { __builtin_amdgcn_s_setprio(1); _Pragma("unroll") for (int m = 0; m < 4; ++m) _Pragma("unroll") for (int n = 0; n < 2; ++n) _Pragma("unroll") for (int k = 0; k < 2; ++k) \
;         acc[ai][bj][m][n] = __builtin_amdgcn_mfma_f32_16x16x32_bf16(Bt[n][k], At[m][k], acc[ai][bj][m][n], 0, 0, 0); __builtin_amdgcn_s_setprio(0); } while (0)
; #define PG8_WAIT_V(n) asm volatile("s_waitcnt vmcnt(" #n ")" ::: "memory")
; #define PG8_WAIT_L(n) asm volatile("s_waitcnt lgkmcnt(" #n ")" ::: "memory")
; #define PG8_BAR __builtin_amdgcn_s_barrier()
; #define PG8_SCHED __builtin_amdgcn_sched_barrier(0)
; template <class Epi, class Sched, bool ALIGN_EPI = false, bool SP2 = false>
; __device__ __forceinline__ void gemm_phase(PG8_LAS unsigned char* lds, const Gemm g, const Sched& S, const Epi& E) {
;     ...
;             PG8_WAIT_V(8); PG8_WAIT_L(0); PG8_BAR; PG8_MMA(0, 0, At, B0); PG8_MMA(0, 1, At, B1); PG8_BAR; PG8_SCHED;
;             PG8_LDA(At, 1, 1); PG8_STAGE(PG8_SB(1, 0), b3, voffB); PG8_STAGE(PG8_SB(1, 1), b3 + hstep, voffB); PG8_STAGE(PG8_SA(1, 0), a3, voffA);
;             PG8_WAIT_V(8); PG8_WAIT_L(0); PG8_BAR; PG8_MMA(1, 0, At, B0); PG8_MMA(1, 1, At, B1); PG8_BAR; PG8_SCHED;
	v_mfma_f32_16x16x32_bf16 v[128:131], v[132:135], v[176:179], v[128:131]
	v_mfma_f32_16x16x32_bf16 v[128:131], v[136:139], v[180:183], v[128:131]
	v_mfma_f32_16x16x32_bf16 v[124:127], v[152:155], v[176:179], v[124:127]
	v_mfma_f32_16x16x32_bf16 v[124:127], v[156:159], v[180:183], v[124:127]
	v_mfma_f32_16x16x32_bf16 v[108:111], v[152:155], v[184:187], v[108:111]
	v_mfma_f32_16x16x32_bf16 v[108:111], v[156:159], v[196:199], v[108:111]
	v_mfma_f32_16x16x32_bf16 v[112:115], v[132:135], v[184:187], v[112:115]
	v_mfma_f32_16x16x32_bf16 v[112:115], v[136:139], v[196:199], v[112:115]
	v_mfma_f32_16x16x32_bf16 v[96:99], v[132:135], v[200:203], v[96:99]
	v_mfma_f32_16x16x32_bf16 v[96:99], v[136:139], v[204:207], v[96:99]
	v_mfma_f32_16x16x32_bf16 v[92:95], v[152:155], v[200:203], v[92:95]
	v_mfma_f32_16x16x32_bf16 v[92:95], v[156:159], v[204:207], v[92:95]
	v_mfma_f32_16x16x32_bf16 v[76:79], v[152:155], v[208:211], v[76:79]
	v_mfma_f32_16x16x32_bf16 v[76:79], v[156:159], v[212:215], v[76:79]
	v_mfma_f32_16x16x32_bf16 v[80:83], v[132:135], v[208:211], v[80:83]
	v_mfma_f32_16x16x32_bf16 v[80:83], v[136:139], v[212:215], v[80:83]
	s_setprio 0
	s_setprio 1
	v_mfma_f32_16x16x32_bf16 v[120:123], v[160:163], v[176:179], v[120:123]
	v_mfma_f32_16x16x32_bf16 v[120:123], v[164:167], v[180:183], v[120:123]
	v_mfma_f32_16x16x32_bf16 v[116:119], v[168:171], v[176:179], v[116:119]
	v_mfma_f32_16x16x32_bf16 v[116:119], v[172:175], v[180:183], v[116:119]
	v_mfma_f32_16x16x32_bf16 v[100:103], v[168:171], v[184:187], v[100:103]
	v_mfma_f32_16x16x32_bf16 v[100:103], v[172:175], v[196:199], v[100:103]
	v_mfma_f32_16x16x32_bf16 v[104:107], v[160:163], v[184:187], v[104:107]
	v_mfma_f32_16x16x32_bf16 v[104:107], v[164:167], v[196:199], v[104:107]
	v_mfma_f32_16x16x32_bf16 v[88:91], v[160:163], v[200:203], v[88:91]
	v_mfma_f32_16x16x32_bf16 v[88:91], v[164:167], v[204:207], v[88:91]
	v_mfma_f32_16x16x32_bf16 v[84:87], v[168:171], v[200:203], v[84:87]
	v_mfma_f32_16x16x32_bf16 v[84:87], v[172:175], v[204:207], v[84:87]
	v_mfma_f32_16x16x32_bf16 v[68:71], v[168:171], v[208:211], v[68:71]
	v_mfma_f32_16x16x32_bf16 v[68:71], v[172:175], v[212:215], v[68:71]
	v_mfma_f32_16x16x32_bf16 v[72:75], v[160:163], v[208:211], v[72:75]
	v_mfma_f32_16x16x32_bf16 v[72:75], v[164:167], v[212:215], v[72:75]
	s_barrier
	ds_read_b128 v[176:179], v194 offset:49152
	ds_read_b128 v[180:183], v194 offset:50176
	ds_read_b128 v[184:187], v194 offset:51200
	ds_read_b128 v[196:199], v194 offset:52224
	ds_read_b128 v[200:203], v194 offset:53248
	ds_read_b128 v[204:207], v194 offset:54272
	ds_read_b128 v[208:211], v194 offset:55296
	ds_read_b128 v[212:215], v194 offset:56320
	s_setprio 0
	s_add_i32 s26, s77, s10
	s_mov_b32 m0, s26
	s_add_u32 s0, s0, 0x80
	s_addc_u32 s1, s1, 0
	global_load_lds_dwordx4 v2, s[0:1]
	s_add_i32 m0, s26, 0x2000
	s_add_i32 s26, s78, s10
	global_load_lds_dwordx4 v144, s[0:1]
	s_add_u32 s0, s0, 0x100000
	s_addc_u32 s1, s1, 0
	s_mov_b32 m0, s26
	s_nop 0
	global_load_lds_dwordx4 v2, s[0:1]
	s_add_i32 m0, s26, 0x2000
	s_nop 0
	global_load_lds_dwordx4 v144, s[0:1]
	s_setprio 1
	s_waitcnt vmcnt(6)
	s_waitcnt lgkmcnt(0)
	s_barrier
	v_mfma_f32_16x16x32_bf16 v[64:67], v[132:135], v[176:179], v[64:67]
	v_mfma_f32_16x16x32_bf16 v[64:67], v[136:139], v[180:183], v[64:67]
	v_mfma_f32_16x16x32_bf16 v[60:63], v[152:155], v[176:179], v[60:63]
	v_mfma_f32_16x16x32_bf16 v[60:63], v[156:159], v[180:183], v[60:63]
	v_mfma_f32_16x16x32_bf16 v[44:47], v[152:155], v[184:187], v[44:47]
	v_mfma_f32_16x16x32_bf16 v[44:47], v[156:159], v[196:199], v[44:47]
	v_mfma_f32_16x16x32_bf16 v[48:51], v[132:135], v[184:187], v[48:51]
	v_mfma_f32_16x16x32_bf16 v[48:51], v[136:139], v[196:199], v[48:51]
	v_mfma_f32_16x16x32_bf16 v[32:35], v[132:135], v[200:203], v[32:35]
	v_mfma_f32_16x16x32_bf16 v[32:35], v[136:139], v[204:207], v[32:35]
	v_mfma_f32_16x16x32_bf16 v[28:31], v[152:155], v[200:203], v[28:31]
	v_mfma_f32_16x16x32_bf16 v[28:31], v[156:159], v[204:207], v[28:31]
	v_mfma_f32_16x16x32_bf16 v[12:15], v[152:155], v[208:211], v[12:15]
	v_mfma_f32_16x16x32_bf16 v[12:15], v[156:159], v[212:215], v[12:15]
	v_mfma_f32_16x16x32_bf16 v[16:19], v[132:135], v[208:211], v[16:19]
	v_mfma_f32_16x16x32_bf16 v[16:19], v[136:139], v[212:215], v[16:19]
	s_setprio 0
	s_setprio 1
	s_add_i32 s76, s76, 2
	s_add_u32 s40, s40, 0x100
	s_addc_u32 s41, s41, 0
	s_add_u32 s58, s58, 0x100
	s_addc_u32 s59, s59, 0
	s_nop 0
	v_mfma_f32_16x16x32_bf16 v[56:59], v[160:163], v[176:179], v[56:59]
	v_mfma_f32_16x16x32_bf16 v[56:59], v[164:167], v[180:183], v[56:59]
	v_mfma_f32_16x16x32_bf16 v[52:55], v[168:171], v[176:179], v[52:55]
	v_mfma_f32_16x16x32_bf16 v[52:55], v[172:175], v[180:183], v[52:55]
	v_mfma_f32_16x16x32_bf16 v[36:39], v[168:171], v[184:187], v[36:39]
	v_mfma_f32_16x16x32_bf16 v[36:39], v[172:175], v[196:199], v[36:39]
	v_mfma_f32_16x16x32_bf16 v[40:43], v[160:163], v[184:187], v[40:43]
	v_mfma_f32_16x16x32_bf16 v[40:43], v[164:167], v[196:199], v[40:43]
	v_mfma_f32_16x16x32_bf16 v[24:27], v[160:163], v[200:203], v[24:27]
	v_mfma_f32_16x16x32_bf16 v[24:27], v[164:167], v[204:207], v[24:27]
	v_mfma_f32_16x16x32_bf16 v[20:23], v[168:171], v[200:203], v[20:23]
	v_mfma_f32_16x16x32_bf16 v[20:23], v[172:175], v[204:207], v[20:23]
	v_mfma_f32_16x16x32_bf16 v[4:7], v[168:171], v[208:211], v[4:7]
	v_mfma_f32_16x16x32_bf16 v[4:7], v[172:175], v[212:215], v[4:7]
	v_mfma_f32_16x16x32_bf16 v[8:11], v[160:163], v[208:211], v[8:11]
	v_mfma_f32_16x16x32_bf16 v[8:11], v[164:167], v[212:215], v[8:11]
	s_barrier
	s_cmp_gt_u32 s76, 61
	s_cbranch_scc0 .LBB0_2115
	s_setprio 0
	s_and_b64 vcc, exec, s[36:37]
	s_cbranch_vccz .LBB0_2118
	s_barrier

; #define PG8_STAGE(bufoff, gbase, voff) do { _Pragma("unroll") for (int _i = 0; _i < 2; ++_i) \
;         __builtin_amdgcn_global_load_lds((const unsigned*)((const char*)(gbase) + (voff)[_i]), (PG8_LAS unsigned*)(lds + (bufoff) + ldsw + _i * 8192), 16, 0, 0); } while (0)
; #define PG8_LDA(dst, b, h) do { _Pragma("unroll") for (int m = 0; m < 4; ++m) _Pragma("unroll") for (int k = 0; k < 2; ++k) dst[m][k] = *(const PG8_LAS bf16x8*)(lds + PG8_SA(b, h) + aoff + m * 2048 + k * 1024); } while (0)
; #define PG8_LDB(dst, b, h) do { _Pragma("unroll") for (int n = 0; n < 2; ++n) _Pragma("unroll") for (int k = 0; k < 2; ++k) dst[n][k] = *(const PG8_LAS bf16x8*)(lds + PG8_SB(b, h) + boff + n * 2048 + k * 1024); } while (0)
; #define PG8_MMA(ai, bj, At, Bt) do { __builtin_amdgcn_s_setprio(1); _Pragma("unroll") for (int m = 0; m < 4; ++m) _Pragma("unroll") for (int n = 0; n < 2; ++n) _Pragma("unroll") for (int k = 0; k < 2; ++k) \
;         acc[ai][bj][m][n] = __builtin_amdgcn_mfma_f32_16x16x32_bf16(Bt[n][k], At[m][k], acc[ai][bj][m][n], 0, 0, 0); __builtin_amdgcn_s_setprio(0); } while (0)
; #define PG8_WAIT_V(n) asm volatile("s_waitcnt vmcnt(" #n ")" ::: "memory")
; #define PG8_WAIT_L(n) asm volatile("s_waitcnt lgkmcnt(" #n ")" ::: "memory")
; #define PG8_BAR __builtin_amdgcn_s_barrier()
; #define PG8_SCHED __builtin_amdgcn_sched_barrier(0)
; template <class Epi, class Sched, bool ALIGN_EPI = false, bool SP2 = false>
; __device__ __forceinline__ void gemm_phase(PG8_LAS unsigned char* lds, const Gemm g, const Sched& S, const Epi& E) {
;     ...
;             PG8_LDB(B0, 0, 0); PG8_LDB(B1, 0, 1); PG8_SCHED; PG8_LDA(At, 0, 0); PG8_STAGE(PG8_SA(1, 1), a1 + hstep, voffA);
;             PG8_WAIT_V(8); PG8_WAIT_L(0); PG8_BAR; PG8_MMA(0, 0, At, B0); PG8_MMA(0, 1, At, B1); PG8_BAR; PG8_SCHED;
;             PG8_LDA(At, 0, 1); PG8_STAGE(PG8_SB(0, 0), b2, voffB); PG8_STAGE(PG8_SB(0, 1), b2 + hstep, voffB); PG8_STAGE(PG8_SA(0, 0), a2, voffA);
;             PG8_WAIT_V(8); PG8_WAIT_L(0); PG8_BAR; PG8_MMA(1, 0, At, B0); PG8_MMA(1, 1, At, B1); PG8_BAR; PG8_SCHED;
.LBB0_2692:
	ds_read_b128 v[142:145], v210
	ds_read_b128 v[150:153], v210 offset:1024
	ds_read_b128 v[154:157], v210 offset:2048
	ds_read_b128 v[158:161], v210 offset:3072
	ds_read_b128 v[162:165], v210 offset:16384
	ds_read_b128 v[166:169], v210 offset:17408
	ds_read_b128 v[170:173], v210 offset:18432
	ds_read_b128 v[174:177], v210 offset:19456
	ds_read_b128 v[178:181], v149
	ds_read_b128 v[182:185], v149 offset:1024
	ds_read_b128 v[186:189], v149 offset:2048
	ds_read_b128 v[190:193], v149 offset:3072
	ds_read_b128 v[194:197], v149 offset:4096
	ds_read_b128 v[198:201], v149 offset:5120
	ds_read_b128 v[202:205], v149 offset:6144
	ds_read_b128 v[206:209], v149 offset:7168
	s_setprio 0
	s_add_u32 s0, s56, 0xfffe0080
	s_addc_u32 s1, s57, -1
	s_add_i32 s63, 0, 0x10000
	s_cmp_eq_u32 s62, 4
	s_cselect_b32 s27, s51, s1
	s_cselect_b32 s26, s50, s0
	s_cselect_b32 s1, s53, s49
	s_cselect_b32 s0, s52, s47
	s_add_i32 s66, 0, 0x14000
	s_add_u32 s100, s56, 0xfffe0000
	s_addc_u32 s101, s57, -1
	s_mov_b32 m0, s58
	s_nop 0
	global_load_lds_dwordx4 v132, s[100:101]
	s_mov_b32 m0, s59
	s_nop 0
	global_load_lds_dwordx4 v134, s[100:101]
	s_add_i32 m0, s10, 0xc000
	s_nop 0
	global_load_lds_dwordx4 v138, s[56:57]
	s_add_i32 m0, s10, 0xe000
	s_nop 0
	global_load_lds_dwordx4 v140, s[56:57]
	s_setprio 1
	s_waitcnt vmcnt(8)
	s_waitcnt lgkmcnt(0)
	s_barrier
	v_mfma_f32_16x16x32_bf16 v[128:131], v[142:145], v[178:181], v[128:131]
	v_mfma_f32_16x16x32_bf16 v[128:131], v[150:153], v[182:185], v[128:131]
	v_mfma_f32_16x16x32_bf16 v[124:127], v[154:157], v[178:181], v[124:127]
	v_mfma_f32_16x16x32_bf16 v[124:127], v[158:161], v[182:185], v[124:127]
	v_mfma_f32_16x16x32_bf16 v[108:111], v[154:157], v[186:189], v[108:111]
	v_mfma_f32_16x16x32_bf16 v[108:111], v[158:161], v[190:193], v[108:111]
	v_mfma_f32_16x16x32_bf16 v[112:115], v[142:145], v[186:189], v[112:115]
	v_mfma_f32_16x16x32_bf16 v[112:115], v[150:153], v[190:193], v[112:115]
	v_mfma_f32_16x16x32_bf16 v[96:99], v[142:145], v[194:197], v[96:99]
	v_mfma_f32_16x16x32_bf16 v[96:99], v[150:153], v[198:201], v[96:99]
	v_mfma_f32_16x16x32_bf16 v[92:95], v[154:157], v[194:197], v[92:95]
	v_mfma_f32_16x16x32_bf16 v[92:95], v[158:161], v[198:201], v[92:95]
	v_mfma_f32_16x16x32_bf16 v[76:79], v[154:157], v[202:205], v[76:79]
	v_mfma_f32_16x16x32_bf16 v[76:79], v[158:161], v[206:209], v[76:79]
	v_mfma_f32_16x16x32_bf16 v[80:83], v[142:145], v[202:205], v[80:83]
	v_mfma_f32_16x16x32_bf16 v[80:83], v[150:153], v[206:209], v[80:83]
	s_setprio 0
	s_setprio 1
	v_mfma_f32_16x16x32_bf16 v[120:123], v[162:165], v[178:181], v[120:123]
	v_mfma_f32_16x16x32_bf16 v[120:123], v[166:169], v[182:185], v[120:123]
	v_mfma_f32_16x16x32_bf16 v[116:119], v[170:173], v[178:181], v[116:119]
	v_mfma_f32_16x16x32_bf16 v[116:119], v[174:177], v[182:185], v[116:119]
	v_mfma_f32_16x16x32_bf16 v[100:103], v[170:173], v[186:189], v[100:103]
	v_mfma_f32_16x16x32_bf16 v[100:103], v[174:177], v[190:193], v[100:103]
	v_mfma_f32_16x16x32_bf16 v[104:107], v[162:165], v[186:189], v[104:107]
	v_mfma_f32_16x16x32_bf16 v[104:107], v[166:169], v[190:193], v[104:107]
	v_mfma_f32_16x16x32_bf16 v[88:91], v[162:165], v[194:197], v[88:91]
	v_mfma_f32_16x16x32_bf16 v[88:91], v[166:169], v[198:201], v[88:91]
	v_mfma_f32_16x16x32_bf16 v[84:87], v[170:173], v[194:197], v[84:87]
	v_mfma_f32_16x16x32_bf16 v[84:87], v[174:177], v[198:201], v[84:87]
	v_mfma_f32_16x16x32_bf16 v[68:71], v[170:173], v[202:205], v[68:71]
	v_mfma_f32_16x16x32_bf16 v[68:71], v[174:177], v[206:209], v[68:71]
	v_mfma_f32_16x16x32_bf16 v[72:75], v[162:165], v[202:205], v[72:75]
	v_mfma_f32_16x16x32_bf16 v[72:75], v[166:169], v[206:209], v[72:75]
	s_barrier
	ds_read_b128 v[178:181], v149 offset:16384
	ds_read_b128 v[182:185], v149 offset:17408
	ds_read_b128 v[186:189], v149 offset:18432
	ds_read_b128 v[190:193], v149 offset:19456
	ds_read_b128 v[194:197], v149 offset:20480
	ds_read_b128 v[198:201], v149 offset:21504
	ds_read_b128 v[202:205], v149 offset:22528
	ds_read_b128 v[206:209], v149 offset:23552
	s_setprio 0
	s_add_i32 s63, s63, s9
	s_mov_b32 m0, s63
	s_nop 0
	global_load_lds_dwordx4 v2, s[0:1]
	s_add_i32 m0, s63, 0x2000
	s_add_u32 s64, s0, 0x20000
	s_addc_u32 s65, s1, 0
	s_add_i32 s63, s66, s9
	global_load_lds_dwordx4 v136, s[0:1]
	s_mov_b32 m0, s63
	s_nop 0
	global_load_lds_dwordx4 v2, s[64:65]
	s_add_i32 m0, s63, 0x2000
	s_nop 0
	global_load_lds_dwordx4 v136, s[64:65]
	s_setprio 1
	s_waitcnt vmcnt(6)
	s_waitcnt lgkmcnt(0)
	s_barrier
	v_mfma_f32_16x16x32_bf16 v[64:67], v[142:145], v[178:181], v[64:67]
	v_mfma_f32_16x16x32_bf16 v[64:67], v[150:153], v[182:185], v[64:67]
	v_mfma_f32_16x16x32_bf16 v[60:63], v[154:157], v[178:181], v[60:63]
	v_mfma_f32_16x16x32_bf16 v[60:63], v[158:161], v[182:185], v[60:63]
	v_mfma_f32_16x16x32_bf16 v[44:47], v[154:157], v[186:189], v[44:47]
	v_mfma_f32_16x16x32_bf16 v[44:47], v[158:161], v[190:193], v[44:47]
	v_mfma_f32_16x16x32_bf16 v[48:51], v[142:145], v[186:189], v[48:51]
	v_mfma_f32_16x16x32_bf16 v[48:51], v[150:153], v[190:193], v[48:51]
	v_mfma_f32_16x16x32_bf16 v[32:35], v[142:145], v[194:197], v[32:35]
	v_mfma_f32_16x16x32_bf16 v[32:35], v[150:153], v[198:201], v[32:35]
	v_mfma_f32_16x16x32_bf16 v[28:31], v[154:157], v[194:197], v[28:31]
	v_mfma_f32_16x16x32_bf16 v[28:31], v[158:161], v[198:201], v[28:31]
	v_mfma_f32_16x16x32_bf16 v[12:15], v[154:157], v[202:205], v[12:15]
	v_mfma_f32_16x16x32_bf16 v[12:15], v[158:161], v[206:209], v[12:15]
	v_mfma_f32_16x16x32_bf16 v[16:19], v[142:145], v[202:205], v[16:19]
	v_mfma_f32_16x16x32_bf16 v[16:19], v[150:153], v[206:209], v[16:19]
	s_setprio 0
	s_setprio 1
	v_mfma_f32_16x16x32_bf16 v[56:59], v[162:165], v[178:181], v[56:59]
	v_mfma_f32_16x16x32_bf16 v[56:59], v[166:169], v[182:185], v[56:59]
	v_mfma_f32_16x16x32_bf16 v[52:55], v[170:173], v[178:181], v[52:55]
	v_mfma_f32_16x16x32_bf16 v[52:55], v[174:177], v[182:185], v[52:55]
	v_mfma_f32_16x16x32_bf16 v[36:39], v[170:173], v[186:189], v[36:39]
	v_mfma_f32_16x16x32_bf16 v[36:39], v[174:177], v[190:193], v[36:39]
	v_mfma_f32_16x16x32_bf16 v[40:43], v[162:165], v[186:189], v[40:43]
	v_mfma_f32_16x16x32_bf16 v[40:43], v[166:169], v[190:193], v[40:43]
	v_mfma_f32_16x16x32_bf16 v[24:27], v[162:165], v[194:197], v[24:27]
	v_mfma_f32_16x16x32_bf16 v[24:27], v[166:169], v[198:201], v[24:27]
	v_mfma_f32_16x16x32_bf16 v[20:23], v[170:173], v[194:197], v[20:23]
	v_mfma_f32_16x16x32_bf16 v[20:23], v[174:177], v[198:201], v[20:23]
	v_mfma_f32_16x16x32_bf16 v[4:7], v[170:173], v[202:205], v[4:7]
	v_mfma_f32_16x16x32_bf16 v[4:7], v[174:177], v[206:209], v[4:7]
	v_mfma_f32_16x16x32_bf16 v[8:11], v[162:165], v[202:205], v[8:11]
	v_mfma_f32_16x16x32_bf16 v[8:11], v[166:169], v[206:209], v[8:11]
	s_barrier
; #define PG8_STAGE(bufoff, gbase, voff) do { _Pragma("unroll") for (int _i = 0; _i < 2; ++_i) \
;         __builtin_amdgcn_global_load_lds((const unsigned*)((const char*)(gbase) + (voff)[_i]), (PG8_LAS unsigned*)(lds + (bufoff) + ldsw + _i * 8192), 16, 0, 0); } while (0)
; #define PG8_LDA(dst, b, h) do { _Pragma("unroll") for (int m = 0; m < 4; ++m) _Pragma("unroll") for (int k = 0; k < 2; ++k) dst[m][k] = *(const PG8_LAS bf16x8*)(lds + PG8_SA(b, h) + aoff + m * 2048 + k * 1024); } while (0)
; #define PG8_LDB(dst, b, h) do { _Pragma("unroll") for (int n = 0; n < 2; ++n) _Pragma("unroll") for (int k = 0; k < 2; ++k) dst[n][k] = *(const PG8_LAS bf16x8*)(lds + PG8_SB(b, h) + boff + n * 2048 + k * 1024); } while (0)
; #define PG8_MMA(ai, bj, At, Bt) do { __builtin_amdgcn_s_setprio(1); _Pragma("unroll") for (int m = 0; m < 4; ++m) _Pragma("unroll") for (int n = 0; n < 2; ++n) _Pragma("unroll") for (int k = 0; k < 2; ++k) \
;         acc[ai][bj][m][n] = __builtin_amdgcn_mfma_f32_16x16x32_bf16(Bt[n][k], At[m][k], acc[ai][bj][m][n], 0, 0, 0); __builtin_amdgcn_s_setprio(0); } while (0)
; #define PG8_WAIT_V(n) asm volatile("s_waitcnt vmcnt(" #n ")" ::: "memory")
; #define PG8_WAIT_L(n) asm volatile("s_waitcnt lgkmcnt(" #n ")" ::: "memory")
; #define PG8_BAR __builtin_amdgcn_s_barrier()
; #define PG8_SCHED __builtin_amdgcn_sched_barrier(0)
; template <class Epi, class Sched, bool ALIGN_EPI = false, bool SP2 = false>
; __device__ __forceinline__ void gemm_phase(PG8_LAS unsigned char* lds, const Gemm g, const Sched& S, const Epi& E) {
;     ...
;             PG8_LDB(B0, 1, 0); PG8_LDB(B1, 1, 1); PG8_SCHED; PG8_LDA(At, 1, 0); PG8_STAGE(PG8_SA(0, 1), a2 + hstep, voffA);
;             PG8_WAIT_V(8); PG8_WAIT_L(0); PG8_BAR; PG8_MMA(0, 0, At, B0); PG8_MMA(0, 1, At, B1); PG8_BAR; PG8_SCHED;
;             PG8_LDA(At, 1, 1); PG8_STAGE(PG8_SB(1, 0), b3, voffB); PG8_STAGE(PG8_SB(1, 1), b3 + hstep, voffB); PG8_STAGE(PG8_SA(1, 0), a3, voffA);
;             PG8_WAIT_V(8); PG8_WAIT_L(0); PG8_BAR; PG8_MMA(1, 0, At, B0); PG8_MMA(1, 1, At, B1); PG8_BAR; PG8_SCHED;
	ds_read_b128 v[142:145], v210 offset:32768
	ds_read_b128 v[150:153], v210 offset:33792
	ds_read_b128 v[154:157], v210 offset:34816
	ds_read_b128 v[158:161], v210 offset:35840
	ds_read_b128 v[162:165], v210 offset:49152
	ds_read_b128 v[166:169], v210 offset:50176
	ds_read_b128 v[170:173], v210 offset:51200
	ds_read_b128 v[174:177], v210 offset:52224
	ds_read_b128 v[178:181], v149 offset:32768
	ds_read_b128 v[182:185], v149 offset:33792
	ds_read_b128 v[186:189], v149 offset:34816
	ds_read_b128 v[190:193], v149 offset:35840
	ds_read_b128 v[194:197], v149 offset:36864
	ds_read_b128 v[198:201], v149 offset:37888
	ds_read_b128 v[202:205], v149 offset:38912
	ds_read_b128 v[206:209], v149 offset:39936
	s_setprio 0
	s_add_i32 s63, 0, 0x18000
	s_add_i32 s64, 0, 0x1c000
	s_mov_b32 m0, s10
	s_nop 0
	global_load_lds_dwordx4 v132, s[26:27]
	s_mov_b32 m0, s11
	s_nop 0
	global_load_lds_dwordx4 v134, s[26:27]
	s_add_u32 s26, s26, 0x20000
	s_addc_u32 s27, s27, 0
	s_mov_b32 m0, s25
	s_nop 0
	global_load_lds_dwordx4 v132, s[26:27]
	s_mov_b32 m0, s55
	s_nop 0
	global_load_lds_dwordx4 v134, s[26:27]
	s_nop 0
	s_setprio 1
	s_waitcnt vmcnt(8)
	s_waitcnt lgkmcnt(0)
	s_barrier
	v_mfma_f32_16x16x32_bf16 v[128:131], v[142:145], v[178:181], v[128:131]
	v_mfma_f32_16x16x32_bf16 v[128:131], v[150:153], v[182:185], v[128:131]
	v_mfma_f32_16x16x32_bf16 v[124:127], v[154:157], v[178:181], v[124:127]
	v_mfma_f32_16x16x32_bf16 v[124:127], v[158:161], v[182:185], v[124:127]
	v_mfma_f32_16x16x32_bf16 v[108:111], v[154:157], v[186:189], v[108:111]
	v_mfma_f32_16x16x32_bf16 v[108:111], v[158:161], v[190:193], v[108:111]
	v_mfma_f32_16x16x32_bf16 v[112:115], v[142:145], v[186:189], v[112:115]
	v_mfma_f32_16x16x32_bf16 v[112:115], v[150:153], v[190:193], v[112:115]
	v_mfma_f32_16x16x32_bf16 v[96:99], v[142:145], v[194:197], v[96:99]
	v_mfma_f32_16x16x32_bf16 v[96:99], v[150:153], v[198:201], v[96:99]
	v_mfma_f32_16x16x32_bf16 v[92:95], v[154:157], v[194:197], v[92:95]
	v_mfma_f32_16x16x32_bf16 v[92:95], v[158:161], v[198:201], v[92:95]
	v_mfma_f32_16x16x32_bf16 v[76:79], v[154:157], v[202:205], v[76:79]
	v_mfma_f32_16x16x32_bf16 v[76:79], v[158:161], v[206:209], v[76:79]
	v_mfma_f32_16x16x32_bf16 v[80:83], v[142:145], v[202:205], v[80:83]
	v_mfma_f32_16x16x32_bf16 v[80:83], v[150:153], v[206:209], v[80:83]
	s_setprio 0
	s_setprio 1
	v_mfma_f32_16x16x32_bf16 v[120:123], v[162:165], v[178:181], v[120:123]
	v_mfma_f32_16x16x32_bf16 v[120:123], v[166:169], v[182:185], v[120:123]
	v_mfma_f32_16x16x32_bf16 v[116:119], v[170:173], v[178:181], v[116:119]
	v_mfma_f32_16x16x32_bf16 v[116:119], v[174:177], v[182:185], v[116:119]
	v_mfma_f32_16x16x32_bf16 v[100:103], v[170:173], v[186:189], v[100:103]
	v_mfma_f32_16x16x32_bf16 v[100:103], v[174:177], v[190:193], v[100:103]
	v_mfma_f32_16x16x32_bf16 v[104:107], v[162:165], v[186:189], v[104:107]
	v_mfma_f32_16x16x32_bf16 v[104:107], v[166:169], v[190:193], v[104:107]
	v_mfma_f32_16x16x32_bf16 v[88:91], v[162:165], v[194:197], v[88:91]
	v_mfma_f32_16x16x32_bf16 v[88:91], v[166:169], v[198:201], v[88:91]
	v_mfma_f32_16x16x32_bf16 v[84:87], v[170:173], v[194:197], v[84:87]
	v_mfma_f32_16x16x32_bf16 v[84:87], v[174:177], v[198:201], v[84:87]
	v_mfma_f32_16x16x32_bf16 v[68:71], v[170:173], v[202:205], v[68:71]
	v_mfma_f32_16x16x32_bf16 v[68:71], v[174:177], v[206:209], v[68:71]
	v_mfma_f32_16x16x32_bf16 v[72:75], v[162:165], v[202:205], v[72:75]
	v_mfma_f32_16x16x32_bf16 v[72:75], v[166:169], v[206:209], v[72:75]
	s_barrier
	ds_read_b128 v[178:181], v149 offset:49152
	ds_read_b128 v[182:185], v149 offset:50176
	ds_read_b128 v[186:189], v149 offset:51200
	ds_read_b128 v[190:193], v149 offset:52224
	ds_read_b128 v[194:197], v149 offset:53248
	ds_read_b128 v[198:201], v149 offset:54272
	ds_read_b128 v[202:205], v149 offset:55296
	ds_read_b128 v[206:209], v149 offset:56320
	s_setprio 0
	s_add_i32 s26, s63, s9
	s_mov_b32 m0, s26
	s_add_u32 s0, s0, 0x80
	s_addc_u32 s1, s1, 0
	global_load_lds_dwordx4 v2, s[0:1]
	s_add_i32 m0, s26, 0x2000
	s_add_i32 s26, s64, s9
	global_load_lds_dwordx4 v136, s[0:1]
	s_add_u32 s0, s0, 0x20000
	s_addc_u32 s1, s1, 0
	s_mov_b32 m0, s26
	s_nop 0
	global_load_lds_dwordx4 v2, s[0:1]
	s_add_i32 m0, s26, 0x2000
	s_nop 0
	global_load_lds_dwordx4 v136, s[0:1]
	s_setprio 1
	s_waitcnt vmcnt(6)
	s_waitcnt lgkmcnt(0)
	s_barrier
	v_mfma_f32_16x16x32_bf16 v[64:67], v[142:145], v[178:181], v[64:67]
	v_mfma_f32_16x16x32_bf16 v[64:67], v[150:153], v[182:185], v[64:67]
	v_mfma_f32_16x16x32_bf16 v[60:63], v[154:157], v[178:181], v[60:63]
	v_mfma_f32_16x16x32_bf16 v[60:63], v[158:161], v[182:185], v[60:63]
	v_mfma_f32_16x16x32_bf16 v[44:47], v[154:157], v[186:189], v[44:47]
	v_mfma_f32_16x16x32_bf16 v[44:47], v[158:161], v[190:193], v[44:47]
	v_mfma_f32_16x16x32_bf16 v[48:51], v[142:145], v[186:189], v[48:51]
	v_mfma_f32_16x16x32_bf16 v[48:51], v[150:153], v[190:193], v[48:51]
	v_mfma_f32_16x16x32_bf16 v[32:35], v[142:145], v[194:197], v[32:35]
	v_mfma_f32_16x16x32_bf16 v[32:35], v[150:153], v[198:201], v[32:35]
	v_mfma_f32_16x16x32_bf16 v[28:31], v[154:157], v[194:197], v[28:31]
	v_mfma_f32_16x16x32_bf16 v[28:31], v[158:161], v[198:201], v[28:31]
	v_mfma_f32_16x16x32_bf16 v[12:15], v[154:157], v[202:205], v[12:15]
	v_mfma_f32_16x16x32_bf16 v[12:15], v[158:161], v[206:209], v[12:15]
	v_mfma_f32_16x16x32_bf16 v[16:19], v[142:145], v[202:205], v[16:19]
	v_mfma_f32_16x16x32_bf16 v[16:19], v[150:153], v[206:209], v[16:19]
	s_setprio 0
	s_setprio 1
	s_add_i32 s62, s62, 2
	s_add_u32 s56, s56, 0x100
	s_addc_u32 s57, s57, 0
	s_add_u32 s47, s47, 0x100
	s_addc_u32 s49, s49, 0
	s_nop 0
	v_mfma_f32_16x16x32_bf16 v[56:59], v[162:165], v[178:181], v[56:59]
	v_mfma_f32_16x16x32_bf16 v[56:59], v[166:169], v[182:185], v[56:59]
	v_mfma_f32_16x16x32_bf16 v[52:55], v[170:173], v[178:181], v[52:55]
	v_mfma_f32_16x16x32_bf16 v[52:55], v[174:177], v[182:185], v[52:55]
	v_mfma_f32_16x16x32_bf16 v[36:39], v[170:173], v[186:189], v[36:39]
	v_mfma_f32_16x16x32_bf16 v[36:39], v[174:177], v[190:193], v[36:39]
	v_mfma_f32_16x16x32_bf16 v[40:43], v[162:165], v[186:189], v[40:43]
	v_mfma_f32_16x16x32_bf16 v[40:43], v[166:169], v[190:193], v[40:43]
	v_mfma_f32_16x16x32_bf16 v[24:27], v[162:165], v[194:197], v[24:27]
	v_mfma_f32_16x16x32_bf16 v[24:27], v[166:169], v[198:201], v[24:27]
	v_mfma_f32_16x16x32_bf16 v[20:23], v[170:173], v[194:197], v[20:23]
	v_mfma_f32_16x16x32_bf16 v[20:23], v[174:177], v[198:201], v[20:23]
	v_mfma_f32_16x16x32_bf16 v[4:7], v[170:173], v[202:205], v[4:7]
	v_mfma_f32_16x16x32_bf16 v[4:7], v[174:177], v[206:209], v[4:7]
	v_mfma_f32_16x16x32_bf16 v[8:11], v[162:165], v[202:205], v[8:11]
	v_mfma_f32_16x16x32_bf16 v[8:11], v[166:169], v[206:209], v[8:11]
	s_barrier
	s_cmp_gt_u32 s62, 5
	s_cbranch_scc0 .LBB0_2692
	s_setprio 0
	s_and_b64 vcc, exec, s[44:45]
	s_cbranch_vccz .LBB0_2695
	s_barrier

; #define PG8_STAGE(bufoff, gbase, voff) do { _Pragma("unroll") for (int _i = 0; _i < 2; ++_i) \
;         __builtin_amdgcn_global_load_lds((const unsigned*)((const char*)(gbase) + (voff)[_i]), (PG8_LAS unsigned*)(lds + (bufoff) + ldsw + _i * 8192), 16, 0, 0); } while (0)
; #define PG8_LDA(dst, b, h) do { _Pragma("unroll") for (int m = 0; m < 4; ++m) _Pragma("unroll") for (int k = 0; k < 2; ++k) dst[m][k] = *(const PG8_LAS bf16x8*)(lds + PG8_SA(b, h) + aoff + m * 2048 + k * 1024); } while (0)
; #define PG8_LDB(dst, b, h) do { _Pragma("unroll") for (int n = 0; n < 2; ++n) _Pragma("unroll") for (int k = 0; k < 2; ++k) dst[n][k] = *(const PG8_LAS bf16x8*)(lds + PG8_SB(b, h) + boff + n * 2048 + k * 1024); } while (0)
; #define PG8_MMA(ai, bj, At, Bt) do { __builtin_amdgcn_s_setprio(1); _Pragma("unroll") for (int m = 0; m < 4; ++m) _Pragma("unroll") for (int n = 0; n < 2; ++n) _Pragma("unroll") for (int k = 0; k < 2; ++k) \
;         acc[ai][bj][m][n] = __builtin_amdgcn_mfma_f32_16x16x32_bf16(Bt[n][k], At[m][k], acc[ai][bj][m][n], 0, 0, 0); __builtin_amdgcn_s_setprio(0); } while (0)
; #define PG8_WAIT_V(n) asm volatile("s_waitcnt vmcnt(" #n ")" ::: "memory")
; #define PG8_WAIT_L(n) asm volatile("s_waitcnt lgkmcnt(" #n ")" ::: "memory")
; #define PG8_BAR __builtin_amdgcn_s_barrier()
; #define PG8_SCHED __builtin_amdgcn_sched_barrier(0)
; template <class Epi, class Sched, bool ALIGN_EPI = false, bool SP2 = false>
; __device__ __forceinline__ void gemm_phase(PG8_LAS unsigned char* lds, const Gemm g, const Sched& S, const Epi& E) {
;     ...
;             PG8_LDB(B0, 0, 0); PG8_LDB(B1, 0, 1); PG8_SCHED; PG8_LDA(At, 0, 0); PG8_STAGE(PG8_SA(1, 1), a1 + hstep, voffA);
;             PG8_WAIT_V(8); PG8_WAIT_L(0); PG8_BAR; PG8_MMA(0, 0, At, B0); PG8_MMA(0, 1, At, B1); PG8_BAR; PG8_SCHED;
;             PG8_LDA(At, 0, 1); PG8_STAGE(PG8_SB(0, 0), b2, voffB); PG8_STAGE(PG8_SB(0, 1), b2 + hstep, voffB); PG8_STAGE(PG8_SA(0, 0), a2, voffA);
;             PG8_WAIT_V(8); PG8_WAIT_L(0); PG8_BAR; PG8_MMA(1, 0, At, B0); PG8_MMA(1, 1, At, B1); PG8_BAR; PG8_SCHED;
.LBB0_3159:
	ds_read_b128 v[142:145], v146
	ds_read_b128 v[152:155], v146 offset:1024
	ds_read_b128 v[156:159], v146 offset:2048
	ds_read_b128 v[160:163], v146 offset:3072
	ds_read_b128 v[164:167], v146 offset:16384
	ds_read_b128 v[168:171], v146 offset:17408
	ds_read_b128 v[172:175], v146 offset:18432
	ds_read_b128 v[176:179], v146 offset:19456
	ds_read_b128 v[180:183], v151
	ds_read_b128 v[184:187], v151 offset:1024
	ds_read_b128 v[188:191], v151 offset:2048
	ds_read_b128 v[192:195], v151 offset:3072
	ds_read_b128 v[196:199], v151 offset:4096
	ds_read_b128 v[200:203], v151 offset:5120
	ds_read_b128 v[204:207], v151 offset:6144
	ds_read_b128 v[208:211], v151 offset:7168
	s_setprio 0
	s_add_u32 s0, s24, 0xfff00080
	s_addc_u32 s1, s25, -1
	s_add_i32 s65, 0, 0x10000
	s_cmp_eq_u32 s64, 60
	s_cselect_b32 s27, s51, s1
	s_cselect_b32 s26, s60, s0
	s_cselect_b32 s1, s49, s63
	s_cselect_b32 s0, s61, s62
	s_add_i32 s70, 0, 0x14000
	s_add_u32 s100, s24, 0xfff00000
	s_addc_u32 s101, s25, -1
	s_mov_b32 m0, s56
	s_nop 0
	global_load_lds_dwordx4 v136, s[100:101]
	s_mov_b32 m0, s57
	s_nop 0
	global_load_lds_dwordx4 v134, s[100:101]
	s_add_i32 m0, s34, 0xc000
	s_nop 0
	global_load_lds_dwordx4 v138, s[24:25]
	s_add_i32 m0, s34, 0xe000
	s_nop 0
	global_load_lds_dwordx4 v140, s[24:25]
	s_nop 0
	s_setprio 1
	s_waitcnt vmcnt(8)
	s_waitcnt lgkmcnt(0)
	s_barrier
	v_mfma_f32_16x16x32_bf16 v[128:131], v[142:145], v[180:183], v[128:131]
	v_mfma_f32_16x16x32_bf16 v[128:131], v[152:155], v[184:187], v[128:131]
	v_mfma_f32_16x16x32_bf16 v[124:127], v[156:159], v[180:183], v[124:127]
	v_mfma_f32_16x16x32_bf16 v[124:127], v[160:163], v[184:187], v[124:127]
	v_mfma_f32_16x16x32_bf16 v[108:111], v[156:159], v[188:191], v[108:111]
	v_mfma_f32_16x16x32_bf16 v[108:111], v[160:163], v[192:195], v[108:111]
	v_mfma_f32_16x16x32_bf16 v[112:115], v[142:145], v[188:191], v[112:115]
	v_mfma_f32_16x16x32_bf16 v[112:115], v[152:155], v[192:195], v[112:115]
	v_mfma_f32_16x16x32_bf16 v[96:99], v[142:145], v[196:199], v[96:99]
	v_mfma_f32_16x16x32_bf16 v[96:99], v[152:155], v[200:203], v[96:99]
	v_mfma_f32_16x16x32_bf16 v[92:95], v[156:159], v[196:199], v[92:95]
	v_mfma_f32_16x16x32_bf16 v[92:95], v[160:163], v[200:203], v[92:95]
	v_mfma_f32_16x16x32_bf16 v[76:79], v[156:159], v[204:207], v[76:79]
	v_mfma_f32_16x16x32_bf16 v[76:79], v[160:163], v[208:211], v[76:79]
	v_mfma_f32_16x16x32_bf16 v[80:83], v[142:145], v[204:207], v[80:83]
	v_mfma_f32_16x16x32_bf16 v[80:83], v[152:155], v[208:211], v[80:83]
	s_setprio 0
	s_setprio 1
	v_mfma_f32_16x16x32_bf16 v[120:123], v[164:167], v[180:183], v[120:123]
	v_mfma_f32_16x16x32_bf16 v[120:123], v[168:171], v[184:187], v[120:123]
	v_mfma_f32_16x16x32_bf16 v[116:119], v[172:175], v[180:183], v[116:119]
	v_mfma_f32_16x16x32_bf16 v[116:119], v[176:179], v[184:187], v[116:119]
	v_mfma_f32_16x16x32_bf16 v[100:103], v[172:175], v[188:191], v[100:103]
	v_mfma_f32_16x16x32_bf16 v[100:103], v[176:179], v[192:195], v[100:103]
	v_mfma_f32_16x16x32_bf16 v[104:107], v[164:167], v[188:191], v[104:107]
	v_mfma_f32_16x16x32_bf16 v[104:107], v[168:171], v[192:195], v[104:107]
	v_mfma_f32_16x16x32_bf16 v[88:91], v[164:167], v[196:199], v[88:91]
	v_mfma_f32_16x16x32_bf16 v[88:91], v[168:171], v[200:203], v[88:91]
	v_mfma_f32_16x16x32_bf16 v[84:87], v[172:175], v[196:199], v[84:87]
	v_mfma_f32_16x16x32_bf16 v[84:87], v[176:179], v[200:203], v[84:87]
	v_mfma_f32_16x16x32_bf16 v[68:71], v[172:175], v[204:207], v[68:71]
	v_mfma_f32_16x16x32_bf16 v[68:71], v[176:179], v[208:211], v[68:71]
	v_mfma_f32_16x16x32_bf16 v[72:75], v[164:167], v[204:207], v[72:75]
	v_mfma_f32_16x16x32_bf16 v[72:75], v[168:171], v[208:211], v[72:75]
	s_barrier
	ds_read_b128 v[180:183], v151 offset:16384
	ds_read_b128 v[184:187], v151 offset:17408
	ds_read_b128 v[188:191], v151 offset:18432
	ds_read_b128 v[192:195], v151 offset:19456
	ds_read_b128 v[196:199], v151 offset:20480
	ds_read_b128 v[200:203], v151 offset:21504
	ds_read_b128 v[204:207], v151 offset:22528
	ds_read_b128 v[208:211], v151 offset:23552
	s_setprio 0
	s_add_i32 s65, s65, s9
	s_mov_b32 m0, s65
	s_nop 0
	global_load_lds_dwordx4 v2, s[0:1]
	s_add_i32 m0, s65, 0x2000
	s_add_u32 s66, s0, 0x100000
	s_addc_u32 s67, s1, 0
	s_add_i32 s65, s70, s9
	global_load_lds_dwordx4 v132, s[0:1]
	s_mov_b32 m0, s65
	s_nop 0
	global_load_lds_dwordx4 v2, s[66:67]
	s_add_i32 m0, s65, 0x2000
	s_nop 0
	global_load_lds_dwordx4 v132, s[66:67]
	s_setprio 1
	s_waitcnt vmcnt(6)
	s_waitcnt lgkmcnt(0)
	s_barrier
	v_mfma_f32_16x16x32_bf16 v[64:67], v[142:145], v[180:183], v[64:67]
	v_mfma_f32_16x16x32_bf16 v[64:67], v[152:155], v[184:187], v[64:67]
	v_mfma_f32_16x16x32_bf16 v[60:63], v[156:159], v[180:183], v[60:63]
	v_mfma_f32_16x16x32_bf16 v[60:63], v[160:163], v[184:187], v[60:63]
	v_mfma_f32_16x16x32_bf16 v[44:47], v[156:159], v[188:191], v[44:47]
	v_mfma_f32_16x16x32_bf16 v[44:47], v[160:163], v[192:195], v[44:47]
	v_mfma_f32_16x16x32_bf16 v[48:51], v[142:145], v[188:191], v[48:51]
	v_mfma_f32_16x16x32_bf16 v[48:51], v[152:155], v[192:195], v[48:51]
	v_mfma_f32_16x16x32_bf16 v[32:35], v[142:145], v[196:199], v[32:35]
	v_mfma_f32_16x16x32_bf16 v[32:35], v[152:155], v[200:203], v[32:35]
	v_mfma_f32_16x16x32_bf16 v[28:31], v[156:159], v[196:199], v[28:31]
	v_mfma_f32_16x16x32_bf16 v[28:31], v[160:163], v[200:203], v[28:31]
	v_mfma_f32_16x16x32_bf16 v[12:15], v[156:159], v[204:207], v[12:15]
	v_mfma_f32_16x16x32_bf16 v[12:15], v[160:163], v[208:211], v[12:15]
	v_mfma_f32_16x16x32_bf16 v[16:19], v[142:145], v[204:207], v[16:19]
	v_mfma_f32_16x16x32_bf16 v[16:19], v[152:155], v[208:211], v[16:19]
	s_setprio 0
	s_setprio 1
	v_mfma_f32_16x16x32_bf16 v[56:59], v[164:167], v[180:183], v[56:59]
	v_mfma_f32_16x16x32_bf16 v[56:59], v[168:171], v[184:187], v[56:59]
	v_mfma_f32_16x16x32_bf16 v[52:55], v[172:175], v[180:183], v[52:55]
	v_mfma_f32_16x16x32_bf16 v[52:55], v[176:179], v[184:187], v[52:55]
	v_mfma_f32_16x16x32_bf16 v[36:39], v[172:175], v[188:191], v[36:39]
	v_mfma_f32_16x16x32_bf16 v[36:39], v[176:179], v[192:195], v[36:39]
	v_mfma_f32_16x16x32_bf16 v[40:43], v[164:167], v[188:191], v[40:43]
	v_mfma_f32_16x16x32_bf16 v[40:43], v[168:171], v[192:195], v[40:43]
	v_mfma_f32_16x16x32_bf16 v[24:27], v[164:167], v[196:199], v[24:27]
	v_mfma_f32_16x16x32_bf16 v[24:27], v[168:171], v[200:203], v[24:27]
	v_mfma_f32_16x16x32_bf16 v[20:23], v[172:175], v[196:199], v[20:23]
	v_mfma_f32_16x16x32_bf16 v[20:23], v[176:179], v[200:203], v[20:23]
	v_mfma_f32_16x16x32_bf16 v[4:7], v[172:175], v[204:207], v[4:7]
	v_mfma_f32_16x16x32_bf16 v[4:7], v[176:179], v[208:211], v[4:7]
	v_mfma_f32_16x16x32_bf16 v[8:11], v[164:167], v[204:207], v[8:11]
	v_mfma_f32_16x16x32_bf16 v[8:11], v[168:171], v[208:211], v[8:11]
	s_barrier
; #define PG8_STAGE(bufoff, gbase, voff) do { _Pragma("unroll") for (int _i = 0; _i < 2; ++_i) \
;         __builtin_amdgcn_global_load_lds((const unsigned*)((const char*)(gbase) + (voff)[_i]), (PG8_LAS unsigned*)(lds + (bufoff) + ldsw + _i * 8192), 16, 0, 0); } while (0)
; #define PG8_LDA(dst, b, h) do { _Pragma("unroll") for (int m = 0; m < 4; ++m) _Pragma("unroll") for (int k = 0; k < 2; ++k) dst[m][k] = *(const PG8_LAS bf16x8*)(lds + PG8_SA(b, h) + aoff + m * 2048 + k * 1024); } while (0)
; #define PG8_LDB(dst, b, h) do { _Pragma("unroll") for (int n = 0; n < 2; ++n) _Pragma("unroll") for (int k = 0; k < 2; ++k) dst[n][k] = *(const PG8_LAS bf16x8*)(lds + PG8_SB(b, h) + boff + n * 2048 + k * 1024); } while (0)
; #define PG8_MMA(ai, bj, At, Bt) do { __builtin_amdgcn_s_setprio(1); _Pragma("unroll") for (int m = 0; m < 4; ++m) _Pragma("unroll") for (int n = 0; n < 2; ++n) _Pragma("unroll") for (int k = 0; k < 2; ++k) \
;         acc[ai][bj][m][n] = __builtin_amdgcn_mfma_f32_16x16x32_bf16(Bt[n][k], At[m][k], acc[ai][bj][m][n], 0, 0, 0); __builtin_amdgcn_s_setprio(0); } while (0)
; #define PG8_WAIT_V(n) asm volatile("s_waitcnt vmcnt(" #n ")" ::: "memory")
; #define PG8_WAIT_L(n) asm volatile("s_waitcnt lgkmcnt(" #n ")" ::: "memory")
; #define PG8_BAR __builtin_amdgcn_s_barrier()
; #define PG8_SCHED __builtin_amdgcn_sched_barrier(0)
; template <class Epi, class Sched, bool ALIGN_EPI = false, bool SP2 = false>
; __device__ __forceinline__ void gemm_phase(PG8_LAS unsigned char* lds, const Gemm g, const Sched& S, const Epi& E) {
;     ...
;             PG8_LDB(B0, 1, 0); PG8_LDB(B1, 1, 1); PG8_SCHED; PG8_LDA(At, 1, 0); PG8_STAGE(PG8_SA(0, 1), a2 + hstep, voffA);
;             PG8_WAIT_V(8); PG8_WAIT_L(0); PG8_BAR; PG8_MMA(0, 0, At, B0); PG8_MMA(0, 1, At, B1); PG8_BAR; PG8_SCHED;
;             PG8_LDA(At, 1, 1); PG8_STAGE(PG8_SB(1, 0), b3, voffB); PG8_STAGE(PG8_SB(1, 1), b3 + hstep, voffB); PG8_STAGE(PG8_SA(1, 0), a3, voffA);
;             PG8_WAIT_V(8); PG8_WAIT_L(0); PG8_BAR; PG8_MMA(1, 0, At, B0); PG8_MMA(1, 1, At, B1); PG8_BAR; PG8_SCHED;
	ds_read_b128 v[142:145], v146 offset:32768
	ds_read_b128 v[152:155], v146 offset:33792
	ds_read_b128 v[156:159], v146 offset:34816
	ds_read_b128 v[160:163], v146 offset:35840
	ds_read_b128 v[164:167], v146 offset:49152
	ds_read_b128 v[168:171], v146 offset:50176
	ds_read_b128 v[172:175], v146 offset:51200
	ds_read_b128 v[176:179], v146 offset:52224
	ds_read_b128 v[180:183], v151 offset:32768
	ds_read_b128 v[184:187], v151 offset:33792
	ds_read_b128 v[188:191], v151 offset:34816
	ds_read_b128 v[192:195], v151 offset:35840
	ds_read_b128 v[196:199], v151 offset:36864
	ds_read_b128 v[200:203], v151 offset:37888
	ds_read_b128 v[204:207], v151 offset:38912
	ds_read_b128 v[208:211], v151 offset:39936
	s_setprio 0
	s_add_i32 s65, 0, 0x18000
	s_add_i32 s66, 0, 0x1c000
	s_mov_b32 m0, s34
	s_nop 0
	global_load_lds_dwordx4 v136, s[26:27]
	s_mov_b32 m0, s35
	s_nop 0
	global_load_lds_dwordx4 v134, s[26:27]
	s_add_u32 s26, s26, 0x100000
	s_addc_u32 s27, s27, 0
	s_mov_b32 m0, s54
	s_nop 0
	global_load_lds_dwordx4 v136, s[26:27]
	s_mov_b32 m0, s55
	s_nop 0
	global_load_lds_dwordx4 v134, s[26:27]
	s_nop 0
	s_setprio 1
	s_waitcnt vmcnt(8)
	s_waitcnt lgkmcnt(0)
	s_barrier
	v_mfma_f32_16x16x32_bf16 v[128:131], v[142:145], v[180:183], v[128:131]
	v_mfma_f32_16x16x32_bf16 v[128:131], v[152:155], v[184:187], v[128:131]
	v_mfma_f32_16x16x32_bf16 v[124:127], v[156:159], v[180:183], v[124:127]
	v_mfma_f32_16x16x32_bf16 v[124:127], v[160:163], v[184:187], v[124:127]
	v_mfma_f32_16x16x32_bf16 v[108:111], v[156:159], v[188:191], v[108:111]
	v_mfma_f32_16x16x32_bf16 v[108:111], v[160:163], v[192:195], v[108:111]
	v_mfma_f32_16x16x32_bf16 v[112:115], v[142:145], v[188:191], v[112:115]
	v_mfma_f32_16x16x32_bf16 v[112:115], v[152:155], v[192:195], v[112:115]
	v_mfma_f32_16x16x32_bf16 v[96:99], v[142:145], v[196:199], v[96:99]
	v_mfma_f32_16x16x32_bf16 v[96:99], v[152:155], v[200:203], v[96:99]
	v_mfma_f32_16x16x32_bf16 v[92:95], v[156:159], v[196:199], v[92:95]
	v_mfma_f32_16x16x32_bf16 v[92:95], v[160:163], v[200:203], v[92:95]
	v_mfma_f32_16x16x32_bf16 v[76:79], v[156:159], v[204:207], v[76:79]
	v_mfma_f32_16x16x32_bf16 v[76:79], v[160:163], v[208:211], v[76:79]
	v_mfma_f32_16x16x32_bf16 v[80:83], v[142:145], v[204:207], v[80:83]
	v_mfma_f32_16x16x32_bf16 v[80:83], v[152:155], v[208:211], v[80:83]
	s_setprio 0
	s_setprio 1
	v_mfma_f32_16x16x32_bf16 v[120:123], v[164:167], v[180:183], v[120:123]
	v_mfma_f32_16x16x32_bf16 v[120:123], v[168:171], v[184:187], v[120:123]
	v_mfma_f32_16x16x32_bf16 v[116:119], v[172:175], v[180:183], v[116:119]
	v_mfma_f32_16x16x32_bf16 v[116:119], v[176:179], v[184:187], v[116:119]
	v_mfma_f32_16x16x32_bf16 v[100:103], v[172:175], v[188:191], v[100:103]
	v_mfma_f32_16x16x32_bf16 v[100:103], v[176:179], v[192:195], v[100:103]
	v_mfma_f32_16x16x32_bf16 v[104:107], v[164:167], v[188:191], v[104:107]
	v_mfma_f32_16x16x32_bf16 v[104:107], v[168:171], v[192:195], v[104:107]
	v_mfma_f32_16x16x32_bf16 v[88:91], v[164:167], v[196:199], v[88:91]
	v_mfma_f32_16x16x32_bf16 v[88:91], v[168:171], v[200:203], v[88:91]
	v_mfma_f32_16x16x32_bf16 v[84:87], v[172:175], v[196:199], v[84:87]
	v_mfma_f32_16x16x32_bf16 v[84:87], v[176:179], v[200:203], v[84:87]
	v_mfma_f32_16x16x32_bf16 v[68:71], v[172:175], v[204:207], v[68:71]
	v_mfma_f32_16x16x32_bf16 v[68:71], v[176:179], v[208:211], v[68:71]
	v_mfma_f32_16x16x32_bf16 v[72:75], v[164:167], v[204:207], v[72:75]
	v_mfma_f32_16x16x32_bf16 v[72:75], v[168:171], v[208:211], v[72:75]
	s_barrier
	ds_read_b128 v[180:183], v151 offset:49152
	ds_read_b128 v[184:187], v151 offset:50176
	ds_read_b128 v[188:191], v151 offset:51200
	ds_read_b128 v[192:195], v151 offset:52224
	ds_read_b128 v[196:199], v151 offset:53248
	ds_read_b128 v[200:203], v151 offset:54272
	ds_read_b128 v[204:207], v151 offset:55296
	ds_read_b128 v[208:211], v151 offset:56320
	s_setprio 0
	s_add_i32 s26, s65, s9
	s_mov_b32 m0, s26
	s_add_u32 s0, s0, 0x80
	s_addc_u32 s1, s1, 0
	global_load_lds_dwordx4 v2, s[0:1]
	s_add_i32 m0, s26, 0x2000
	s_add_i32 s26, s66, s9
	global_load_lds_dwordx4 v132, s[0:1]
	s_add_u32 s0, s0, 0x100000
	s_addc_u32 s1, s1, 0
	s_mov_b32 m0, s26
	s_nop 0
	global_load_lds_dwordx4 v2, s[0:1]
	s_add_i32 m0, s26, 0x2000
	s_nop 0
	global_load_lds_dwordx4 v132, s[0:1]
	s_setprio 1
	s_waitcnt vmcnt(6)
	s_waitcnt lgkmcnt(0)
	s_barrier
	v_mfma_f32_16x16x32_bf16 v[64:67], v[142:145], v[180:183], v[64:67]
	v_mfma_f32_16x16x32_bf16 v[64:67], v[152:155], v[184:187], v[64:67]
	v_mfma_f32_16x16x32_bf16 v[60:63], v[156:159], v[180:183], v[60:63]
	v_mfma_f32_16x16x32_bf16 v[60:63], v[160:163], v[184:187], v[60:63]
	v_mfma_f32_16x16x32_bf16 v[44:47], v[156:159], v[188:191], v[44:47]
	v_mfma_f32_16x16x32_bf16 v[44:47], v[160:163], v[192:195], v[44:47]
	v_mfma_f32_16x16x32_bf16 v[48:51], v[142:145], v[188:191], v[48:51]
	v_mfma_f32_16x16x32_bf16 v[48:51], v[152:155], v[192:195], v[48:51]
	v_mfma_f32_16x16x32_bf16 v[32:35], v[142:145], v[196:199], v[32:35]
	v_mfma_f32_16x16x32_bf16 v[32:35], v[152:155], v[200:203], v[32:35]
	v_mfma_f32_16x16x32_bf16 v[28:31], v[156:159], v[196:199], v[28:31]
	v_mfma_f32_16x16x32_bf16 v[28:31], v[160:163], v[200:203], v[28:31]
	v_mfma_f32_16x16x32_bf16 v[12:15], v[156:159], v[204:207], v[12:15]
	v_mfma_f32_16x16x32_bf16 v[12:15], v[160:163], v[208:211], v[12:15]
	v_mfma_f32_16x16x32_bf16 v[16:19], v[142:145], v[204:207], v[16:19]
	v_mfma_f32_16x16x32_bf16 v[16:19], v[152:155], v[208:211], v[16:19]
	s_setprio 0
	s_setprio 1
	s_add_i32 s64, s64, 2
	s_add_u32 s24, s24, 0x100
	s_addc_u32 s25, s25, 0
	s_add_u32 s62, s62, 0x100
	s_addc_u32 s63, s63, 0
	s_nop 0
	v_mfma_f32_16x16x32_bf16 v[56:59], v[164:167], v[180:183], v[56:59]
	v_mfma_f32_16x16x32_bf16 v[56:59], v[168:171], v[184:187], v[56:59]
	v_mfma_f32_16x16x32_bf16 v[52:55], v[172:175], v[180:183], v[52:55]
	v_mfma_f32_16x16x32_bf16 v[52:55], v[176:179], v[184:187], v[52:55]
	v_mfma_f32_16x16x32_bf16 v[36:39], v[172:175], v[188:191], v[36:39]
	v_mfma_f32_16x16x32_bf16 v[36:39], v[176:179], v[192:195], v[36:39]
	v_mfma_f32_16x16x32_bf16 v[40:43], v[164:167], v[188:191], v[40:43]
	v_mfma_f32_16x16x32_bf16 v[40:43], v[168:171], v[192:195], v[40:43]
	v_mfma_f32_16x16x32_bf16 v[24:27], v[164:167], v[196:199], v[24:27]
	v_mfma_f32_16x16x32_bf16 v[24:27], v[168:171], v[200:203], v[24:27]
	v_mfma_f32_16x16x32_bf16 v[20:23], v[172:175], v[196:199], v[20:23]
	v_mfma_f32_16x16x32_bf16 v[20:23], v[176:179], v[200:203], v[20:23]
	v_mfma_f32_16x16x32_bf16 v[4:7], v[172:175], v[204:207], v[4:7]
	v_mfma_f32_16x16x32_bf16 v[4:7], v[176:179], v[208:211], v[4:7]
	v_mfma_f32_16x16x32_bf16 v[8:11], v[164:167], v[204:207], v[8:11]
	v_mfma_f32_16x16x32_bf16 v[8:11], v[168:171], v[208:211], v[8:11]
	s_barrier
	s_cmp_gt_u32 s64, 61
	s_cbranch_scc0 .LBB0_3159
	s_setprio 0
	s_and_b64 vcc, exec, s[46:47]
	s_cbranch_vccz .LBB0_3162
	s_barrier

; #define PG8_STAGE(bufoff, gbase, voff) do { _Pragma("unroll") for (int _i = 0; _i < 2; ++_i) \
;         __builtin_amdgcn_global_load_lds((const unsigned*)((const char*)(gbase) + (voff)[_i]), (PG8_LAS unsigned*)(lds + (bufoff) + ldsw + _i * 8192), 16, 0, 0); } while (0)
; #define PG8_LDA(dst, b, h) do { _Pragma("unroll") for (int m = 0; m < 4; ++m) _Pragma("unroll") for (int k = 0; k < 2; ++k) dst[m][k] = *(const PG8_LAS bf16x8*)(lds + PG8_SA(b, h) + aoff + m * 2048 + k * 1024); } while (0)
; #define PG8_LDB(dst, b, h) do { _Pragma("unroll") for (int n = 0; n < 2; ++n) _Pragma("unroll") for (int k = 0; k < 2; ++k) dst[n][k] = *(const PG8_LAS bf16x8*)(lds + PG8_SB(b, h) + boff + n * 2048 + k * 1024); } while (0)
; #define PG8_MMA(ai, bj, At, Bt) do { __builtin_amdgcn_s_setprio(1); _Pragma("unroll") for (int m = 0; m < 4; ++m) _Pragma("unroll") for (int n = 0; n < 2; ++n) _Pragma("unroll") for (int k = 0; k < 2; ++k) \
;         acc[ai][bj][m][n] = __builtin_amdgcn_mfma_f32_16x16x32_bf16(Bt[n][k], At[m][k], acc[ai][bj][m][n], 0, 0, 0); __builtin_amdgcn_s_setprio(0); } while (0)
; #define PG8_WAIT_V(n) asm volatile("s_waitcnt vmcnt(" #n ")" ::: "memory")
; #define PG8_WAIT_L(n) asm volatile("s_waitcnt lgkmcnt(" #n ")" ::: "memory")
; #define PG8_BAR __builtin_amdgcn_s_barrier()
; #define PG8_SCHED __builtin_amdgcn_sched_barrier(0)
; template <class Epi, class Sched, bool ALIGN_EPI = false, bool SP2 = false>
; __device__ __forceinline__ void gemm_phase(PG8_LAS unsigned char* lds, const Gemm g, const Sched& S, const Epi& E) {
;     ...
;             PG8_LDB(B0, 0, 0); PG8_LDB(B1, 0, 1); PG8_SCHED; PG8_LDA(At, 0, 0); PG8_STAGE(PG8_SA(1, 1), a1 + hstep, voffA);
;             PG8_WAIT_V(8); PG8_WAIT_L(0); PG8_BAR; PG8_MMA(0, 0, At, B0); PG8_MMA(0, 1, At, B1); PG8_BAR; PG8_SCHED;
;             PG8_LDA(At, 0, 1); PG8_STAGE(PG8_SB(0, 0), b2, voffB); PG8_STAGE(PG8_SB(0, 1), b2 + hstep, voffB); PG8_STAGE(PG8_SA(0, 0), a2, voffA);
;             PG8_WAIT_V(8); PG8_WAIT_L(0); PG8_BAR; PG8_MMA(1, 0, At, B0); PG8_MMA(1, 1, At, B1); PG8_BAR; PG8_SCHED;
.LBB0_3627:
	s_waitcnt lgkmcnt(0)
	ds_read_b128 v[132:135], v162
	ds_read_b128 v[136:139], v162 offset:1024
	ds_read_b128 v[140:143], v162 offset:2048
	ds_read_b128 v[154:157], v162 offset:3072
	ds_read_b128 v[158:161], v162 offset:16384
	ds_read_b128 v[170:173], v162 offset:17408
	ds_read_b128 v[174:177], v162 offset:18432
	ds_read_b128 v[178:181], v162 offset:19456
	ds_read_b128 v[182:185], v169
	ds_read_b128 v[186:189], v169 offset:1024
	ds_read_b128 v[190:193], v169 offset:2048
	ds_read_b128 v[194:197], v169 offset:3072
	ds_read_b128 v[198:201], v169 offset:4096
	ds_read_b128 v[202:205], v169 offset:5120
	ds_read_b128 v[206:209], v169 offset:6144
	ds_read_b128 v[210:213], v169 offset:7168
	s_setprio 0
	s_add_i32 s72, s26, 2
	s_add_u32 s0, s24, 0x100
	s_addc_u32 s1, s25, 0
	s_add_i32 s73, 0, 0x10000
	s_cmp_eq_u32 s44, s26
	s_cselect_b32 s35, s79, s1
	s_cselect_b32 s34, s78, s0
	s_cselect_b32 s27, s81, s47
	s_cselect_b32 s26, s80, s45
	s_add_i32 vcc_lo, 0, 0x14000
	s_add_u32 s100, s24, 0x80
	s_addc_u32 s101, s25, 0
	s_mov_b32 m0, s65
	s_nop 0
	global_load_lds_dwordx4 v144, s[100:101]
	s_mov_b32 m0, s4
	s_nop 0
	global_load_lds_dwordx4 v146, s[100:101]
	s_add_i32 m0, s92, 0xc000
	s_nop 0
	global_load_lds_dwordx4 v150, s[24:25]
	s_add_i32 m0, s92, 0xe000
	s_nop 0
	global_load_lds_dwordx4 v152, s[24:25]
	s_setprio 1
	s_waitcnt vmcnt(8)
	s_waitcnt lgkmcnt(0)
	s_barrier
	v_mfma_f32_16x16x32_bf16 v[128:131], v[132:135], v[182:185], v[128:131]
	v_mfma_f32_16x16x32_bf16 v[128:131], v[136:139], v[186:189], v[128:131]
	v_mfma_f32_16x16x32_bf16 v[124:127], v[140:143], v[182:185], v[124:127]
	v_mfma_f32_16x16x32_bf16 v[124:127], v[154:157], v[186:189], v[124:127]
	v_mfma_f32_16x16x32_bf16 v[116:119], v[140:143], v[190:193], v[116:119]
	v_mfma_f32_16x16x32_bf16 v[116:119], v[154:157], v[194:197], v[116:119]
	v_mfma_f32_16x16x32_bf16 v[120:123], v[132:135], v[190:193], v[120:123]
	v_mfma_f32_16x16x32_bf16 v[120:123], v[136:139], v[194:197], v[120:123]
	v_mfma_f32_16x16x32_bf16 v[112:115], v[132:135], v[198:201], v[112:115]
	v_mfma_f32_16x16x32_bf16 v[112:115], v[136:139], v[202:205], v[112:115]
	v_mfma_f32_16x16x32_bf16 v[108:111], v[140:143], v[198:201], v[108:111]
	v_mfma_f32_16x16x32_bf16 v[108:111], v[154:157], v[202:205], v[108:111]
	v_mfma_f32_16x16x32_bf16 v[100:103], v[140:143], v[206:209], v[100:103]
	v_mfma_f32_16x16x32_bf16 v[100:103], v[154:157], v[210:213], v[100:103]
	v_mfma_f32_16x16x32_bf16 v[104:107], v[132:135], v[206:209], v[104:107]
	v_mfma_f32_16x16x32_bf16 v[104:107], v[136:139], v[210:213], v[104:107]
	s_setprio 0
	s_setprio 1
	v_mfma_f32_16x16x32_bf16 v[96:99], v[158:161], v[182:185], v[96:99]
	v_mfma_f32_16x16x32_bf16 v[96:99], v[170:173], v[186:189], v[96:99]
	v_mfma_f32_16x16x32_bf16 v[92:95], v[174:177], v[182:185], v[92:95]
	v_mfma_f32_16x16x32_bf16 v[92:95], v[178:181], v[186:189], v[92:95]
	v_mfma_f32_16x16x32_bf16 v[84:87], v[174:177], v[190:193], v[84:87]
	v_mfma_f32_16x16x32_bf16 v[84:87], v[178:181], v[194:197], v[84:87]
	v_mfma_f32_16x16x32_bf16 v[88:91], v[158:161], v[190:193], v[88:91]
	v_mfma_f32_16x16x32_bf16 v[88:91], v[170:173], v[194:197], v[88:91]
	v_mfma_f32_16x16x32_bf16 v[80:83], v[158:161], v[198:201], v[80:83]
	v_mfma_f32_16x16x32_bf16 v[80:83], v[170:173], v[202:205], v[80:83]
	v_mfma_f32_16x16x32_bf16 v[76:79], v[174:177], v[198:201], v[76:79]
	v_mfma_f32_16x16x32_bf16 v[76:79], v[178:181], v[202:205], v[76:79]
	v_mfma_f32_16x16x32_bf16 v[68:71], v[174:177], v[206:209], v[68:71]
	v_mfma_f32_16x16x32_bf16 v[68:71], v[178:181], v[210:213], v[68:71]
	v_mfma_f32_16x16x32_bf16 v[72:75], v[158:161], v[206:209], v[72:75]
	v_mfma_f32_16x16x32_bf16 v[72:75], v[170:173], v[210:213], v[72:75]
	s_barrier
	ds_read_b128 v[182:185], v169 offset:16384
	ds_read_b128 v[186:189], v169 offset:17408
	ds_read_b128 v[190:193], v169 offset:18432
	ds_read_b128 v[194:197], v169 offset:19456
	ds_read_b128 v[198:201], v169 offset:20480
	ds_read_b128 v[202:205], v169 offset:21504
	ds_read_b128 v[206:209], v169 offset:22528
	ds_read_b128 v[210:213], v169 offset:23552
	s_setprio 0
	s_add_i32 s24, s73, s83
	s_mov_b32 m0, s24
	s_nop 0
	global_load_lds_dwordx4 v2, s[26:27]
	s_add_i32 m0, s24, 0x2000
	s_add_u32 s24, s26, 0x2b0000
	s_addc_u32 s25, s27, 0
	s_add_i32 s73, vcc_lo, s83
	global_load_lds_dwordx4 v148, s[26:27]
	s_mov_b32 m0, s73
	s_nop 0
	global_load_lds_dwordx4 v2, s[24:25]
	s_add_i32 m0, s73, 0x2000
	s_nop 0
	global_load_lds_dwordx4 v148, s[24:25]
	s_nop 0
	s_nop 0
	s_setprio 1
	s_waitcnt vmcnt(6)
	s_waitcnt lgkmcnt(0)
	s_barrier
; #define PG8_STAGE(bufoff, gbase, voff) do { _Pragma("unroll") for (int _i = 0; _i < 2; ++_i) \
;         __builtin_amdgcn_global_load_lds((const unsigned*)((const char*)(gbase) + (voff)[_i]), (PG8_LAS unsigned*)(lds + (bufoff) + ldsw + _i * 8192), 16, 0, 0); } while (0)
; #define PG8_LDA(dst, b, h) do { _Pragma("unroll") for (int m = 0; m < 4; ++m) _Pragma("unroll") for (int k = 0; k < 2; ++k) dst[m][k] = *(const PG8_LAS bf16x8*)(lds + PG8_SA(b, h) + aoff + m * 2048 + k * 1024); } while (0)
; #define PG8_LDB(dst, b, h) do { _Pragma("unroll") for (int n = 0; n < 2; ++n) _Pragma("unroll") for (int k = 0; k < 2; ++k) dst[n][k] = *(const PG8_LAS bf16x8*)(lds + PG8_SB(b, h) + boff + n * 2048 + k * 1024); } while (0)
; #define PG8_MMA(ai, bj, At, Bt) do { __builtin_amdgcn_s_setprio(1); _Pragma("unroll") for (int m = 0; m < 4; ++m) _Pragma("unroll") for (int n = 0; n < 2; ++n) _Pragma("unroll") for (int k = 0; k < 2; ++k) \
;         acc[ai][bj][m][n] = __builtin_amdgcn_mfma_f32_16x16x32_bf16(Bt[n][k], At[m][k], acc[ai][bj][m][n], 0, 0, 0); __builtin_amdgcn_s_setprio(0); } while (0)
; #define PG8_WAIT_V(n) asm volatile("s_waitcnt vmcnt(" #n ")" ::: "memory")
; #define PG8_WAIT_L(n) asm volatile("s_waitcnt lgkmcnt(" #n ")" ::: "memory")
; #define PG8_BAR __builtin_amdgcn_s_barrier()
; #define PG8_SCHED __builtin_amdgcn_sched_barrier(0)
; template <class Epi, class Sched, bool ALIGN_EPI = false, bool SP2 = false>
; __device__ __forceinline__ void gemm_phase(PG8_LAS unsigned char* lds, const Gemm g, const Sched& S, const Epi& E) {
;     ...
;             PG8_WAIT_V(8); PG8_WAIT_L(0); PG8_BAR; PG8_MMA(1, 0, At, B0); PG8_MMA(1, 1, At, B1); PG8_BAR; PG8_SCHED;
;             PG8_LDB(B0, 1, 0); PG8_LDB(B1, 1, 1); PG8_SCHED; PG8_LDA(At, 1, 0); PG8_STAGE(PG8_SA(0, 1), a2 + hstep, voffA);
	v_mfma_f32_16x16x32_bf16 v[64:67], v[132:135], v[182:185], v[64:67]
	v_mfma_f32_16x16x32_bf16 v[64:67], v[136:139], v[186:189], v[64:67]
	v_mfma_f32_16x16x32_bf16 v[60:63], v[140:143], v[182:185], v[60:63]
	v_mfma_f32_16x16x32_bf16 v[60:63], v[154:157], v[186:189], v[60:63]
	v_mfma_f32_16x16x32_bf16 v[52:55], v[140:143], v[190:193], v[52:55]
	v_mfma_f32_16x16x32_bf16 v[52:55], v[154:157], v[194:197], v[52:55]
	v_mfma_f32_16x16x32_bf16 v[56:59], v[132:135], v[190:193], v[56:59]
	v_mfma_f32_16x16x32_bf16 v[56:59], v[136:139], v[194:197], v[56:59]
	v_mfma_f32_16x16x32_bf16 v[48:51], v[132:135], v[198:201], v[48:51]
	v_mfma_f32_16x16x32_bf16 v[48:51], v[136:139], v[202:205], v[48:51]
	v_mfma_f32_16x16x32_bf16 v[44:47], v[140:143], v[198:201], v[44:47]
	v_mfma_f32_16x16x32_bf16 v[44:47], v[154:157], v[202:205], v[44:47]
	v_mfma_f32_16x16x32_bf16 v[36:39], v[140:143], v[206:209], v[36:39]
	v_mfma_f32_16x16x32_bf16 v[36:39], v[154:157], v[210:213], v[36:39]
	v_mfma_f32_16x16x32_bf16 v[40:43], v[132:135], v[206:209], v[40:43]
	v_mfma_f32_16x16x32_bf16 v[40:43], v[136:139], v[210:213], v[40:43]
	s_setprio 0
	s_setprio 1
	v_mfma_f32_16x16x32_bf16 v[32:35], v[158:161], v[182:185], v[32:35]
	v_mfma_f32_16x16x32_bf16 v[32:35], v[170:173], v[186:189], v[32:35]
	v_mfma_f32_16x16x32_bf16 v[28:31], v[174:177], v[182:185], v[28:31]
	v_mfma_f32_16x16x32_bf16 v[28:31], v[178:181], v[186:189], v[28:31]
	v_mfma_f32_16x16x32_bf16 v[20:23], v[174:177], v[190:193], v[20:23]
	v_mfma_f32_16x16x32_bf16 v[20:23], v[178:181], v[194:197], v[20:23]
	v_mfma_f32_16x16x32_bf16 v[24:27], v[158:161], v[190:193], v[24:27]
	v_mfma_f32_16x16x32_bf16 v[24:27], v[170:173], v[194:197], v[24:27]
	v_mfma_f32_16x16x32_bf16 v[16:19], v[158:161], v[198:201], v[16:19]
	v_mfma_f32_16x16x32_bf16 v[16:19], v[170:173], v[202:205], v[16:19]
	v_mfma_f32_16x16x32_bf16 v[12:15], v[174:177], v[198:201], v[12:15]
	v_mfma_f32_16x16x32_bf16 v[12:15], v[178:181], v[202:205], v[12:15]
	v_mfma_f32_16x16x32_bf16 v[4:7], v[174:177], v[206:209], v[4:7]
	v_mfma_f32_16x16x32_bf16 v[4:7], v[178:181], v[210:213], v[4:7]
	v_mfma_f32_16x16x32_bf16 v[8:11], v[158:161], v[206:209], v[8:11]
	v_mfma_f32_16x16x32_bf16 v[8:11], v[170:173], v[210:213], v[8:11]
	s_barrier
	ds_read_b128 v[132:135], v162 offset:32768
	ds_read_b128 v[136:139], v162 offset:33792
	ds_read_b128 v[140:143], v162 offset:34816
	ds_read_b128 v[154:157], v162 offset:35840
	ds_read_b128 v[158:161], v162 offset:49152
	ds_read_b128 v[170:173], v162 offset:50176
	ds_read_b128 v[174:177], v162 offset:51200
	ds_read_b128 v[178:181], v162 offset:52224
	ds_read_b128 v[182:185], v169 offset:32768
	ds_read_b128 v[186:189], v169 offset:33792
	ds_read_b128 v[190:193], v169 offset:34816
	ds_read_b128 v[194:197], v169 offset:35840
	ds_read_b128 v[198:201], v169 offset:36864
	ds_read_b128 v[202:205], v169 offset:37888
	ds_read_b128 v[206:209], v169 offset:38912
	ds_read_b128 v[210:213], v169 offset:39936
	s_setprio 0
	s_add_i32 s73, 0, 0x18000
	s_add_i32 vcc_lo, 0, 0x1c000
	s_mov_b32 m0, s92
	s_nop 0
	global_load_lds_dwordx4 v144, s[34:35]
	s_mov_b32 m0, s93
	s_nop 0
	global_load_lds_dwordx4 v146, s[34:35]
	s_add_u32 s24, s34, 0x2b0000
	s_addc_u32 s25, s35, 0
	s_mov_b32 m0, s94
	s_nop 0
	global_load_lds_dwordx4 v144, s[24:25]
	s_mov_b32 m0, s95
	s_nop 0
	global_load_lds_dwordx4 v146, s[24:25]
	s_nop 0
	s_setprio 1
	s_waitcnt vmcnt(8)
	s_waitcnt lgkmcnt(0)
	s_barrier
; #define PG8_STAGE(bufoff, gbase, voff) do { _Pragma("unroll") for (int _i = 0; _i < 2; ++_i) \
;         __builtin_amdgcn_global_load_lds((const unsigned*)((const char*)(gbase) + (voff)[_i]), (PG8_LAS unsigned*)(lds + (bufoff) + ldsw + _i * 8192), 16, 0, 0); } while (0)
; #define PG8_LDA(dst, b, h) do { _Pragma("unroll") for (int m = 0; m < 4; ++m) _Pragma("unroll") for (int k = 0; k < 2; ++k) dst[m][k] = *(const PG8_LAS bf16x8*)(lds + PG8_SA(b, h) + aoff + m * 2048 + k * 1024); } while (0)
; #define PG8_MMA(ai, bj, At, Bt) do { __builtin_amdgcn_s_setprio(1); _Pragma("unroll") for (int m = 0; m < 4; ++m) _Pragma("unroll") for (int n = 0; n < 2; ++n) _Pragma("unroll") for (int k = 0; k < 2; ++k) \
;         acc[ai][bj][m][n] = __builtin_amdgcn_mfma_f32_16x16x32_bf16(Bt[n][k], At[m][k], acc[ai][bj][m][n], 0, 0, 0); __builtin_amdgcn_s_setprio(0); } while (0)
; #define PG8_WAIT_V(n) asm volatile("s_waitcnt vmcnt(" #n ")" ::: "memory")
; #define PG8_WAIT_L(n) asm volatile("s_waitcnt lgkmcnt(" #n ")" ::: "memory")
; #define PG8_BAR __builtin_amdgcn_s_barrier()
; #define PG8_SCHED __builtin_amdgcn_sched_barrier(0)
; template <class Epi, class Sched, bool ALIGN_EPI = false, bool SP2 = false>
; __device__ __forceinline__ void gemm_phase(PG8_LAS unsigned char* lds, const Gemm g, const Sched& S, const Epi& E) {
;     ...
;             PG8_WAIT_V(8); PG8_WAIT_L(0); PG8_BAR; PG8_MMA(0, 0, At, B0); PG8_MMA(0, 1, At, B1); PG8_BAR; PG8_SCHED;
;             PG8_LDA(At, 1, 1); PG8_STAGE(PG8_SB(1, 0), b3, voffB); PG8_STAGE(PG8_SB(1, 1), b3 + hstep, voffB); PG8_STAGE(PG8_SA(1, 0), a3, voffA);
;             PG8_WAIT_V(8); PG8_WAIT_L(0); PG8_BAR; PG8_MMA(1, 0, At, B0); PG8_MMA(1, 1, At, B1); PG8_BAR; PG8_SCHED;
	v_mfma_f32_16x16x32_bf16 v[128:131], v[132:135], v[182:185], v[128:131]
	v_mfma_f32_16x16x32_bf16 v[128:131], v[136:139], v[186:189], v[128:131]
	v_mfma_f32_16x16x32_bf16 v[124:127], v[140:143], v[182:185], v[124:127]
	v_mfma_f32_16x16x32_bf16 v[124:127], v[154:157], v[186:189], v[124:127]
	v_mfma_f32_16x16x32_bf16 v[116:119], v[140:143], v[190:193], v[116:119]
	v_mfma_f32_16x16x32_bf16 v[116:119], v[154:157], v[194:197], v[116:119]
	v_mfma_f32_16x16x32_bf16 v[120:123], v[132:135], v[190:193], v[120:123]
	v_mfma_f32_16x16x32_bf16 v[120:123], v[136:139], v[194:197], v[120:123]
	v_mfma_f32_16x16x32_bf16 v[112:115], v[132:135], v[198:201], v[112:115]
	v_mfma_f32_16x16x32_bf16 v[112:115], v[136:139], v[202:205], v[112:115]
	v_mfma_f32_16x16x32_bf16 v[108:111], v[140:143], v[198:201], v[108:111]
	v_mfma_f32_16x16x32_bf16 v[108:111], v[154:157], v[202:205], v[108:111]
	v_mfma_f32_16x16x32_bf16 v[100:103], v[140:143], v[206:209], v[100:103]
	v_mfma_f32_16x16x32_bf16 v[100:103], v[154:157], v[210:213], v[100:103]
	v_mfma_f32_16x16x32_bf16 v[104:107], v[132:135], v[206:209], v[104:107]
	v_mfma_f32_16x16x32_bf16 v[104:107], v[136:139], v[210:213], v[104:107]
	s_setprio 0
	s_setprio 1
	v_mfma_f32_16x16x32_bf16 v[96:99], v[158:161], v[182:185], v[96:99]
	v_mfma_f32_16x16x32_bf16 v[96:99], v[170:173], v[186:189], v[96:99]
	v_mfma_f32_16x16x32_bf16 v[92:95], v[174:177], v[182:185], v[92:95]
	v_mfma_f32_16x16x32_bf16 v[92:95], v[178:181], v[186:189], v[92:95]
	v_mfma_f32_16x16x32_bf16 v[84:87], v[174:177], v[190:193], v[84:87]
	v_mfma_f32_16x16x32_bf16 v[84:87], v[178:181], v[194:197], v[84:87]
	v_mfma_f32_16x16x32_bf16 v[88:91], v[158:161], v[190:193], v[88:91]
	v_mfma_f32_16x16x32_bf16 v[88:91], v[170:173], v[194:197], v[88:91]
	v_mfma_f32_16x16x32_bf16 v[80:83], v[158:161], v[198:201], v[80:83]
	v_mfma_f32_16x16x32_bf16 v[80:83], v[170:173], v[202:205], v[80:83]
	v_mfma_f32_16x16x32_bf16 v[76:79], v[174:177], v[198:201], v[76:79]
	v_mfma_f32_16x16x32_bf16 v[76:79], v[178:181], v[202:205], v[76:79]
	v_mfma_f32_16x16x32_bf16 v[68:71], v[174:177], v[206:209], v[68:71]
	v_mfma_f32_16x16x32_bf16 v[68:71], v[178:181], v[210:213], v[68:71]
	v_mfma_f32_16x16x32_bf16 v[72:75], v[158:161], v[206:209], v[72:75]
	v_mfma_f32_16x16x32_bf16 v[72:75], v[170:173], v[210:213], v[72:75]
	s_barrier
	ds_read_b128 v[182:185], v169 offset:49152
	ds_read_b128 v[186:189], v169 offset:50176
	ds_read_b128 v[190:193], v169 offset:51200
	ds_read_b128 v[194:197], v169 offset:52224
	ds_read_b128 v[198:201], v169 offset:53248
	ds_read_b128 v[202:205], v169 offset:54272
	ds_read_b128 v[206:209], v169 offset:55296
	ds_read_b128 v[210:213], v169 offset:56320
	s_setprio 0
	s_add_i32 s24, s73, s83
	s_add_u32 s100, s26, 0x80
	s_addc_u32 s101, s27, 0
	s_mov_b32 m0, s24
	s_nop 0
	global_load_lds_dwordx4 v2, s[100:101]
	s_add_i32 m0, s24, 0x2000
	s_add_u32 s24, s26, 0x2b0080
	s_addc_u32 s25, s27, 0
	s_add_i32 s26, vcc_lo, s83
	global_load_lds_dwordx4 v148, s[100:101]
	s_mov_b32 m0, s26
	s_nop 0
	global_load_lds_dwordx4 v2, s[24:25]
	s_add_i32 m0, s26, 0x2000
	s_nop 0
	global_load_lds_dwordx4 v148, s[24:25]
	s_nop 0
	s_setprio 1
	s_waitcnt vmcnt(6)
	s_waitcnt lgkmcnt(0)
	s_barrier
	v_mfma_f32_16x16x32_bf16 v[64:67], v[132:135], v[182:185], v[64:67]
	v_mfma_f32_16x16x32_bf16 v[64:67], v[136:139], v[186:189], v[64:67]
	v_mfma_f32_16x16x32_bf16 v[60:63], v[140:143], v[182:185], v[60:63]
	v_mfma_f32_16x16x32_bf16 v[60:63], v[154:157], v[186:189], v[60:63]
	v_mfma_f32_16x16x32_bf16 v[52:55], v[140:143], v[190:193], v[52:55]
	v_mfma_f32_16x16x32_bf16 v[52:55], v[154:157], v[194:197], v[52:55]
	v_mfma_f32_16x16x32_bf16 v[56:59], v[132:135], v[190:193], v[56:59]
	v_mfma_f32_16x16x32_bf16 v[56:59], v[136:139], v[194:197], v[56:59]
	v_mfma_f32_16x16x32_bf16 v[48:51], v[132:135], v[198:201], v[48:51]
	v_mfma_f32_16x16x32_bf16 v[48:51], v[136:139], v[202:205], v[48:51]
	v_mfma_f32_16x16x32_bf16 v[44:47], v[140:143], v[198:201], v[44:47]
	v_mfma_f32_16x16x32_bf16 v[44:47], v[154:157], v[202:205], v[44:47]
	v_mfma_f32_16x16x32_bf16 v[36:39], v[140:143], v[206:209], v[36:39]
	v_mfma_f32_16x16x32_bf16 v[36:39], v[154:157], v[210:213], v[36:39]
	v_mfma_f32_16x16x32_bf16 v[40:43], v[132:135], v[206:209], v[40:43]
	v_mfma_f32_16x16x32_bf16 v[40:43], v[136:139], v[210:213], v[40:43]
	s_setprio 0
	s_setprio 1
	s_add_u32 s45, s45, 0x100
	s_addc_u32 s47, s47, 0
	s_mov_b64 s[24:25], s[0:1]
	s_mov_b32 s26, s72
	s_nop 0
	v_mfma_f32_16x16x32_bf16 v[32:35], v[158:161], v[182:185], v[32:35]
	v_mfma_f32_16x16x32_bf16 v[32:35], v[170:173], v[186:189], v[32:35]
	v_mfma_f32_16x16x32_bf16 v[28:31], v[174:177], v[182:185], v[28:31]
	v_mfma_f32_16x16x32_bf16 v[28:31], v[178:181], v[186:189], v[28:31]
	v_mfma_f32_16x16x32_bf16 v[20:23], v[174:177], v[190:193], v[20:23]
	v_mfma_f32_16x16x32_bf16 v[20:23], v[178:181], v[194:197], v[20:23]
	v_mfma_f32_16x16x32_bf16 v[24:27], v[158:161], v[190:193], v[24:27]
	v_mfma_f32_16x16x32_bf16 v[24:27], v[170:173], v[194:197], v[24:27]
	v_mfma_f32_16x16x32_bf16 v[16:19], v[158:161], v[198:201], v[16:19]
	v_mfma_f32_16x16x32_bf16 v[16:19], v[170:173], v[202:205], v[16:19]
	v_mfma_f32_16x16x32_bf16 v[12:15], v[174:177], v[198:201], v[12:15]
	v_mfma_f32_16x16x32_bf16 v[12:15], v[178:181], v[202:205], v[12:15]
	v_mfma_f32_16x16x32_bf16 v[4:7], v[174:177], v[206:209], v[4:7]
	v_mfma_f32_16x16x32_bf16 v[4:7], v[178:181], v[210:213], v[4:7]
	v_mfma_f32_16x16x32_bf16 v[8:11], v[158:161], v[206:209], v[8:11]
	v_mfma_f32_16x16x32_bf16 v[8:11], v[170:173], v[210:213], v[8:11]
	s_barrier
	s_cmp_ge_i32 s72, s46
	s_cbranch_scc0 .LBB0_3627
	s_setprio 0
	s_and_b64 vcc, exec, s[50:51]
	s_cbranch_vccz .LBB0_3630
	s_barrier
